# speedup vs baseline: 1.0456x; 1.0068x over previous
.LBB0_184:
	s_bfe_u32 s0, s13, 0x100005
	s_mulk_i32 s0, 0x2493
	s_lshr_b32 s0, s0, 16
	s_and_b32 s0, s0, 0xffff
	s_mul_i32 s2, s0, 0xff20
	s_add_i32 s3, s2, s13
	s_sext_i32_i16 s2, s3
	s_mulk_i32 s2, 0x4925
	s_lshr_b32 s4, s2, 31
	s_ashr_i32 s2, s2, 17
	s_add_i32 s2, s2, s4
	s_mul_i32 s4, s2, 7
	s_lshl_b32 s2, s2, 10
	s_or_b32 s2, s2, s14
	v_or_b32_e32 v2, s2, v1
	v_ashrrev_i32_e32 v3, 31, v2
	v_lshlrev_b64 v[2:3], 11, v[2:3]
	s_sub_i32 s3, s3, s4
	s_mul_i32 s0, s0, 7
	v_lshl_add_u64 v[104:105], v[100:101], 0, v[2:3]
	s_sext_i32_i16 s3, s3
	s_add_i32 s0, s0, s3
	s_lshl_b32 s3, s0, 7
	v_or_b32_e32 v18, s3, v1
	v_ashrrev_i32_e32 v19, 31, v18
	v_lshlrev_b64 v[18:19], 11, v[18:19]
	v_lshl_add_u64 v[108:109], v[102:103], 0, v[18:19]
	s_mov_b32 s4, -2
	s_mov_b32 s5, s1
	v_mov_b32_e32 v26, 0
	v_mov_b32_e32 v27, v99
	v_mov_b32_e32 v28, v99
	v_mov_b32_e32 v29, v99
	v_mov_b32_e32 v46, 0
	v_mov_b32_e32 v47, v99
	v_mov_b32_e32 v48, v99
	v_mov_b32_e32 v49, v99
	v_mov_b32_e32 v62, 0
	v_mov_b32_e32 v63, v99
	v_mov_b32_e32 v64, v99
	v_mov_b32_e32 v65, v99
	v_mov_b32_e32 v78, 0
	v_mov_b32_e32 v79, v99
	v_mov_b32_e32 v80, v99
	v_mov_b32_e32 v81, v99
	v_mov_b32_e32 v82, 0
	v_mov_b32_e32 v83, v99
	v_mov_b32_e32 v84, v99
	v_mov_b32_e32 v85, v99
	v_mov_b32_e32 v86, 0
	v_mov_b32_e32 v87, v99
	v_mov_b32_e32 v88, v99
	v_mov_b32_e32 v89, v99
	v_mov_b32_e32 v90, 0
	v_mov_b32_e32 v91, v99
	v_mov_b32_e32 v92, v99
	v_mov_b32_e32 v93, v99
	v_mov_b32_e32 v94, 0
	v_mov_b32_e32 v95, v99
	v_mov_b32_e32 v96, v99
	v_mov_b32_e32 v97, v99
	v_mov_b32_e32 v38, 0
	v_mov_b32_e32 v39, v99
	v_mov_b32_e32 v40, v99
	v_mov_b32_e32 v41, v99
	v_mov_b32_e32 v30, 0
	v_mov_b32_e32 v31, v99
	v_mov_b32_e32 v32, v99
	v_mov_b32_e32 v33, v99
	v_mov_b32_e32 v22, 0
	v_mov_b32_e32 v23, v99
	v_mov_b32_e32 v24, v99
	v_mov_b32_e32 v25, v99
	v_mov_b32_e32 v18, 0
	v_mov_b32_e32 v19, v99
	v_mov_b32_e32 v20, v99
	v_mov_b32_e32 v21, v99
	v_mov_b32_e32 v14, 0
	v_mov_b32_e32 v15, v99
	v_mov_b32_e32 v16, v99
	v_mov_b32_e32 v17, v99
	v_mov_b32_e32 v10, 0
	v_mov_b32_e32 v11, v99
	v_mov_b32_e32 v12, v99
	v_mov_b32_e32 v13, v99
	v_mov_b32_e32 v6, 0
	v_mov_b32_e32 v7, v99
	v_mov_b32_e32 v8, v99
	v_mov_b32_e32 v9, v99
	v_mov_b32_e32 v2, 0
	v_mov_b32_e32 v3, v99
	v_mov_b32_e32 v4, v99
	v_mov_b32_e32 v5, v99
	v_and_b32_e32 v181, 7, v106
	v_bfe_u32 v180, v106, 3, 3
	v_xor_b32_e32 v180, v181, v180
	v_sub_u32_e32 v180, v180, v181
	v_lshlrev_b32_e32 v180, 4, v180
	v_ashrrev_i32_e32 v181, 31, v180
	v_lshrrev_b32_e32 v186, 6, v106
	v_mov_b32_e32 v187, 0x110
	v_lshl_add_u32 v186, v186, 10, v187
	v_lshl_add_u64 v[188:189], v[104:105], 0, v[180:181]
	v_lshl_add_u64 v[196:197], v[108:109], 0, v[180:181]
	v_readfirstlane_b32 s6, v186
	v_add_co_u32_e32 v190, vcc, s15, v188
	v_addc_co_u32_e32 v191, vcc, 0, v189, vcc
	v_add_co_u32_e32 v192, vcc, s16, v188
	v_addc_co_u32_e32 v193, vcc, 0, v189, vcc
	v_add_co_u32_e32 v194, vcc, s17, v188
	v_addc_co_u32_e32 v195, vcc, 0, v189, vcc
	v_add_co_u32_e32 v198, vcc, s15, v196
	v_addc_co_u32_e32 v199, vcc, 0, v197, vcc
	v_add_co_u32_e32 v200, vcc, s16, v196
	v_addc_co_u32_e32 v201, vcc, 0, v197, vcc
	v_add_co_u32_e32 v202, vcc, s17, v196
	v_addc_co_u32_e32 v203, vcc, 0, v197, vcc
	s_add_u32 m0, s6, 0x0
	s_nop 0
	global_load_lds_dwordx4 v[188:189], off
	s_add_u32 m0, s6, 0x1000
	s_nop 0
	global_load_lds_dwordx4 v[190:191], off
	s_add_u32 m0, s6, 0x2000
	s_nop 0
	global_load_lds_dwordx4 v[192:193], off
	s_add_u32 m0, s6, 0x3000
	s_nop 0
	global_load_lds_dwordx4 v[194:195], off
	s_add_u32 m0, s6, 0x4000
	s_nop 0
	global_load_lds_dwordx4 v[196:197], off
	s_add_u32 m0, s6, 0x5000
	s_nop 0
	global_load_lds_dwordx4 v[198:199], off
	s_add_u32 m0, s6, 0x6000
	s_nop 0
	global_load_lds_dwordx4 v[200:201], off
	s_add_u32 m0, s6, 0x7000
	s_nop 0
	global_load_lds_dwordx4 v[202:203], off
	s_mov_b32 s0, 0x80
	s_add_u32 m0, s6, 0x8000
	v_lshl_add_u64 v[204:205], v[188:189], 0, s[0:1]
	global_load_lds_dwordx4 v[204:205], off
	s_add_u32 m0, s6, 0x9000
	v_lshl_add_u64 v[206:207], v[190:191], 0, s[0:1]
	global_load_lds_dwordx4 v[206:207], off
	s_add_u32 m0, s6, 0xa000
	v_lshl_add_u64 v[204:205], v[192:193], 0, s[0:1]
	global_load_lds_dwordx4 v[204:205], off
	s_add_u32 m0, s6, 0xb000
	v_lshl_add_u64 v[206:207], v[194:195], 0, s[0:1]
	global_load_lds_dwordx4 v[206:207], off
	s_add_u32 m0, s6, 0xc000
	v_lshl_add_u64 v[204:205], v[196:197], 0, s[0:1]
	global_load_lds_dwordx4 v[204:205], off
	s_add_u32 m0, s6, 0xd000
	v_lshl_add_u64 v[206:207], v[198:199], 0, s[0:1]
	global_load_lds_dwordx4 v[206:207], off
	s_add_u32 m0, s6, 0xe000
	v_lshl_add_u64 v[204:205], v[200:201], 0, s[0:1]
	global_load_lds_dwordx4 v[204:205], off
	s_add_u32 m0, s6, 0xf000
	v_lshl_add_u64 v[206:207], v[202:203], 0, s[0:1]
	global_load_lds_dwordx4 v[206:207], off
	s_mov_b32 s5, 0
	s_mov_b32 s4, -2
	s_waitcnt vmcnt(8)
	s_barrier
.Lglds2_2829:
	ds_read_b128 v[152:155], v112 offset:16384
	ds_read_b128 v[156:159], v112 offset:18432
	ds_read_b128 v[160:163], v110
	ds_read_b128 v[164:167], v110 offset:2048
	ds_read_b128 v[168:171], v112 offset:20480
	ds_read_b128 v[172:175], v113 offset:16384
	ds_read_b128 v[208:211], v110 offset:4096
	ds_read_b128 v[212:215], v111
	ds_read_b128 v[216:219], v116 offset:16384
	ds_read_b128 v[220:223], v116 offset:18432
	ds_read_b128 v[224:227], v114
	ds_read_b128 v[228:231], v114 offset:2048
	ds_read_b128 v[232:235], v116 offset:20480
	ds_read_b128 v[236:239], v117 offset:16384
	ds_read_b128 v[240:243], v114 offset:4096
	ds_read_b128 v[244:247], v115
	s_setprio 1
	s_waitcnt lgkmcnt(8)
	v_mfma_f32_16x16x32_bf16 v[94:97], v[152:155], v[160:163], v[94:97]
	v_mfma_f32_16x16x32_bf16 v[90:93], v[156:159], v[160:163], v[90:93]
	v_mfma_f32_16x16x32_bf16 v[86:89], v[168:171], v[160:163], v[86:89]
	v_mfma_f32_16x16x32_bf16 v[82:85], v[172:175], v[160:163], v[82:85]
	v_mfma_f32_16x16x32_bf16 v[78:81], v[152:155], v[164:167], v[78:81]
	v_mfma_f32_16x16x32_bf16 v[62:65], v[156:159], v[164:167], v[62:65]
	v_mfma_f32_16x16x32_bf16 v[46:49], v[168:171], v[164:167], v[46:49]
	v_mfma_f32_16x16x32_bf16 v[26:29], v[172:175], v[164:167], v[26:29]
	v_mfma_f32_16x16x32_bf16 v[38:41], v[152:155], v[208:211], v[38:41]
	v_mfma_f32_16x16x32_bf16 v[30:33], v[156:159], v[208:211], v[30:33]
	v_mfma_f32_16x16x32_bf16 v[22:25], v[168:171], v[208:211], v[22:25]
	v_mfma_f32_16x16x32_bf16 v[18:21], v[172:175], v[208:211], v[18:21]
	v_mfma_f32_16x16x32_bf16 v[14:17], v[152:155], v[212:215], v[14:17]
	v_mfma_f32_16x16x32_bf16 v[10:13], v[156:159], v[212:215], v[10:13]
	v_mfma_f32_16x16x32_bf16 v[6:9], v[168:171], v[212:215], v[6:9]
	v_mfma_f32_16x16x32_bf16 v[2:5], v[172:175], v[212:215], v[2:5]
	s_setprio 0
	s_waitcnt lgkmcnt(0)
	s_barrier
	s_add_i32 s0, s5, 0x80
	s_min_u32 s0, s0, 0x3c0
	s_lshl_b32 s0, s0, 1
	s_setprio 1
	v_mfma_f32_16x16x32_bf16 v[94:97], v[216:219], v[224:227], v[94:97]
	s_add_u32 m0, s6, 0x0
	v_lshl_add_u64 v[204:205], v[188:189], 0, s[0:1]
	global_load_lds_dwordx4 v[204:205], off
	v_mfma_f32_16x16x32_bf16 v[90:93], v[220:223], v[224:227], v[90:93]
	v_mfma_f32_16x16x32_bf16 v[86:89], v[232:235], v[224:227], v[86:89]
	s_add_u32 m0, s6, 0x1000
	v_lshl_add_u64 v[206:207], v[190:191], 0, s[0:1]
	global_load_lds_dwordx4 v[206:207], off
	v_mfma_f32_16x16x32_bf16 v[82:85], v[236:239], v[224:227], v[82:85]
	v_mfma_f32_16x16x32_bf16 v[78:81], v[216:219], v[228:231], v[78:81]
	s_add_u32 m0, s6, 0x2000
	v_lshl_add_u64 v[204:205], v[192:193], 0, s[0:1]
	global_load_lds_dwordx4 v[204:205], off
	v_mfma_f32_16x16x32_bf16 v[62:65], v[220:223], v[228:231], v[62:65]
	v_mfma_f32_16x16x32_bf16 v[46:49], v[232:235], v[228:231], v[46:49]
	s_add_u32 m0, s6, 0x3000
	v_lshl_add_u64 v[206:207], v[194:195], 0, s[0:1]
	global_load_lds_dwordx4 v[206:207], off
	v_mfma_f32_16x16x32_bf16 v[26:29], v[236:239], v[228:231], v[26:29]
	v_mfma_f32_16x16x32_bf16 v[38:41], v[216:219], v[240:243], v[38:41]
	s_add_u32 m0, s6, 0x4000
	v_lshl_add_u64 v[204:205], v[196:197], 0, s[0:1]
	global_load_lds_dwordx4 v[204:205], off
	v_mfma_f32_16x16x32_bf16 v[30:33], v[220:223], v[240:243], v[30:33]
	v_mfma_f32_16x16x32_bf16 v[22:25], v[232:235], v[240:243], v[22:25]
	s_add_u32 m0, s6, 0x5000
	v_lshl_add_u64 v[206:207], v[198:199], 0, s[0:1]
	global_load_lds_dwordx4 v[206:207], off
	v_mfma_f32_16x16x32_bf16 v[18:21], v[236:239], v[240:243], v[18:21]
	v_mfma_f32_16x16x32_bf16 v[14:17], v[216:219], v[244:247], v[14:17]
	s_add_u32 m0, s6, 0x6000
	v_lshl_add_u64 v[204:205], v[200:201], 0, s[0:1]
	global_load_lds_dwordx4 v[204:205], off
	v_mfma_f32_16x16x32_bf16 v[10:13], v[220:223], v[244:247], v[10:13]
	v_mfma_f32_16x16x32_bf16 v[6:9], v[232:235], v[244:247], v[6:9]
	s_add_u32 m0, s6, 0x7000
	v_lshl_add_u64 v[206:207], v[202:203], 0, s[0:1]
	global_load_lds_dwordx4 v[206:207], off
	v_mfma_f32_16x16x32_bf16 v[2:5], v[236:239], v[244:247], v[2:5]
	s_setprio 0
	s_waitcnt vmcnt(8)
	s_barrier
	ds_read_b128 v[152:155], v112 offset:49152
	ds_read_b128 v[156:159], v112 offset:51200
	ds_read_b128 v[160:163], v110 offset:32768
	ds_read_b128 v[164:167], v110 offset:34816
	ds_read_b128 v[168:171], v112 offset:53248
	ds_read_b128 v[172:175], v113 offset:49152
	ds_read_b128 v[208:211], v110 offset:36864
	ds_read_b128 v[212:215], v111 offset:32768
	ds_read_b128 v[216:219], v116 offset:49152
	ds_read_b128 v[220:223], v116 offset:51200
	ds_read_b128 v[224:227], v114 offset:32768
	ds_read_b128 v[228:231], v114 offset:34816
	ds_read_b128 v[232:235], v116 offset:53248
	ds_read_b128 v[236:239], v117 offset:49152
	ds_read_b128 v[240:243], v114 offset:36864
	ds_read_b128 v[244:247], v115 offset:32768
	s_setprio 1
	s_waitcnt lgkmcnt(8)
	v_mfma_f32_16x16x32_bf16 v[94:97], v[152:155], v[160:163], v[94:97]
	v_mfma_f32_16x16x32_bf16 v[90:93], v[156:159], v[160:163], v[90:93]
	v_mfma_f32_16x16x32_bf16 v[86:89], v[168:171], v[160:163], v[86:89]
	v_mfma_f32_16x16x32_bf16 v[82:85], v[172:175], v[160:163], v[82:85]
	v_mfma_f32_16x16x32_bf16 v[78:81], v[152:155], v[164:167], v[78:81]
	v_mfma_f32_16x16x32_bf16 v[62:65], v[156:159], v[164:167], v[62:65]
	v_mfma_f32_16x16x32_bf16 v[46:49], v[168:171], v[164:167], v[46:49]
	v_mfma_f32_16x16x32_bf16 v[26:29], v[172:175], v[164:167], v[26:29]
	v_mfma_f32_16x16x32_bf16 v[38:41], v[152:155], v[208:211], v[38:41]
	v_mfma_f32_16x16x32_bf16 v[30:33], v[156:159], v[208:211], v[30:33]
	v_mfma_f32_16x16x32_bf16 v[22:25], v[168:171], v[208:211], v[22:25]
	v_mfma_f32_16x16x32_bf16 v[18:21], v[172:175], v[208:211], v[18:21]
	v_mfma_f32_16x16x32_bf16 v[14:17], v[152:155], v[212:215], v[14:17]
	v_mfma_f32_16x16x32_bf16 v[10:13], v[156:159], v[212:215], v[10:13]
	v_mfma_f32_16x16x32_bf16 v[6:9], v[168:171], v[212:215], v[6:9]
	v_mfma_f32_16x16x32_bf16 v[2:5], v[172:175], v[212:215], v[2:5]
	s_setprio 0
	s_waitcnt lgkmcnt(0)
	s_barrier
	s_add_i32 s0, s5, 0xc0
	s_min_u32 s0, s0, 0x3c0
	s_lshl_b32 s0, s0, 1
	s_setprio 1
	v_mfma_f32_16x16x32_bf16 v[94:97], v[216:219], v[224:227], v[94:97]
	s_add_u32 m0, s6, 0x8000
	v_lshl_add_u64 v[204:205], v[188:189], 0, s[0:1]
	global_load_lds_dwordx4 v[204:205], off
	v_mfma_f32_16x16x32_bf16 v[90:93], v[220:223], v[224:227], v[90:93]
	v_mfma_f32_16x16x32_bf16 v[86:89], v[232:235], v[224:227], v[86:89]
	s_add_u32 m0, s6, 0x9000
	v_lshl_add_u64 v[206:207], v[190:191], 0, s[0:1]
	global_load_lds_dwordx4 v[206:207], off
	v_mfma_f32_16x16x32_bf16 v[82:85], v[236:239], v[224:227], v[82:85]
	v_mfma_f32_16x16x32_bf16 v[78:81], v[216:219], v[228:231], v[78:81]
	s_add_u32 m0, s6, 0xa000
	v_lshl_add_u64 v[204:205], v[192:193], 0, s[0:1]
	global_load_lds_dwordx4 v[204:205], off
	v_mfma_f32_16x16x32_bf16 v[62:65], v[220:223], v[228:231], v[62:65]
	v_mfma_f32_16x16x32_bf16 v[46:49], v[232:235], v[228:231], v[46:49]
	s_add_u32 m0, s6, 0xb000
	v_lshl_add_u64 v[206:207], v[194:195], 0, s[0:1]
	global_load_lds_dwordx4 v[206:207], off
	v_mfma_f32_16x16x32_bf16 v[26:29], v[236:239], v[228:231], v[26:29]
	v_mfma_f32_16x16x32_bf16 v[38:41], v[216:219], v[240:243], v[38:41]
	s_add_u32 m0, s6, 0xc000
	v_lshl_add_u64 v[204:205], v[196:197], 0, s[0:1]
	global_load_lds_dwordx4 v[204:205], off
	v_mfma_f32_16x16x32_bf16 v[30:33], v[220:223], v[240:243], v[30:33]
	v_mfma_f32_16x16x32_bf16 v[22:25], v[232:235], v[240:243], v[22:25]
	s_add_u32 m0, s6, 0xd000
	v_lshl_add_u64 v[206:207], v[198:199], 0, s[0:1]
	global_load_lds_dwordx4 v[206:207], off
	v_mfma_f32_16x16x32_bf16 v[18:21], v[236:239], v[240:243], v[18:21]
	v_mfma_f32_16x16x32_bf16 v[14:17], v[216:219], v[244:247], v[14:17]
	s_add_u32 m0, s6, 0xe000
	v_lshl_add_u64 v[204:205], v[200:201], 0, s[0:1]
	global_load_lds_dwordx4 v[204:205], off
	v_mfma_f32_16x16x32_bf16 v[10:13], v[220:223], v[244:247], v[10:13]
	v_mfma_f32_16x16x32_bf16 v[6:9], v[232:235], v[244:247], v[6:9]
	s_add_u32 m0, s6, 0xf000
	v_lshl_add_u64 v[206:207], v[202:203], 0, s[0:1]
	global_load_lds_dwordx4 v[206:207], off
	v_mfma_f32_16x16x32_bf16 v[2:5], v[236:239], v[244:247], v[2:5]
	s_setprio 0
	s_waitcnt vmcnt(8)
	s_barrier
	s_add_i32 s5, s5, 0x80
	s_add_i32 s4, s4, 2
	s_cmp_gt_u32 s4, 13
	s_cbranch_scc0 .Lglds2_2829
	s_waitcnt vmcnt(0)
	v_readlane_b32 s36, v254, 40
	s_waitcnt vmcnt(7)
	v_or_b32_e32 v35, s2, v118
	v_readlane_b32 s48, v254, 52
	v_readlane_b32 s49, v254, 53
	v_or_b32_e32 v34, s3, v119
	s_waitcnt vmcnt(6)
	v_add_u32_e32 v42, v35, v120
	v_mov_b64_e32 v[36:37], s[48:49]
	v_mad_i64_i32 v[36:37], s[2:3], v42, s18, v[36:37]
	v_cmp_gt_i32_e32 vcc, s19, v34
	v_ashrrev_i32_e32 v35, 31, v34
	v_readlane_b32 s37, v254, 41
	v_readlane_b32 s38, v254, 42
	v_readlane_b32 s39, v254, 43
	v_readlane_b32 s40, v254, 44
	v_readlane_b32 s41, v254, 45
	v_readlane_b32 s42, v254, 46
	v_readlane_b32 s43, v254, 47
	v_readlane_b32 s44, v254, 48
	v_readlane_b32 s45, v254, 49
	v_readlane_b32 s46, v254, 50
	v_readlane_b32 s47, v254, 51
	v_readlane_b32 s50, v254, 54
	v_readlane_b32 s51, v254, 55
	s_and_saveexec_b64 s[2:3], vcc
	s_cbranch_execnz .LBB0_205
	s_or_b64 exec, exec, s[2:3]
	v_cmp_gt_i32_e64 s[4:5], s20, v34
	s_and_saveexec_b64 s[2:3], s[4:5]
	s_cbranch_execnz .LBB0_206

.LBB0_220:
	s_ashr_i32 s12, s2, 6
	s_ashr_i32 s13, s12, 31
	s_lshl_b64 s[16:17], s[12:13], 20
	s_add_u32 s18, s36, s16
	s_addc_u32 s19, s37, s17
	s_lshl_b32 s0, s2, 5
	s_and_b32 s16, s0, 0x780
	s_lshl_b32 s0, s2, 7
	s_and_b32 s17, s0, 0x180
	v_or_b32_e32 v2, s16, v1
	v_lshlrev_b32_e32 v98, 11, v2
	v_or_b32_e32 v2, s17, v1
	v_lshl_add_u64 v[104:105], v[100:101], 0, v[98:99]
	v_lshlrev_b32_e32 v98, 11, v2
	v_lshl_add_u64 v[2:3], s[18:19], 0, v[98:99]
	v_lshl_add_u64 v[108:109], v[2:3], 0, v[102:103]
	s_mov_b32 s18, -2
	s_mov_b32 s19, s1
	v_mov_b32_e32 v34, 0
	v_mov_b32_e32 v35, v99
	v_mov_b32_e32 v36, v99
	v_mov_b32_e32 v37, v99
	v_mov_b32_e32 v38, 0
	v_mov_b32_e32 v39, v99
	v_mov_b32_e32 v40, v99
	v_mov_b32_e32 v41, v99
	v_mov_b32_e32 v54, 0
	v_mov_b32_e32 v55, v99
	v_mov_b32_e32 v56, v99
	v_mov_b32_e32 v57, v99
	v_mov_b32_e32 v78, 0
	v_mov_b32_e32 v79, v99
	v_mov_b32_e32 v80, v99
	v_mov_b32_e32 v81, v99
	v_mov_b32_e32 v82, 0
	v_mov_b32_e32 v83, v99
	v_mov_b32_e32 v84, v99
	v_mov_b32_e32 v85, v99
	v_mov_b32_e32 v86, 0
	v_mov_b32_e32 v87, v99
	v_mov_b32_e32 v88, v99
	v_mov_b32_e32 v89, v99
	v_mov_b32_e32 v90, 0
	v_mov_b32_e32 v91, v99
	v_mov_b32_e32 v92, v99
	v_mov_b32_e32 v93, v99
	v_mov_b32_e32 v94, 0
	v_mov_b32_e32 v95, v99
	v_mov_b32_e32 v96, v99
	v_mov_b32_e32 v97, v99
	v_mov_b32_e32 v74, 0
	v_mov_b32_e32 v75, v99
	v_mov_b32_e32 v76, v99
	v_mov_b32_e32 v77, v99
	v_mov_b32_e32 v70, 0
	v_mov_b32_e32 v71, v99
	v_mov_b32_e32 v72, v99
	v_mov_b32_e32 v73, v99
	v_mov_b32_e32 v66, 0
	v_mov_b32_e32 v67, v99
	v_mov_b32_e32 v68, v99
	v_mov_b32_e32 v69, v99
	v_mov_b32_e32 v62, 0
	v_mov_b32_e32 v63, v99
	v_mov_b32_e32 v64, v99
	v_mov_b32_e32 v65, v99
	v_mov_b32_e32 v58, 0
	v_mov_b32_e32 v59, v99
	v_mov_b32_e32 v60, v99
	v_mov_b32_e32 v61, v99
	v_mov_b32_e32 v50, 0
	v_mov_b32_e32 v51, v99
	v_mov_b32_e32 v52, v99
	v_mov_b32_e32 v53, v99
	v_mov_b32_e32 v46, 0
	v_mov_b32_e32 v47, v99
	v_mov_b32_e32 v48, v99
	v_mov_b32_e32 v49, v99
	v_mov_b32_e32 v42, 0
	v_mov_b32_e32 v43, v99
	v_mov_b32_e32 v44, v99
	v_mov_b32_e32 v45, v99
	v_and_b32_e32 v181, 7, v106
	v_bfe_u32 v180, v106, 3, 3
	v_xor_b32_e32 v180, v181, v180
	v_sub_u32_e32 v180, v180, v181
	v_lshlrev_b32_e32 v180, 4, v180
	v_ashrrev_i32_e32 v181, 31, v180
	v_lshrrev_b32_e32 v186, 6, v106
	v_mov_b32_e32 v187, 0x110
	v_lshl_add_u32 v186, v186, 10, v187
	v_lshl_add_u64 v[188:189], v[104:105], 0, v[180:181]
	v_lshl_add_u64 v[196:197], v[108:109], 0, v[180:181]
	v_readfirstlane_b32 s20, v186
	v_add_co_u32_e32 v190, vcc, s3, v188
	v_addc_co_u32_e32 v191, vcc, 0, v189, vcc
	v_add_co_u32_e32 v192, vcc, s14, v188
	v_addc_co_u32_e32 v193, vcc, 0, v189, vcc
	v_add_co_u32_e32 v194, vcc, s15, v188
	v_addc_co_u32_e32 v195, vcc, 0, v189, vcc
	v_add_co_u32_e32 v198, vcc, s3, v196
	v_addc_co_u32_e32 v199, vcc, 0, v197, vcc
	v_add_co_u32_e32 v200, vcc, s14, v196
	v_addc_co_u32_e32 v201, vcc, 0, v197, vcc
	v_add_co_u32_e32 v202, vcc, s15, v196
	v_addc_co_u32_e32 v203, vcc, 0, v197, vcc
	s_add_u32 m0, s20, 0x0
	s_nop 0
	global_load_lds_dwordx4 v[188:189], off
	s_add_u32 m0, s20, 0x1000
	s_nop 0
	global_load_lds_dwordx4 v[190:191], off
	s_add_u32 m0, s20, 0x2000
	s_nop 0
	global_load_lds_dwordx4 v[192:193], off
	s_add_u32 m0, s20, 0x3000
	s_nop 0
	global_load_lds_dwordx4 v[194:195], off
	s_add_u32 m0, s20, 0x4000
	s_nop 0
	global_load_lds_dwordx4 v[196:197], off
	s_add_u32 m0, s20, 0x5000
	s_nop 0
	global_load_lds_dwordx4 v[198:199], off
	s_add_u32 m0, s20, 0x6000
	s_nop 0
	global_load_lds_dwordx4 v[200:201], off
	s_add_u32 m0, s20, 0x7000
	s_nop 0
	global_load_lds_dwordx4 v[202:203], off
	s_mov_b32 s0, 0x80
	s_add_u32 m0, s20, 0x8000
	v_lshl_add_u64 v[204:205], v[188:189], 0, s[0:1]
	global_load_lds_dwordx4 v[204:205], off
	s_add_u32 m0, s20, 0x9000
	v_lshl_add_u64 v[206:207], v[190:191], 0, s[0:1]
	global_load_lds_dwordx4 v[206:207], off
	s_add_u32 m0, s20, 0xa000
	v_lshl_add_u64 v[204:205], v[192:193], 0, s[0:1]
	global_load_lds_dwordx4 v[204:205], off
	s_add_u32 m0, s20, 0xb000
	v_lshl_add_u64 v[206:207], v[194:195], 0, s[0:1]
	global_load_lds_dwordx4 v[206:207], off
	s_add_u32 m0, s20, 0xc000
	v_lshl_add_u64 v[204:205], v[196:197], 0, s[0:1]
	global_load_lds_dwordx4 v[204:205], off
	s_add_u32 m0, s20, 0xd000
	v_lshl_add_u64 v[206:207], v[198:199], 0, s[0:1]
	global_load_lds_dwordx4 v[206:207], off
	s_add_u32 m0, s20, 0xe000
	v_lshl_add_u64 v[204:205], v[200:201], 0, s[0:1]
	global_load_lds_dwordx4 v[204:205], off
	s_add_u32 m0, s20, 0xf000
	v_lshl_add_u64 v[206:207], v[202:203], 0, s[0:1]
	global_load_lds_dwordx4 v[206:207], off
	s_mov_b32 s19, 0
	s_mov_b32 s18, -2
	s_waitcnt vmcnt(8)
	s_barrier
.Lglds2_3547:
	ds_read_b128 v[152:155], v112 offset:16384
	ds_read_b128 v[156:159], v112 offset:18432
	ds_read_b128 v[160:163], v110
	ds_read_b128 v[164:167], v110 offset:2048
	ds_read_b128 v[168:171], v112 offset:20480
	ds_read_b128 v[172:175], v113 offset:16384
	ds_read_b128 v[208:211], v110 offset:4096
	ds_read_b128 v[212:215], v111
	ds_read_b128 v[216:219], v116 offset:16384
	ds_read_b128 v[220:223], v116 offset:18432
	ds_read_b128 v[224:227], v114
	ds_read_b128 v[228:231], v114 offset:2048
	ds_read_b128 v[232:235], v116 offset:20480
	ds_read_b128 v[236:239], v117 offset:16384
	ds_read_b128 v[240:243], v114 offset:4096
	ds_read_b128 v[244:247], v115
	s_setprio 1
	s_waitcnt lgkmcnt(8)
	v_mfma_f32_16x16x32_bf16 v[94:97], v[152:155], v[160:163], v[94:97]
	v_mfma_f32_16x16x32_bf16 v[90:93], v[156:159], v[160:163], v[90:93]
	v_mfma_f32_16x16x32_bf16 v[86:89], v[168:171], v[160:163], v[86:89]
	v_mfma_f32_16x16x32_bf16 v[82:85], v[172:175], v[160:163], v[82:85]
	v_mfma_f32_16x16x32_bf16 v[78:81], v[152:155], v[164:167], v[78:81]
	v_mfma_f32_16x16x32_bf16 v[54:57], v[156:159], v[164:167], v[54:57]
	v_mfma_f32_16x16x32_bf16 v[38:41], v[168:171], v[164:167], v[38:41]
	v_mfma_f32_16x16x32_bf16 v[34:37], v[172:175], v[164:167], v[34:37]
	v_mfma_f32_16x16x32_bf16 v[74:77], v[152:155], v[208:211], v[74:77]
	v_mfma_f32_16x16x32_bf16 v[70:73], v[156:159], v[208:211], v[70:73]
	v_mfma_f32_16x16x32_bf16 v[66:69], v[168:171], v[208:211], v[66:69]
	v_mfma_f32_16x16x32_bf16 v[62:65], v[172:175], v[208:211], v[62:65]
	v_mfma_f32_16x16x32_bf16 v[58:61], v[152:155], v[212:215], v[58:61]
	v_mfma_f32_16x16x32_bf16 v[50:53], v[156:159], v[212:215], v[50:53]
	v_mfma_f32_16x16x32_bf16 v[46:49], v[168:171], v[212:215], v[46:49]
	v_mfma_f32_16x16x32_bf16 v[42:45], v[172:175], v[212:215], v[42:45]
	s_setprio 0
	s_waitcnt lgkmcnt(0)
	s_barrier
	s_add_i32 s0, s19, 0x80
	s_min_u32 s0, s0, 0x3c0
	s_lshl_b32 s0, s0, 1
	s_setprio 1
	v_mfma_f32_16x16x32_bf16 v[94:97], v[216:219], v[224:227], v[94:97]
	s_add_u32 m0, s20, 0x0
	v_lshl_add_u64 v[204:205], v[188:189], 0, s[0:1]
	global_load_lds_dwordx4 v[204:205], off
	v_mfma_f32_16x16x32_bf16 v[90:93], v[220:223], v[224:227], v[90:93]
	v_mfma_f32_16x16x32_bf16 v[86:89], v[232:235], v[224:227], v[86:89]
	s_add_u32 m0, s20, 0x1000
	v_lshl_add_u64 v[206:207], v[190:191], 0, s[0:1]
	global_load_lds_dwordx4 v[206:207], off
	v_mfma_f32_16x16x32_bf16 v[82:85], v[236:239], v[224:227], v[82:85]
	v_mfma_f32_16x16x32_bf16 v[78:81], v[216:219], v[228:231], v[78:81]
	s_add_u32 m0, s20, 0x2000
	v_lshl_add_u64 v[204:205], v[192:193], 0, s[0:1]
	global_load_lds_dwordx4 v[204:205], off
	v_mfma_f32_16x16x32_bf16 v[54:57], v[220:223], v[228:231], v[54:57]
	v_mfma_f32_16x16x32_bf16 v[38:41], v[232:235], v[228:231], v[38:41]
	s_add_u32 m0, s20, 0x3000
	v_lshl_add_u64 v[206:207], v[194:195], 0, s[0:1]
	global_load_lds_dwordx4 v[206:207], off
	v_mfma_f32_16x16x32_bf16 v[34:37], v[236:239], v[228:231], v[34:37]
	v_mfma_f32_16x16x32_bf16 v[74:77], v[216:219], v[240:243], v[74:77]
	s_add_u32 m0, s20, 0x4000
	v_lshl_add_u64 v[204:205], v[196:197], 0, s[0:1]
	global_load_lds_dwordx4 v[204:205], off
	v_mfma_f32_16x16x32_bf16 v[70:73], v[220:223], v[240:243], v[70:73]
	v_mfma_f32_16x16x32_bf16 v[66:69], v[232:235], v[240:243], v[66:69]
	s_add_u32 m0, s20, 0x5000
	v_lshl_add_u64 v[206:207], v[198:199], 0, s[0:1]
	global_load_lds_dwordx4 v[206:207], off
	v_mfma_f32_16x16x32_bf16 v[62:65], v[236:239], v[240:243], v[62:65]
	v_mfma_f32_16x16x32_bf16 v[58:61], v[216:219], v[244:247], v[58:61]
	s_add_u32 m0, s20, 0x6000
	v_lshl_add_u64 v[204:205], v[200:201], 0, s[0:1]
	global_load_lds_dwordx4 v[204:205], off
	v_mfma_f32_16x16x32_bf16 v[50:53], v[220:223], v[244:247], v[50:53]
	v_mfma_f32_16x16x32_bf16 v[46:49], v[232:235], v[244:247], v[46:49]
	s_add_u32 m0, s20, 0x7000
	v_lshl_add_u64 v[206:207], v[202:203], 0, s[0:1]
	global_load_lds_dwordx4 v[206:207], off
	v_mfma_f32_16x16x32_bf16 v[42:45], v[236:239], v[244:247], v[42:45]
	s_setprio 0
	s_waitcnt vmcnt(8)
	s_barrier
	ds_read_b128 v[152:155], v112 offset:49152
	ds_read_b128 v[156:159], v112 offset:51200
	ds_read_b128 v[160:163], v110 offset:32768
	ds_read_b128 v[164:167], v110 offset:34816
	ds_read_b128 v[168:171], v112 offset:53248
	ds_read_b128 v[172:175], v113 offset:49152
	ds_read_b128 v[208:211], v110 offset:36864
	ds_read_b128 v[212:215], v111 offset:32768
	ds_read_b128 v[216:219], v116 offset:49152
	ds_read_b128 v[220:223], v116 offset:51200
	ds_read_b128 v[224:227], v114 offset:32768
	ds_read_b128 v[228:231], v114 offset:34816
	ds_read_b128 v[232:235], v116 offset:53248
	ds_read_b128 v[236:239], v117 offset:49152
	ds_read_b128 v[240:243], v114 offset:36864
	ds_read_b128 v[244:247], v115 offset:32768
	s_setprio 1
	s_waitcnt lgkmcnt(8)
	v_mfma_f32_16x16x32_bf16 v[94:97], v[152:155], v[160:163], v[94:97]
	v_mfma_f32_16x16x32_bf16 v[90:93], v[156:159], v[160:163], v[90:93]
	v_mfma_f32_16x16x32_bf16 v[86:89], v[168:171], v[160:163], v[86:89]
	v_mfma_f32_16x16x32_bf16 v[82:85], v[172:175], v[160:163], v[82:85]
	v_mfma_f32_16x16x32_bf16 v[78:81], v[152:155], v[164:167], v[78:81]
	v_mfma_f32_16x16x32_bf16 v[54:57], v[156:159], v[164:167], v[54:57]
	v_mfma_f32_16x16x32_bf16 v[38:41], v[168:171], v[164:167], v[38:41]
	v_mfma_f32_16x16x32_bf16 v[34:37], v[172:175], v[164:167], v[34:37]
	v_mfma_f32_16x16x32_bf16 v[74:77], v[152:155], v[208:211], v[74:77]
	v_mfma_f32_16x16x32_bf16 v[70:73], v[156:159], v[208:211], v[70:73]
	v_mfma_f32_16x16x32_bf16 v[66:69], v[168:171], v[208:211], v[66:69]
	v_mfma_f32_16x16x32_bf16 v[62:65], v[172:175], v[208:211], v[62:65]
	v_mfma_f32_16x16x32_bf16 v[58:61], v[152:155], v[212:215], v[58:61]
	v_mfma_f32_16x16x32_bf16 v[50:53], v[156:159], v[212:215], v[50:53]
	v_mfma_f32_16x16x32_bf16 v[46:49], v[168:171], v[212:215], v[46:49]
	v_mfma_f32_16x16x32_bf16 v[42:45], v[172:175], v[212:215], v[42:45]
	s_setprio 0
	s_waitcnt lgkmcnt(0)
	s_barrier
	s_add_i32 s0, s19, 0xc0
	s_min_u32 s0, s0, 0x3c0
	s_lshl_b32 s0, s0, 1
	s_setprio 1
	v_mfma_f32_16x16x32_bf16 v[94:97], v[216:219], v[224:227], v[94:97]
	s_add_u32 m0, s20, 0x8000
	v_lshl_add_u64 v[204:205], v[188:189], 0, s[0:1]
	global_load_lds_dwordx4 v[204:205], off
	v_mfma_f32_16x16x32_bf16 v[90:93], v[220:223], v[224:227], v[90:93]
	v_mfma_f32_16x16x32_bf16 v[86:89], v[232:235], v[224:227], v[86:89]
	s_add_u32 m0, s20, 0x9000
	v_lshl_add_u64 v[206:207], v[190:191], 0, s[0:1]
	global_load_lds_dwordx4 v[206:207], off
	v_mfma_f32_16x16x32_bf16 v[82:85], v[236:239], v[224:227], v[82:85]
	v_mfma_f32_16x16x32_bf16 v[78:81], v[216:219], v[228:231], v[78:81]
	s_add_u32 m0, s20, 0xa000
	v_lshl_add_u64 v[204:205], v[192:193], 0, s[0:1]
	global_load_lds_dwordx4 v[204:205], off
	v_mfma_f32_16x16x32_bf16 v[54:57], v[220:223], v[228:231], v[54:57]
	v_mfma_f32_16x16x32_bf16 v[38:41], v[232:235], v[228:231], v[38:41]
	s_add_u32 m0, s20, 0xb000
	v_lshl_add_u64 v[206:207], v[194:195], 0, s[0:1]
	global_load_lds_dwordx4 v[206:207], off
	v_mfma_f32_16x16x32_bf16 v[34:37], v[236:239], v[228:231], v[34:37]
	v_mfma_f32_16x16x32_bf16 v[74:77], v[216:219], v[240:243], v[74:77]
	s_add_u32 m0, s20, 0xc000
	v_lshl_add_u64 v[204:205], v[196:197], 0, s[0:1]
	global_load_lds_dwordx4 v[204:205], off
	v_mfma_f32_16x16x32_bf16 v[70:73], v[220:223], v[240:243], v[70:73]
	v_mfma_f32_16x16x32_bf16 v[66:69], v[232:235], v[240:243], v[66:69]
	s_add_u32 m0, s20, 0xd000
	v_lshl_add_u64 v[206:207], v[198:199], 0, s[0:1]
	global_load_lds_dwordx4 v[206:207], off
	v_mfma_f32_16x16x32_bf16 v[62:65], v[236:239], v[240:243], v[62:65]
	v_mfma_f32_16x16x32_bf16 v[58:61], v[216:219], v[244:247], v[58:61]
	s_add_u32 m0, s20, 0xe000
	v_lshl_add_u64 v[204:205], v[200:201], 0, s[0:1]
	global_load_lds_dwordx4 v[204:205], off
	v_mfma_f32_16x16x32_bf16 v[50:53], v[220:223], v[244:247], v[50:53]
	v_mfma_f32_16x16x32_bf16 v[46:49], v[232:235], v[244:247], v[46:49]
	s_add_u32 m0, s20, 0xf000
	v_lshl_add_u64 v[206:207], v[202:203], 0, s[0:1]
	global_load_lds_dwordx4 v[206:207], off
	v_mfma_f32_16x16x32_bf16 v[42:45], v[236:239], v[244:247], v[42:45]
	s_setprio 0
	s_waitcnt vmcnt(8)
	s_barrier
	s_add_i32 s19, s19, 0x80
	s_add_i32 s18, s18, 2
	s_cmp_lt_u32 s18, 14
	s_cbranch_scc1 .Lglds2_3547
	s_waitcnt vmcnt(0)
	v_readlane_b32 s36, v254, 40
	s_lshl_b64 s[12:13], s[12:13], 21
	v_readlane_b32 s50, v254, 54
	v_readlane_b32 s51, v254, 55
	s_add_u32 s12, s50, s12
	s_addc_u32 s13, s51, s13
	s_waitcnt vmcnt(7)
	v_or_b32_e32 v4, s17, v119
	v_add_lshl_u32 v98, v118, s16, 10
	v_lshl_add_u64 v[2:3], s[12:13], 0, v[98:99]
	v_lshlrev_b32_e32 v98, 1, v4
	v_lshl_add_u64 v[4:5], v[2:3], 0, v[98:99]
	s_waitcnt vmcnt(6)
	v_cvt_pk_bf16_f32 v6, v94, v95
	v_cvt_pk_bf16_f32 v7, v96, v97
	global_store_dwordx2 v[4:5], v[6:7], off
	v_cvt_pk_bf16_f32 v6, v90, v91
	v_cvt_pk_bf16_f32 v7, v92, v93
	global_store_dwordx2 v[4:5], v[6:7], off offset:32
	v_cvt_pk_bf16_f32 v6, v86, v87
	v_cvt_pk_bf16_f32 v7, v88, v89
	global_store_dwordx2 v[4:5], v[6:7], off offset:64
	v_cvt_pk_bf16_f32 v6, v82, v83
	v_cvt_pk_bf16_f32 v7, v84, v85
	global_store_dwordx2 v[4:5], v[6:7], off offset:96
	v_lshl_add_u64 v[4:5], v[2:3], 0, s[4:5]
	v_lshl_add_u64 v[6:7], v[4:5], 0, v[98:99]
	v_cvt_pk_bf16_f32 v8, v78, v79
	v_cvt_pk_bf16_f32 v9, v80, v81
	global_store_dwordx2 v[6:7], v[8:9], off
	v_or_b32_e32 v6, 32, v98
	v_mov_b32_e32 v7, v99
	v_lshl_add_u64 v[8:9], v[4:5], 0, v[6:7]
	s_waitcnt vmcnt(10)
	v_cvt_pk_bf16_f32 v10, v54, v55
	v_cvt_pk_bf16_f32 v11, v56, v57
	global_store_dwordx2 v[8:9], v[10:11], off
	v_or_b32_e32 v8, 64, v98
	v_mov_b32_e32 v9, v99
	v_lshl_add_u64 v[10:11], v[4:5], 0, v[8:9]
	v_cvt_pk_bf16_f32 v12, v38, v39
	v_cvt_pk_bf16_f32 v13, v40, v41
	global_store_dwordx2 v[10:11], v[12:13], off
	v_or_b32_e32 v10, 0x60, v98
	v_mov_b32_e32 v11, v99
	v_lshl_add_u64 v[4:5], v[4:5], 0, v[10:11]
	v_cvt_pk_bf16_f32 v12, v34, v35
	v_cvt_pk_bf16_f32 v13, v36, v37
	global_store_dwordx2 v[4:5], v[12:13], off
	v_lshl_add_u64 v[4:5], v[2:3], 0, s[6:7]
	v_lshl_add_u64 v[12:13], v[4:5], 0, v[98:99]
	s_waitcnt vmcnt(11)
	v_cvt_pk_bf16_f32 v14, v74, v75
	v_cvt_pk_bf16_f32 v15, v76, v77
	global_store_dwordx2 v[12:13], v[14:15], off
	v_lshl_add_u64 v[12:13], v[4:5], 0, v[6:7]
	v_cvt_pk_bf16_f32 v14, v70, v71
	v_cvt_pk_bf16_f32 v15, v72, v73
	global_store_dwordx2 v[12:13], v[14:15], off
	v_lshl_add_u64 v[12:13], v[4:5], 0, v[8:9]
	v_cvt_pk_bf16_f32 v14, v66, v67
	v_cvt_pk_bf16_f32 v15, v68, v69
	global_store_dwordx2 v[12:13], v[14:15], off
	v_lshl_add_u64 v[4:5], v[4:5], 0, v[10:11]
	v_cvt_pk_bf16_f32 v12, v62, v63
	v_cvt_pk_bf16_f32 v13, v64, v65
	v_lshl_add_u64 v[2:3], v[2:3], 0, s[8:9]
	global_store_dwordx2 v[4:5], v[12:13], off
	v_lshl_add_u64 v[4:5], v[2:3], 0, v[98:99]
	v_cvt_pk_bf16_f32 v12, v58, v59
	v_cvt_pk_bf16_f32 v13, v60, v61
	global_store_dwordx2 v[4:5], v[12:13], off
	v_lshl_add_u64 v[4:5], v[2:3], 0, v[6:7]
	v_cvt_pk_bf16_f32 v6, v50, v51
	v_cvt_pk_bf16_f32 v7, v52, v53
	v_readlane_b32 s12, v254, 0
	global_store_dwordx2 v[4:5], v[6:7], off
	v_lshl_add_u64 v[4:5], v[2:3], 0, v[8:9]
	v_cvt_pk_bf16_f32 v6, v46, v47
	v_cvt_pk_bf16_f32 v7, v48, v49
	s_add_i32 s2, s2, s12
	v_readlane_b32 s37, v254, 41
	global_store_dwordx2 v[4:5], v[6:7], off
	v_lshl_add_u64 v[2:3], v[2:3], 0, v[10:11]
	v_cvt_pk_bf16_f32 v4, v42, v43
	v_cvt_pk_bf16_f32 v5, v44, v45
	s_cmpk_lt_i32 s2, 0x80
	v_readlane_b32 s38, v254, 42
	v_readlane_b32 s39, v254, 43
	v_readlane_b32 s40, v254, 44
	v_readlane_b32 s41, v254, 45
	v_readlane_b32 s42, v254, 46
	v_readlane_b32 s43, v254, 47
	v_readlane_b32 s44, v254, 48
	v_readlane_b32 s45, v254, 49
	v_readlane_b32 s46, v254, 50
	v_readlane_b32 s47, v254, 51
	v_readlane_b32 s48, v254, 52
	v_readlane_b32 s49, v254, 53
	v_readlane_b32 s13, v254, 1
	global_store_dwordx2 v[2:3], v[4:5], off
	s_cbranch_scc1 .LBB0_220

.LBB0_422:
	s_and_b32 s4, s7, 0xf8
	s_or_b32 s4, s4, s2
	s_lshl_b32 s11, s4, 7
	s_lshl_b32 s4, s7, 7
	v_or_b32_e32 v2, s11, v1
	s_and_b32 s12, s4, 0x380
	v_lshlrev_b32_e32 v98, 11, v2
	v_lshl_add_u64 v[104:105], v[102:103], 0, v[98:99]
	v_or_b32_e32 v2, s12, v1
	v_lshlrev_b32_e32 v98, 11, v2
	v_lshl_add_u64 v[108:109], v[100:101], 0, v[98:99]
	v_and_b32_e32 v177, 7, v106
	v_bfe_u32 v176, v106, 3, 3
	v_xor_b32_e32 v176, v177, v176
	v_sub_u32_e32 v176, v176, v177
	v_lshlrev_b32_e32 v176, 4, v176
	v_ashrrev_i32_e32 v177, 31, v176
	v_lshrrev_b32_e32 v182, 6, v106
	v_mov_b32_e32 v183, 0x110
	v_lshl_add_u32 v182, v182, 10, v183
	v_lshl_add_u64 v[184:185], v[104:105], 0, v[176:177]
	v_lshl_add_u64 v[192:193], v[108:109], 0, v[176:177]
	v_readfirstlane_b32 s15, v182
	v_add_co_u32_e32 v186, vcc, s8, v184
	v_addc_co_u32_e32 v187, vcc, 0, v185, vcc
	v_add_co_u32_e32 v188, vcc, s9, v184
	v_addc_co_u32_e32 v189, vcc, 0, v185, vcc
	v_add_co_u32_e32 v190, vcc, s10, v184
	v_addc_co_u32_e32 v191, vcc, 0, v185, vcc
	v_add_co_u32_e32 v194, vcc, s8, v192
	v_addc_co_u32_e32 v195, vcc, 0, v193, vcc
	v_add_co_u32_e32 v196, vcc, s9, v192
	v_addc_co_u32_e32 v197, vcc, 0, v193, vcc
	v_add_co_u32_e32 v198, vcc, s10, v192
	v_addc_co_u32_e32 v199, vcc, 0, v193, vcc
	v_mov_b32_e32 v30, 0
	v_mov_b32_e32 v31, v99
	v_mov_b32_e32 v32, v99
	v_mov_b32_e32 v33, v99
	v_mov_b32_e32 v62, 0
	v_mov_b32_e32 v63, v99
	v_mov_b32_e32 v64, v99
	v_mov_b32_e32 v65, v99
	v_mov_b32_e32 v74, 0
	v_mov_b32_e32 v75, v99
	v_mov_b32_e32 v76, v99
	v_mov_b32_e32 v77, v99
	v_mov_b32_e32 v78, 0
	v_mov_b32_e32 v79, v99
	v_mov_b32_e32 v80, v99
	v_mov_b32_e32 v81, v99
	v_mov_b32_e32 v82, 0
	v_mov_b32_e32 v83, v99
	v_mov_b32_e32 v84, v99
	v_mov_b32_e32 v85, v99
	v_mov_b32_e32 v86, 0
	v_mov_b32_e32 v87, v99
	v_mov_b32_e32 v88, v99
	v_mov_b32_e32 v89, v99
	v_mov_b32_e32 v90, 0
	v_mov_b32_e32 v91, v99
	v_mov_b32_e32 v92, v99
	v_mov_b32_e32 v93, v99
	v_mov_b32_e32 v94, 0
	v_mov_b32_e32 v95, v99
	v_mov_b32_e32 v96, v99
	v_mov_b32_e32 v97, v99
	v_mov_b32_e32 v66, 0
	v_mov_b32_e32 v67, v99
	v_mov_b32_e32 v68, v99
	v_mov_b32_e32 v69, v99
	v_mov_b32_e32 v38, 0
	v_mov_b32_e32 v39, v99
	v_mov_b32_e32 v40, v99
	v_mov_b32_e32 v41, v99
	v_mov_b32_e32 v34, 0
	v_mov_b32_e32 v35, v99
	v_mov_b32_e32 v36, v99
	v_mov_b32_e32 v37, v99
	v_mov_b32_e32 v18, 0
	v_mov_b32_e32 v19, v99
	v_mov_b32_e32 v20, v99
	v_mov_b32_e32 v21, v99
	v_mov_b32_e32 v14, 0
	v_mov_b32_e32 v15, v99
	v_mov_b32_e32 v16, v99
	v_mov_b32_e32 v17, v99
	v_mov_b32_e32 v10, 0
	v_mov_b32_e32 v11, v99
	v_mov_b32_e32 v12, v99
	v_mov_b32_e32 v13, v99
	v_mov_b32_e32 v6, 0
	v_mov_b32_e32 v7, v99
	v_mov_b32_e32 v8, v99
	v_mov_b32_e32 v9, v99
	v_mov_b32_e32 v2, 0
	v_mov_b32_e32 v3, v99
	v_mov_b32_e32 v4, v99
	v_mov_b32_e32 v5, v99
	s_add_u32 m0, s15, 0x0
	s_nop 0
	global_load_lds_dwordx4 v[184:185], off
	s_add_u32 m0, s15, 0x1000
	s_nop 0
	global_load_lds_dwordx4 v[186:187], off
	s_add_u32 m0, s15, 0x2000
	s_nop 0
	global_load_lds_dwordx4 v[188:189], off
	s_add_u32 m0, s15, 0x3000
	s_nop 0
	global_load_lds_dwordx4 v[190:191], off
	s_add_u32 m0, s15, 0x4000
	s_nop 0
	global_load_lds_dwordx4 v[192:193], off
	s_add_u32 m0, s15, 0x5000
	s_nop 0
	global_load_lds_dwordx4 v[194:195], off
	s_add_u32 m0, s15, 0x6000
	s_nop 0
	global_load_lds_dwordx4 v[196:197], off
	s_add_u32 m0, s15, 0x7000
	s_nop 0
	global_load_lds_dwordx4 v[198:199], off
	s_mov_b32 s4, 0x80
	s_add_u32 m0, s15, 0x8000
	v_lshl_add_u64 v[200:201], v[184:185], 0, s[4:5]
	global_load_lds_dwordx4 v[200:201], off
	s_add_u32 m0, s15, 0x9000
	v_lshl_add_u64 v[202:203], v[186:187], 0, s[4:5]
	global_load_lds_dwordx4 v[202:203], off
	s_add_u32 m0, s15, 0xa000
	v_lshl_add_u64 v[200:201], v[188:189], 0, s[4:5]
	global_load_lds_dwordx4 v[200:201], off
	s_add_u32 m0, s15, 0xb000
	v_lshl_add_u64 v[202:203], v[190:191], 0, s[4:5]
	global_load_lds_dwordx4 v[202:203], off
	s_add_u32 m0, s15, 0xc000
	v_lshl_add_u64 v[200:201], v[192:193], 0, s[4:5]
	global_load_lds_dwordx4 v[200:201], off
	s_add_u32 m0, s15, 0xd000
	v_lshl_add_u64 v[202:203], v[194:195], 0, s[4:5]
	global_load_lds_dwordx4 v[202:203], off
	s_add_u32 m0, s15, 0xe000
	v_lshl_add_u64 v[200:201], v[196:197], 0, s[4:5]
	global_load_lds_dwordx4 v[200:201], off
	s_add_u32 m0, s15, 0xf000
	v_lshl_add_u64 v[202:203], v[198:199], 0, s[4:5]
	global_load_lds_dwordx4 v[202:203], off
	s_mov_b32 s14, 0
	s_mov_b32 s13, -2
	s_waitcnt vmcnt(8)
	s_barrier
.Lglds2_12468:
	ds_read_b128 v[152:155], v112 offset:16384
	ds_read_b128 v[156:159], v112 offset:18432
	ds_read_b128 v[160:163], v110
	ds_read_b128 v[164:167], v110 offset:2048
	ds_read_b128 v[168:171], v112 offset:20480
	ds_read_b128 v[172:175], v113 offset:16384
	ds_read_b128 v[204:207], v110 offset:4096
	ds_read_b128 v[208:211], v111
	ds_read_b128 v[212:215], v116 offset:16384
	ds_read_b128 v[216:219], v116 offset:18432
	ds_read_b128 v[220:223], v114
	ds_read_b128 v[224:227], v114 offset:2048
	ds_read_b128 v[228:231], v116 offset:20480
	ds_read_b128 v[232:235], v117 offset:16384
	ds_read_b128 v[236:239], v114 offset:4096
	ds_read_b128 v[240:243], v115
	s_setprio 1
	s_waitcnt lgkmcnt(8)
	v_mfma_f32_16x16x32_bf16 v[94:97], v[152:155], v[160:163], v[94:97]
	v_mfma_f32_16x16x32_bf16 v[90:93], v[156:159], v[160:163], v[90:93]
	v_mfma_f32_16x16x32_bf16 v[86:89], v[168:171], v[160:163], v[86:89]
	v_mfma_f32_16x16x32_bf16 v[82:85], v[172:175], v[160:163], v[82:85]
	v_mfma_f32_16x16x32_bf16 v[78:81], v[152:155], v[164:167], v[78:81]
	v_mfma_f32_16x16x32_bf16 v[74:77], v[156:159], v[164:167], v[74:77]
	v_mfma_f32_16x16x32_bf16 v[62:65], v[168:171], v[164:167], v[62:65]
	v_mfma_f32_16x16x32_bf16 v[30:33], v[172:175], v[164:167], v[30:33]
	v_mfma_f32_16x16x32_bf16 v[66:69], v[152:155], v[204:207], v[66:69]
	v_mfma_f32_16x16x32_bf16 v[38:41], v[156:159], v[204:207], v[38:41]
	v_mfma_f32_16x16x32_bf16 v[34:37], v[168:171], v[204:207], v[34:37]
	v_mfma_f32_16x16x32_bf16 v[18:21], v[172:175], v[204:207], v[18:21]
	v_mfma_f32_16x16x32_bf16 v[14:17], v[152:155], v[208:211], v[14:17]
	v_mfma_f32_16x16x32_bf16 v[10:13], v[156:159], v[208:211], v[10:13]
	v_mfma_f32_16x16x32_bf16 v[6:9], v[168:171], v[208:211], v[6:9]
	v_mfma_f32_16x16x32_bf16 v[2:5], v[172:175], v[208:211], v[2:5]
	s_setprio 0
	s_waitcnt lgkmcnt(0)
	s_barrier
	s_add_i32 s4, s14, 0x80
	s_min_u32 s4, s4, 0x3c0
	s_lshl_b32 s4, s4, 1
	s_setprio 1
	v_mfma_f32_16x16x32_bf16 v[94:97], v[212:215], v[220:223], v[94:97]
	s_add_u32 m0, s15, 0x0
	v_lshl_add_u64 v[200:201], v[184:185], 0, s[4:5]
	global_load_lds_dwordx4 v[200:201], off
	v_mfma_f32_16x16x32_bf16 v[90:93], v[216:219], v[220:223], v[90:93]
	v_mfma_f32_16x16x32_bf16 v[86:89], v[228:231], v[220:223], v[86:89]
	s_add_u32 m0, s15, 0x1000
	v_lshl_add_u64 v[202:203], v[186:187], 0, s[4:5]
	global_load_lds_dwordx4 v[202:203], off
	v_mfma_f32_16x16x32_bf16 v[82:85], v[232:235], v[220:223], v[82:85]
	v_mfma_f32_16x16x32_bf16 v[78:81], v[212:215], v[224:227], v[78:81]
	s_add_u32 m0, s15, 0x2000
	v_lshl_add_u64 v[200:201], v[188:189], 0, s[4:5]
	global_load_lds_dwordx4 v[200:201], off
	v_mfma_f32_16x16x32_bf16 v[74:77], v[216:219], v[224:227], v[74:77]
	v_mfma_f32_16x16x32_bf16 v[62:65], v[228:231], v[224:227], v[62:65]
	s_add_u32 m0, s15, 0x3000
	v_lshl_add_u64 v[202:203], v[190:191], 0, s[4:5]
	global_load_lds_dwordx4 v[202:203], off
	v_mfma_f32_16x16x32_bf16 v[30:33], v[232:235], v[224:227], v[30:33]
	v_mfma_f32_16x16x32_bf16 v[66:69], v[212:215], v[236:239], v[66:69]
	s_add_u32 m0, s15, 0x4000
	v_lshl_add_u64 v[200:201], v[192:193], 0, s[4:5]
	global_load_lds_dwordx4 v[200:201], off
	v_mfma_f32_16x16x32_bf16 v[38:41], v[216:219], v[236:239], v[38:41]
	v_mfma_f32_16x16x32_bf16 v[34:37], v[228:231], v[236:239], v[34:37]
	s_add_u32 m0, s15, 0x5000
	v_lshl_add_u64 v[202:203], v[194:195], 0, s[4:5]
	global_load_lds_dwordx4 v[202:203], off
	v_mfma_f32_16x16x32_bf16 v[18:21], v[232:235], v[236:239], v[18:21]
	v_mfma_f32_16x16x32_bf16 v[14:17], v[212:215], v[240:243], v[14:17]
	s_add_u32 m0, s15, 0x6000
	v_lshl_add_u64 v[200:201], v[196:197], 0, s[4:5]
	global_load_lds_dwordx4 v[200:201], off
	v_mfma_f32_16x16x32_bf16 v[10:13], v[216:219], v[240:243], v[10:13]
	v_mfma_f32_16x16x32_bf16 v[6:9], v[228:231], v[240:243], v[6:9]
	s_add_u32 m0, s15, 0x7000
	v_lshl_add_u64 v[202:203], v[198:199], 0, s[4:5]
	global_load_lds_dwordx4 v[202:203], off
	v_mfma_f32_16x16x32_bf16 v[2:5], v[232:235], v[240:243], v[2:5]
	s_setprio 0
	s_waitcnt vmcnt(8)
	s_barrier
	ds_read_b128 v[152:155], v112 offset:49152
	ds_read_b128 v[156:159], v112 offset:51200
	ds_read_b128 v[160:163], v110 offset:32768
	ds_read_b128 v[164:167], v110 offset:34816
	ds_read_b128 v[168:171], v112 offset:53248
	ds_read_b128 v[172:175], v113 offset:49152
	ds_read_b128 v[204:207], v110 offset:36864
	ds_read_b128 v[208:211], v111 offset:32768
	ds_read_b128 v[212:215], v116 offset:49152
	ds_read_b128 v[216:219], v116 offset:51200
	ds_read_b128 v[220:223], v114 offset:32768
	ds_read_b128 v[224:227], v114 offset:34816
	ds_read_b128 v[228:231], v116 offset:53248
	ds_read_b128 v[232:235], v117 offset:49152
	ds_read_b128 v[236:239], v114 offset:36864
	ds_read_b128 v[240:243], v115 offset:32768
	s_setprio 1
	s_waitcnt lgkmcnt(8)
	v_mfma_f32_16x16x32_bf16 v[94:97], v[152:155], v[160:163], v[94:97]
	v_mfma_f32_16x16x32_bf16 v[90:93], v[156:159], v[160:163], v[90:93]
	v_mfma_f32_16x16x32_bf16 v[86:89], v[168:171], v[160:163], v[86:89]
	v_mfma_f32_16x16x32_bf16 v[82:85], v[172:175], v[160:163], v[82:85]
	v_mfma_f32_16x16x32_bf16 v[78:81], v[152:155], v[164:167], v[78:81]
	v_mfma_f32_16x16x32_bf16 v[74:77], v[156:159], v[164:167], v[74:77]
	v_mfma_f32_16x16x32_bf16 v[62:65], v[168:171], v[164:167], v[62:65]
	v_mfma_f32_16x16x32_bf16 v[30:33], v[172:175], v[164:167], v[30:33]
	v_mfma_f32_16x16x32_bf16 v[66:69], v[152:155], v[204:207], v[66:69]
	v_mfma_f32_16x16x32_bf16 v[38:41], v[156:159], v[204:207], v[38:41]
	v_mfma_f32_16x16x32_bf16 v[34:37], v[168:171], v[204:207], v[34:37]
	v_mfma_f32_16x16x32_bf16 v[18:21], v[172:175], v[204:207], v[18:21]
	v_mfma_f32_16x16x32_bf16 v[14:17], v[152:155], v[208:211], v[14:17]
	v_mfma_f32_16x16x32_bf16 v[10:13], v[156:159], v[208:211], v[10:13]
	v_mfma_f32_16x16x32_bf16 v[6:9], v[168:171], v[208:211], v[6:9]
	v_mfma_f32_16x16x32_bf16 v[2:5], v[172:175], v[208:211], v[2:5]
	s_setprio 0
	s_waitcnt lgkmcnt(0)
	s_barrier
	s_add_i32 s4, s14, 0xc0
	s_min_u32 s4, s4, 0x3c0
	s_lshl_b32 s4, s4, 1
	s_setprio 1
	v_mfma_f32_16x16x32_bf16 v[94:97], v[212:215], v[220:223], v[94:97]
	s_add_u32 m0, s15, 0x8000
	v_lshl_add_u64 v[200:201], v[184:185], 0, s[4:5]
	global_load_lds_dwordx4 v[200:201], off
	v_mfma_f32_16x16x32_bf16 v[90:93], v[216:219], v[220:223], v[90:93]
	v_mfma_f32_16x16x32_bf16 v[86:89], v[228:231], v[220:223], v[86:89]
	s_add_u32 m0, s15, 0x9000
	v_lshl_add_u64 v[202:203], v[186:187], 0, s[4:5]
	global_load_lds_dwordx4 v[202:203], off
	v_mfma_f32_16x16x32_bf16 v[82:85], v[232:235], v[220:223], v[82:85]
	v_mfma_f32_16x16x32_bf16 v[78:81], v[212:215], v[224:227], v[78:81]
	s_add_u32 m0, s15, 0xa000
	v_lshl_add_u64 v[200:201], v[188:189], 0, s[4:5]
	global_load_lds_dwordx4 v[200:201], off
	v_mfma_f32_16x16x32_bf16 v[74:77], v[216:219], v[224:227], v[74:77]
	v_mfma_f32_16x16x32_bf16 v[62:65], v[228:231], v[224:227], v[62:65]
	s_add_u32 m0, s15, 0xb000
	v_lshl_add_u64 v[202:203], v[190:191], 0, s[4:5]
	global_load_lds_dwordx4 v[202:203], off
	v_mfma_f32_16x16x32_bf16 v[30:33], v[232:235], v[224:227], v[30:33]
	v_mfma_f32_16x16x32_bf16 v[66:69], v[212:215], v[236:239], v[66:69]
	s_add_u32 m0, s15, 0xc000
	v_lshl_add_u64 v[200:201], v[192:193], 0, s[4:5]
	global_load_lds_dwordx4 v[200:201], off
	v_mfma_f32_16x16x32_bf16 v[38:41], v[216:219], v[236:239], v[38:41]
	v_mfma_f32_16x16x32_bf16 v[34:37], v[228:231], v[236:239], v[34:37]
	s_add_u32 m0, s15, 0xd000
	v_lshl_add_u64 v[202:203], v[194:195], 0, s[4:5]
	global_load_lds_dwordx4 v[202:203], off
	v_mfma_f32_16x16x32_bf16 v[18:21], v[232:235], v[236:239], v[18:21]
	v_mfma_f32_16x16x32_bf16 v[14:17], v[212:215], v[240:243], v[14:17]
	s_add_u32 m0, s15, 0xe000
	v_lshl_add_u64 v[200:201], v[196:197], 0, s[4:5]
	global_load_lds_dwordx4 v[200:201], off
	v_mfma_f32_16x16x32_bf16 v[10:13], v[216:219], v[240:243], v[10:13]
	v_mfma_f32_16x16x32_bf16 v[6:9], v[228:231], v[240:243], v[6:9]
	s_add_u32 m0, s15, 0xf000
	v_lshl_add_u64 v[202:203], v[198:199], 0, s[4:5]
	global_load_lds_dwordx4 v[202:203], off
	v_mfma_f32_16x16x32_bf16 v[2:5], v[232:235], v[240:243], v[2:5]
	s_setprio 0
	s_waitcnt vmcnt(8)
	s_barrier
	s_add_i32 s14, s14, 0x80
	s_add_i32 s13, s13, 2
	s_cmp_lt_u32 s13, 14
	s_cbranch_scc1 .Lglds2_12468
	s_waitcnt vmcnt(0)
	s_waitcnt vmcnt(0)
	v_or_b32_e32 v170, s12, v119
	v_add_lshl_u32 v98, v118, s11, 10
	v_readlane_b32 s12, v254, 8
	v_readlane_b32 s13, v254, 9
	v_readlane_b32 s14, v254, 10
	v_readlane_b32 s15, v254, 11
	v_readlane_b32 s16, v254, 12
	v_readlane_b32 s17, v254, 13
	v_readlane_b32 s18, v254, 14
	v_readlane_b32 s19, v254, 15
	v_readlane_b32 s20, v254, 16
	v_readlane_b32 s21, v254, 17
	v_readlane_b32 s22, v254, 18
	v_readlane_b32 s23, v254, 19
	v_readlane_b32 s24, v254, 20
	v_readlane_b32 s25, v254, 21
	v_readlane_b32 s26, v254, 22
	v_readlane_b32 s27, v254, 23
	v_lshlrev_b32_e32 v168, 2, v170
	v_mov_b32_e32 v169, v99
	v_lshlrev_b64 v[174:175], 2, v[98:99]
	v_lshl_add_u64 v[152:153], s[12:13], 0, v[174:175]
	v_lshl_add_u64 v[160:161], s[82:83], 0, v[174:175]
	v_lshl_add_u64 v[152:153], v[152:153], 0, v[168:169]
	v_lshl_add_u64 v[160:161], v[160:161], 0, v[168:169]
	global_load_dwordx4 v[120:123], v[152:153], off
	global_load_dwordx4 v[124:127], v[152:153], off offset:64
	global_load_dwordx4 v[128:131], v[152:153], off offset:128
	global_load_dwordx4 v[132:135], v[152:153], off offset:192
	v_or_b32_e32 v172, 0x4000, v98
	v_mov_b32_e32 v173, v99
	v_lshlrev_b64 v[174:175], 2, v[172:173]
	v_lshl_add_u64 v[154:155], s[12:13], 0, v[174:175]
	v_lshl_add_u64 v[162:163], s[82:83], 0, v[174:175]
	v_lshl_add_u64 v[154:155], v[154:155], 0, v[168:169]
	v_lshl_add_u64 v[162:163], v[162:163], 0, v[168:169]
	global_load_dwordx4 v[136:139], v[154:155], off
	global_load_dwordx4 v[140:143], v[154:155], off offset:64
	global_load_dwordx4 v[144:147], v[154:155], off offset:128
	global_load_dwordx4 v[148:151], v[154:155], off offset:192
	v_or_b32_e32 v172, 0x8000, v98
	v_mov_b32_e32 v173, v99
	v_lshlrev_b64 v[174:175], 2, v[172:173]
	v_lshl_add_u64 v[156:157], s[12:13], 0, v[174:175]
	v_lshl_add_u64 v[164:165], s[82:83], 0, v[174:175]
	v_lshl_add_u64 v[156:157], v[156:157], 0, v[168:169]
	v_lshl_add_u64 v[164:165], v[164:165], 0, v[168:169]
	global_load_dwordx4 v[22:25], v[156:157], off
	global_load_dwordx4 v[26:29], v[156:157], off offset:64
	global_load_dwordx4 v[42:45], v[156:157], off offset:128
	global_load_dwordx4 v[46:49], v[156:157], off offset:192
	v_or_b32_e32 v172, 0xc000, v98
	v_mov_b32_e32 v173, v99
	v_lshlrev_b64 v[174:175], 2, v[172:173]
	v_lshl_add_u64 v[158:159], s[12:13], 0, v[174:175]
	v_lshl_add_u64 v[166:167], s[82:83], 0, v[174:175]
	v_lshl_add_u64 v[158:159], v[158:159], 0, v[168:169]
	v_lshl_add_u64 v[166:167], v[166:167], 0, v[168:169]
	global_load_dwordx4 v[50:53], v[158:159], off
	global_load_dwordx4 v[54:57], v[158:159], off offset:64
	global_load_dwordx4 v[58:61], v[158:159], off offset:128
	global_load_dwordx4 v[70:73], v[158:159], off offset:192
	s_waitcnt vmcnt(15)
	v_pk_fma_f32 v[120:121], v[120:121], s[6:7], v[94:95] op_sel_hi:[1,0,1]
	v_pk_fma_f32 v[122:123], v[122:123], s[6:7], v[96:97] op_sel_hi:[1,0,1]
	s_waitcnt vmcnt(14)
	v_pk_fma_f32 v[124:125], v[124:125], s[6:7], v[90:91] op_sel_hi:[1,0,1]
	v_pk_fma_f32 v[126:127], v[126:127], s[6:7], v[92:93] op_sel_hi:[1,0,1]
	s_waitcnt vmcnt(13)
	v_pk_fma_f32 v[128:129], v[128:129], s[6:7], v[86:87] op_sel_hi:[1,0,1]
	v_pk_fma_f32 v[130:131], v[130:131], s[6:7], v[88:89] op_sel_hi:[1,0,1]
	s_waitcnt vmcnt(12)
	v_pk_fma_f32 v[132:133], v[132:133], s[6:7], v[82:83] op_sel_hi:[1,0,1]
	v_pk_fma_f32 v[134:135], v[134:135], s[6:7], v[84:85] op_sel_hi:[1,0,1]
	s_waitcnt vmcnt(11)
	v_pk_fma_f32 v[136:137], v[136:137], s[6:7], v[78:79] op_sel_hi:[1,0,1]
	v_pk_fma_f32 v[138:139], v[138:139], s[6:7], v[80:81] op_sel_hi:[1,0,1]
	s_waitcnt vmcnt(10)
	v_pk_fma_f32 v[140:141], v[140:141], s[6:7], v[74:75] op_sel_hi:[1,0,1]
	v_pk_fma_f32 v[142:143], v[142:143], s[6:7], v[76:77] op_sel_hi:[1,0,1]
	s_waitcnt vmcnt(9)
	v_pk_fma_f32 v[144:145], v[144:145], s[6:7], v[62:63] op_sel_hi:[1,0,1]
	v_pk_fma_f32 v[146:147], v[146:147], s[6:7], v[64:65] op_sel_hi:[1,0,1]
	s_waitcnt vmcnt(8)
	v_pk_fma_f32 v[148:149], v[148:149], s[6:7], v[30:31] op_sel_hi:[1,0,1]
	v_pk_fma_f32 v[150:151], v[150:151], s[6:7], v[32:33] op_sel_hi:[1,0,1]
	s_waitcnt vmcnt(7)
	v_pk_fma_f32 v[22:23], v[22:23], s[6:7], v[66:67] op_sel_hi:[1,0,1]
	v_pk_fma_f32 v[24:25], v[24:25], s[6:7], v[68:69] op_sel_hi:[1,0,1]
	s_waitcnt vmcnt(6)
	v_pk_fma_f32 v[26:27], v[26:27], s[6:7], v[38:39] op_sel_hi:[1,0,1]
	v_pk_fma_f32 v[28:29], v[28:29], s[6:7], v[40:41] op_sel_hi:[1,0,1]
	s_waitcnt vmcnt(5)
	v_pk_fma_f32 v[42:43], v[42:43], s[6:7], v[34:35] op_sel_hi:[1,0,1]
	v_pk_fma_f32 v[44:45], v[44:45], s[6:7], v[36:37] op_sel_hi:[1,0,1]
	s_waitcnt vmcnt(4)
	v_pk_fma_f32 v[46:47], v[46:47], s[6:7], v[18:19] op_sel_hi:[1,0,1]
	v_pk_fma_f32 v[48:49], v[48:49], s[6:7], v[20:21] op_sel_hi:[1,0,1]
	s_waitcnt vmcnt(3)
	v_pk_fma_f32 v[50:51], v[50:51], s[6:7], v[14:15] op_sel_hi:[1,0,1]
	v_pk_fma_f32 v[52:53], v[52:53], s[6:7], v[16:17] op_sel_hi:[1,0,1]
	s_waitcnt vmcnt(2)
	v_pk_fma_f32 v[54:55], v[54:55], s[6:7], v[10:11] op_sel_hi:[1,0,1]
	v_pk_fma_f32 v[56:57], v[56:57], s[6:7], v[12:13] op_sel_hi:[1,0,1]
	s_waitcnt vmcnt(1)
	v_pk_fma_f32 v[58:59], v[58:59], s[6:7], v[6:7] op_sel_hi:[1,0,1]
	v_pk_fma_f32 v[60:61], v[60:61], s[6:7], v[8:9] op_sel_hi:[1,0,1]
	s_waitcnt vmcnt(0)
	v_pk_fma_f32 v[70:71], v[70:71], s[6:7], v[2:3] op_sel_hi:[1,0,1]
	v_pk_fma_f32 v[72:73], v[72:73], s[6:7], v[4:5] op_sel_hi:[1,0,1]
	global_store_dwordx4 v[160:161], v[120:123], off
	global_store_dwordx4 v[160:161], v[124:127], off offset:64
	global_store_dwordx4 v[160:161], v[128:131], off offset:128
	global_store_dwordx4 v[160:161], v[132:135], off offset:192
	global_store_dwordx4 v[162:163], v[136:139], off
	global_store_dwordx4 v[162:163], v[140:143], off offset:64
	global_store_dwordx4 v[162:163], v[144:147], off offset:128
	global_store_dwordx4 v[162:163], v[148:151], off offset:192
	global_store_dwordx4 v[164:165], v[22:25], off
	global_store_dwordx4 v[164:165], v[26:29], off offset:64
	global_store_dwordx4 v[164:165], v[42:45], off offset:128
	global_store_dwordx4 v[164:165], v[46:49], off offset:192
	global_store_dwordx4 v[166:167], v[50:53], off
	global_store_dwordx4 v[166:167], v[54:57], off offset:64
	global_store_dwordx4 v[166:167], v[58:61], off offset:128
	global_store_dwordx4 v[166:167], v[70:73], off offset:192
	s_add_i32 s7, s7, s3
	s_cmpk_lt_u32 s7, 0x100
	s_cbranch_scc1 .LBB0_422

.LBB0_518:
	s_lshr_b32 s4, s6, 1
	s_and_b32 s4, s4, 0xf8
	s_or_b32 s4, s4, s2
	s_lshl_b32 s10, s4, 7
	s_lshl_b32 s4, s6, 7
	v_or_b32_e32 v2, s10, v1
	s_and_b32 s11, s4, 0x780
	v_lshlrev_b32_e32 v98, 10, v2
	v_lshl_add_u64 v[104:105], v[100:101], 0, v[98:99]
	v_or_b32_e32 v2, s11, v1
	v_lshlrev_b32_e32 v98, 10, v2
	v_lshl_add_u64 v[108:109], v[102:103], 0, v[98:99]
	v_and_b32_e32 v177, 7, v106
	v_bfe_u32 v176, v106, 3, 3
	v_xor_b32_e32 v176, v177, v176
	v_sub_u32_e32 v176, v176, v177
	v_lshlrev_b32_e32 v176, 4, v176
	v_ashrrev_i32_e32 v177, 31, v176
	v_lshrrev_b32_e32 v182, 6, v106
	v_mov_b32_e32 v183, 0x110
	v_lshl_add_u32 v182, v182, 10, v183
	v_lshl_add_u64 v[184:185], v[104:105], 0, v[176:177]
	v_lshl_add_u64 v[192:193], v[108:109], 0, v[176:177]
	v_readfirstlane_b32 s14, v182
	v_add_co_u32_e32 v186, vcc, s7, v184
	v_addc_co_u32_e32 v187, vcc, 0, v185, vcc
	v_add_co_u32_e32 v188, vcc, s8, v184
	v_addc_co_u32_e32 v189, vcc, 0, v185, vcc
	v_add_co_u32_e32 v190, vcc, s9, v184
	v_addc_co_u32_e32 v191, vcc, 0, v185, vcc
	v_add_co_u32_e32 v194, vcc, s7, v192
	v_addc_co_u32_e32 v195, vcc, 0, v193, vcc
	v_add_co_u32_e32 v196, vcc, s8, v192
	v_addc_co_u32_e32 v197, vcc, 0, v193, vcc
	v_add_co_u32_e32 v198, vcc, s9, v192
	v_addc_co_u32_e32 v199, vcc, 0, v193, vcc
	v_mov_b32_e32 v30, 0
	v_mov_b32_e32 v31, v99
	v_mov_b32_e32 v32, v99
	v_mov_b32_e32 v33, v99
	v_mov_b32_e32 v38, 0
	v_mov_b32_e32 v39, v99
	v_mov_b32_e32 v40, v99
	v_mov_b32_e32 v41, v99
	v_mov_b32_e32 v50, 0
	v_mov_b32_e32 v51, v99
	v_mov_b32_e32 v52, v99
	v_mov_b32_e32 v53, v99
	v_mov_b32_e32 v74, 0
	v_mov_b32_e32 v75, v99
	v_mov_b32_e32 v76, v99
	v_mov_b32_e32 v77, v99
	v_mov_b32_e32 v82, 0
	v_mov_b32_e32 v83, v99
	v_mov_b32_e32 v84, v99
	v_mov_b32_e32 v85, v99
	v_mov_b32_e32 v86, 0
	v_mov_b32_e32 v87, v99
	v_mov_b32_e32 v88, v99
	v_mov_b32_e32 v89, v99
	v_mov_b32_e32 v90, 0
	v_mov_b32_e32 v91, v99
	v_mov_b32_e32 v92, v99
	v_mov_b32_e32 v93, v99
	v_mov_b32_e32 v94, 0
	v_mov_b32_e32 v95, v99
	v_mov_b32_e32 v96, v99
	v_mov_b32_e32 v97, v99
	v_mov_b32_e32 v34, 0
	v_mov_b32_e32 v35, v99
	v_mov_b32_e32 v36, v99
	v_mov_b32_e32 v37, v99
	v_mov_b32_e32 v26, 0
	v_mov_b32_e32 v27, v99
	v_mov_b32_e32 v28, v99
	v_mov_b32_e32 v29, v99
	v_mov_b32_e32 v22, 0
	v_mov_b32_e32 v23, v99
	v_mov_b32_e32 v24, v99
	v_mov_b32_e32 v25, v99
	v_mov_b32_e32 v18, 0
	v_mov_b32_e32 v19, v99
	v_mov_b32_e32 v20, v99
	v_mov_b32_e32 v21, v99
	v_mov_b32_e32 v14, 0
	v_mov_b32_e32 v15, v99
	v_mov_b32_e32 v16, v99
	v_mov_b32_e32 v17, v99
	v_mov_b32_e32 v10, 0
	v_mov_b32_e32 v11, v99
	v_mov_b32_e32 v12, v99
	v_mov_b32_e32 v13, v99
	v_mov_b32_e32 v6, 0
	v_mov_b32_e32 v7, v99
	v_mov_b32_e32 v8, v99
	v_mov_b32_e32 v9, v99
	v_mov_b32_e32 v2, 0
	v_mov_b32_e32 v3, v99
	v_mov_b32_e32 v4, v99
	v_mov_b32_e32 v5, v99
	s_add_u32 m0, s14, 0x0
	s_nop 0
	global_load_lds_dwordx4 v[184:185], off
	s_add_u32 m0, s14, 0x1000
	s_nop 0
	global_load_lds_dwordx4 v[186:187], off
	s_add_u32 m0, s14, 0x2000
	s_nop 0
	global_load_lds_dwordx4 v[188:189], off
	s_add_u32 m0, s14, 0x3000
	s_nop 0
	global_load_lds_dwordx4 v[190:191], off
	s_add_u32 m0, s14, 0x4000
	s_nop 0
	global_load_lds_dwordx4 v[192:193], off
	s_add_u32 m0, s14, 0x5000
	s_nop 0
	global_load_lds_dwordx4 v[194:195], off
	s_add_u32 m0, s14, 0x6000
	s_nop 0
	global_load_lds_dwordx4 v[196:197], off
	s_add_u32 m0, s14, 0x7000
	s_nop 0
	global_load_lds_dwordx4 v[198:199], off
	s_mov_b32 s4, 0x80
	s_add_u32 m0, s14, 0x8000
	v_lshl_add_u64 v[200:201], v[184:185], 0, s[4:5]
	global_load_lds_dwordx4 v[200:201], off
	s_add_u32 m0, s14, 0x9000
	v_lshl_add_u64 v[202:203], v[186:187], 0, s[4:5]
	global_load_lds_dwordx4 v[202:203], off
	s_add_u32 m0, s14, 0xa000
	v_lshl_add_u64 v[200:201], v[188:189], 0, s[4:5]
	global_load_lds_dwordx4 v[200:201], off
	s_add_u32 m0, s14, 0xb000
	v_lshl_add_u64 v[202:203], v[190:191], 0, s[4:5]
	global_load_lds_dwordx4 v[202:203], off
	s_add_u32 m0, s14, 0xc000
	v_lshl_add_u64 v[200:201], v[192:193], 0, s[4:5]
	global_load_lds_dwordx4 v[200:201], off
	s_add_u32 m0, s14, 0xd000
	v_lshl_add_u64 v[202:203], v[194:195], 0, s[4:5]
	global_load_lds_dwordx4 v[202:203], off
	s_add_u32 m0, s14, 0xe000
	v_lshl_add_u64 v[200:201], v[196:197], 0, s[4:5]
	global_load_lds_dwordx4 v[200:201], off
	s_add_u32 m0, s14, 0xf000
	v_lshl_add_u64 v[202:203], v[198:199], 0, s[4:5]
	global_load_lds_dwordx4 v[202:203], off
	s_mov_b32 s13, 0
	s_mov_b32 s12, -2
	s_waitcnt vmcnt(8)
	s_barrier
.Lglds2_14401:
	ds_read_b128 v[152:155], v112 offset:16384
	ds_read_b128 v[156:159], v112 offset:18432
	ds_read_b128 v[160:163], v110
	ds_read_b128 v[164:167], v110 offset:2048
	ds_read_b128 v[168:171], v112 offset:20480
	ds_read_b128 v[172:175], v113 offset:16384
	ds_read_b128 v[204:207], v110 offset:4096
	ds_read_b128 v[208:211], v111
	ds_read_b128 v[212:215], v116 offset:16384
	ds_read_b128 v[216:219], v116 offset:18432
	ds_read_b128 v[220:223], v114
	ds_read_b128 v[224:227], v114 offset:2048
	ds_read_b128 v[228:231], v116 offset:20480
	ds_read_b128 v[232:235], v117 offset:16384
	ds_read_b128 v[236:239], v114 offset:4096
	ds_read_b128 v[240:243], v115
	s_setprio 1
	s_waitcnt lgkmcnt(8)
	v_mfma_i32_16x16x64_i8 v[94:97], v[152:155], v[160:163], v[94:97]
	v_mfma_i32_16x16x64_i8 v[90:93], v[156:159], v[160:163], v[90:93]
	v_mfma_i32_16x16x64_i8 v[86:89], v[168:171], v[160:163], v[86:89]
	v_mfma_i32_16x16x64_i8 v[82:85], v[172:175], v[160:163], v[82:85]
	v_mfma_i32_16x16x64_i8 v[74:77], v[152:155], v[164:167], v[74:77]
	v_mfma_i32_16x16x64_i8 v[50:53], v[156:159], v[164:167], v[50:53]
	v_mfma_i32_16x16x64_i8 v[38:41], v[168:171], v[164:167], v[38:41]
	v_mfma_i32_16x16x64_i8 v[30:33], v[172:175], v[164:167], v[30:33]
	v_mfma_i32_16x16x64_i8 v[34:37], v[152:155], v[204:207], v[34:37]
	v_mfma_i32_16x16x64_i8 v[26:29], v[156:159], v[204:207], v[26:29]
	v_mfma_i32_16x16x64_i8 v[22:25], v[168:171], v[204:207], v[22:25]
	v_mfma_i32_16x16x64_i8 v[18:21], v[172:175], v[204:207], v[18:21]
	v_mfma_i32_16x16x64_i8 v[14:17], v[152:155], v[208:211], v[14:17]
	v_mfma_i32_16x16x64_i8 v[10:13], v[156:159], v[208:211], v[10:13]
	v_mfma_i32_16x16x64_i8 v[6:9], v[168:171], v[208:211], v[6:9]
	v_mfma_i32_16x16x64_i8 v[2:5], v[172:175], v[208:211], v[2:5]
	s_setprio 0
	s_waitcnt lgkmcnt(0)
	s_barrier
	s_add_i32 s4, s13, 0x80
	s_min_u32 s4, s4, 0x1c0
	s_lshl_b32 s4, s4, 1
	s_setprio 1
	v_mfma_i32_16x16x64_i8 v[94:97], v[212:215], v[220:223], v[94:97]
	s_add_u32 m0, s14, 0x0
	v_lshl_add_u64 v[200:201], v[184:185], 0, s[4:5]
	global_load_lds_dwordx4 v[200:201], off
	v_mfma_i32_16x16x64_i8 v[90:93], v[216:219], v[220:223], v[90:93]
	v_mfma_i32_16x16x64_i8 v[86:89], v[228:231], v[220:223], v[86:89]
	s_add_u32 m0, s14, 0x1000
	v_lshl_add_u64 v[202:203], v[186:187], 0, s[4:5]
	global_load_lds_dwordx4 v[202:203], off
	v_mfma_i32_16x16x64_i8 v[82:85], v[232:235], v[220:223], v[82:85]
	v_mfma_i32_16x16x64_i8 v[74:77], v[212:215], v[224:227], v[74:77]
	s_add_u32 m0, s14, 0x2000
	v_lshl_add_u64 v[200:201], v[188:189], 0, s[4:5]
	global_load_lds_dwordx4 v[200:201], off
	v_mfma_i32_16x16x64_i8 v[50:53], v[216:219], v[224:227], v[50:53]
	v_mfma_i32_16x16x64_i8 v[38:41], v[228:231], v[224:227], v[38:41]
	s_add_u32 m0, s14, 0x3000
	v_lshl_add_u64 v[202:203], v[190:191], 0, s[4:5]
	global_load_lds_dwordx4 v[202:203], off
	v_mfma_i32_16x16x64_i8 v[30:33], v[232:235], v[224:227], v[30:33]
	v_mfma_i32_16x16x64_i8 v[34:37], v[212:215], v[236:239], v[34:37]
	s_add_u32 m0, s14, 0x4000
	v_lshl_add_u64 v[200:201], v[192:193], 0, s[4:5]
	global_load_lds_dwordx4 v[200:201], off
	v_mfma_i32_16x16x64_i8 v[26:29], v[216:219], v[236:239], v[26:29]
	v_mfma_i32_16x16x64_i8 v[22:25], v[228:231], v[236:239], v[22:25]
	s_add_u32 m0, s14, 0x5000
	v_lshl_add_u64 v[202:203], v[194:195], 0, s[4:5]
	global_load_lds_dwordx4 v[202:203], off
	v_mfma_i32_16x16x64_i8 v[18:21], v[232:235], v[236:239], v[18:21]
	v_mfma_i32_16x16x64_i8 v[14:17], v[212:215], v[240:243], v[14:17]
	s_add_u32 m0, s14, 0x6000
	v_lshl_add_u64 v[200:201], v[196:197], 0, s[4:5]
	global_load_lds_dwordx4 v[200:201], off
	v_mfma_i32_16x16x64_i8 v[10:13], v[216:219], v[240:243], v[10:13]
	v_mfma_i32_16x16x64_i8 v[6:9], v[228:231], v[240:243], v[6:9]
	s_add_u32 m0, s14, 0x7000
	v_lshl_add_u64 v[202:203], v[198:199], 0, s[4:5]
	global_load_lds_dwordx4 v[202:203], off
	v_mfma_i32_16x16x64_i8 v[2:5], v[232:235], v[240:243], v[2:5]
	s_setprio 0
	s_waitcnt vmcnt(8)
	s_barrier
	ds_read_b128 v[152:155], v112 offset:49152
	ds_read_b128 v[156:159], v112 offset:51200
	ds_read_b128 v[160:163], v110 offset:32768
	ds_read_b128 v[164:167], v110 offset:34816
	ds_read_b128 v[168:171], v112 offset:53248
	ds_read_b128 v[172:175], v113 offset:49152
	ds_read_b128 v[204:207], v110 offset:36864
	ds_read_b128 v[208:211], v111 offset:32768
	ds_read_b128 v[212:215], v116 offset:49152
	ds_read_b128 v[216:219], v116 offset:51200
	ds_read_b128 v[220:223], v114 offset:32768
	ds_read_b128 v[224:227], v114 offset:34816
	ds_read_b128 v[228:231], v116 offset:53248
	ds_read_b128 v[232:235], v117 offset:49152
	ds_read_b128 v[236:239], v114 offset:36864
	ds_read_b128 v[240:243], v115 offset:32768
	s_setprio 1
	s_waitcnt lgkmcnt(8)
	v_mfma_i32_16x16x64_i8 v[94:97], v[152:155], v[160:163], v[94:97]
	v_mfma_i32_16x16x64_i8 v[90:93], v[156:159], v[160:163], v[90:93]
	v_mfma_i32_16x16x64_i8 v[86:89], v[168:171], v[160:163], v[86:89]
	v_mfma_i32_16x16x64_i8 v[82:85], v[172:175], v[160:163], v[82:85]
	v_mfma_i32_16x16x64_i8 v[74:77], v[152:155], v[164:167], v[74:77]
	v_mfma_i32_16x16x64_i8 v[50:53], v[156:159], v[164:167], v[50:53]
	v_mfma_i32_16x16x64_i8 v[38:41], v[168:171], v[164:167], v[38:41]
	v_mfma_i32_16x16x64_i8 v[30:33], v[172:175], v[164:167], v[30:33]
	v_mfma_i32_16x16x64_i8 v[34:37], v[152:155], v[204:207], v[34:37]
	v_mfma_i32_16x16x64_i8 v[26:29], v[156:159], v[204:207], v[26:29]
	v_mfma_i32_16x16x64_i8 v[22:25], v[168:171], v[204:207], v[22:25]
	v_mfma_i32_16x16x64_i8 v[18:21], v[172:175], v[204:207], v[18:21]
	v_mfma_i32_16x16x64_i8 v[14:17], v[152:155], v[208:211], v[14:17]
	v_mfma_i32_16x16x64_i8 v[10:13], v[156:159], v[208:211], v[10:13]
	v_mfma_i32_16x16x64_i8 v[6:9], v[168:171], v[208:211], v[6:9]
	v_mfma_i32_16x16x64_i8 v[2:5], v[172:175], v[208:211], v[2:5]
	s_setprio 0
	s_waitcnt lgkmcnt(0)
	s_barrier
	s_add_i32 s4, s13, 0xc0
	s_min_u32 s4, s4, 0x1c0
	s_lshl_b32 s4, s4, 1
	s_setprio 1
	v_mfma_i32_16x16x64_i8 v[94:97], v[212:215], v[220:223], v[94:97]
	s_add_u32 m0, s14, 0x8000
	v_lshl_add_u64 v[200:201], v[184:185], 0, s[4:5]
	global_load_lds_dwordx4 v[200:201], off
	v_mfma_i32_16x16x64_i8 v[90:93], v[216:219], v[220:223], v[90:93]
	v_mfma_i32_16x16x64_i8 v[86:89], v[228:231], v[220:223], v[86:89]
	s_add_u32 m0, s14, 0x9000
	v_lshl_add_u64 v[202:203], v[186:187], 0, s[4:5]
	global_load_lds_dwordx4 v[202:203], off
	v_mfma_i32_16x16x64_i8 v[82:85], v[232:235], v[220:223], v[82:85]
	v_mfma_i32_16x16x64_i8 v[74:77], v[212:215], v[224:227], v[74:77]
	s_add_u32 m0, s14, 0xa000
	v_lshl_add_u64 v[200:201], v[188:189], 0, s[4:5]
	global_load_lds_dwordx4 v[200:201], off
	v_mfma_i32_16x16x64_i8 v[50:53], v[216:219], v[224:227], v[50:53]
	v_mfma_i32_16x16x64_i8 v[38:41], v[228:231], v[224:227], v[38:41]
	s_add_u32 m0, s14, 0xb000
	v_lshl_add_u64 v[202:203], v[190:191], 0, s[4:5]
	global_load_lds_dwordx4 v[202:203], off
	v_mfma_i32_16x16x64_i8 v[30:33], v[232:235], v[224:227], v[30:33]
	v_mfma_i32_16x16x64_i8 v[34:37], v[212:215], v[236:239], v[34:37]
	s_add_u32 m0, s14, 0xc000
	v_lshl_add_u64 v[200:201], v[192:193], 0, s[4:5]
	global_load_lds_dwordx4 v[200:201], off
	v_mfma_i32_16x16x64_i8 v[26:29], v[216:219], v[236:239], v[26:29]
	v_mfma_i32_16x16x64_i8 v[22:25], v[228:231], v[236:239], v[22:25]
	s_add_u32 m0, s14, 0xd000
	v_lshl_add_u64 v[202:203], v[194:195], 0, s[4:5]
	global_load_lds_dwordx4 v[202:203], off
	v_mfma_i32_16x16x64_i8 v[18:21], v[232:235], v[236:239], v[18:21]
	v_mfma_i32_16x16x64_i8 v[14:17], v[212:215], v[240:243], v[14:17]
	s_add_u32 m0, s14, 0xe000
	v_lshl_add_u64 v[200:201], v[196:197], 0, s[4:5]
	global_load_lds_dwordx4 v[200:201], off
	v_mfma_i32_16x16x64_i8 v[10:13], v[216:219], v[240:243], v[10:13]
	v_mfma_i32_16x16x64_i8 v[6:9], v[228:231], v[240:243], v[6:9]
	s_add_u32 m0, s14, 0xf000
	v_lshl_add_u64 v[202:203], v[198:199], 0, s[4:5]
	global_load_lds_dwordx4 v[202:203], off
	v_mfma_i32_16x16x64_i8 v[2:5], v[232:235], v[240:243], v[2:5]
	s_setprio 0
	s_waitcnt vmcnt(8)
	s_barrier
	s_add_i32 s13, s13, 0x80
	s_add_i32 s12, s12, 2
	s_cmp_lt_u32 s12, 6
	s_cbranch_scc1 .Lglds2_14401
	s_waitcnt vmcnt(0)
	v_cvt_f32_i32_e32 v94, v94
	v_cvt_f32_i32_e32 v95, v95
	v_cvt_f32_i32_e32 v96, v96
	v_cvt_f32_i32_e32 v97, v97
	v_cvt_f32_i32_e32 v90, v90
	v_cvt_f32_i32_e32 v91, v91
	v_cvt_f32_i32_e32 v92, v92
	v_cvt_f32_i32_e32 v93, v93
	v_cvt_f32_i32_e32 v86, v86
	v_cvt_f32_i32_e32 v87, v87
	v_cvt_f32_i32_e32 v88, v88
	v_cvt_f32_i32_e32 v89, v89
	v_cvt_f32_i32_e32 v82, v82
	v_cvt_f32_i32_e32 v83, v83
	v_cvt_f32_i32_e32 v84, v84
	v_cvt_f32_i32_e32 v85, v85
	v_cvt_f32_i32_e32 v74, v74
	v_cvt_f32_i32_e32 v75, v75
	v_cvt_f32_i32_e32 v76, v76
	v_cvt_f32_i32_e32 v77, v77
	v_cvt_f32_i32_e32 v50, v50
	v_cvt_f32_i32_e32 v51, v51
	v_cvt_f32_i32_e32 v52, v52
	v_cvt_f32_i32_e32 v53, v53
	v_cvt_f32_i32_e32 v38, v38
	v_cvt_f32_i32_e32 v39, v39
	v_cvt_f32_i32_e32 v40, v40
	v_cvt_f32_i32_e32 v41, v41
	v_cvt_f32_i32_e32 v30, v30
	v_cvt_f32_i32_e32 v31, v31
	v_cvt_f32_i32_e32 v32, v32
	v_cvt_f32_i32_e32 v33, v33
	v_cvt_f32_i32_e32 v34, v34
	v_cvt_f32_i32_e32 v35, v35
	v_cvt_f32_i32_e32 v36, v36
	v_cvt_f32_i32_e32 v37, v37
	v_cvt_f32_i32_e32 v26, v26
	v_cvt_f32_i32_e32 v27, v27
	v_cvt_f32_i32_e32 v28, v28
	v_cvt_f32_i32_e32 v29, v29
	v_cvt_f32_i32_e32 v22, v22
	v_cvt_f32_i32_e32 v23, v23
	v_cvt_f32_i32_e32 v24, v24
	v_cvt_f32_i32_e32 v25, v25
	v_cvt_f32_i32_e32 v18, v18
	v_cvt_f32_i32_e32 v19, v19
	v_cvt_f32_i32_e32 v20, v20
	v_cvt_f32_i32_e32 v21, v21
	v_cvt_f32_i32_e32 v14, v14
	v_cvt_f32_i32_e32 v15, v15
	v_cvt_f32_i32_e32 v16, v16
	v_cvt_f32_i32_e32 v17, v17
	v_cvt_f32_i32_e32 v10, v10
	v_cvt_f32_i32_e32 v11, v11
	v_cvt_f32_i32_e32 v12, v12
	v_cvt_f32_i32_e32 v13, v13
	v_cvt_f32_i32_e32 v6, v6
	v_cvt_f32_i32_e32 v7, v7
	v_cvt_f32_i32_e32 v8, v8
	v_cvt_f32_i32_e32 v9, v9
	v_cvt_f32_i32_e32 v2, v2
	v_cvt_f32_i32_e32 v3, v3
	v_cvt_f32_i32_e32 v4, v4
	v_cvt_f32_i32_e32 v5, v5
	s_waitcnt vmcnt(0)
	v_add_u32_e32 v98, s10, v118
	v_or_b32_e32 v146, s11, v119
	v_lshl_add_u64 v[144:145], v[98:99], 2, s[68:69]
	v_lshlrev_b32_e32 v148, 2, v146
	global_load_dword v136, v[144:145], off
	global_load_dword v138, v[144:145], off offset:64
	global_load_dword v140, v[144:145], off offset:128
	global_load_dword v142, v[144:145], off offset:192
	global_load_dwordx4 v[120:123], v148, s[74:75]
	global_load_dwordx4 v[124:127], v148, s[74:75] offset:64
	global_load_dwordx4 v[128:131], v148, s[74:75] offset:128
	global_load_dwordx4 v[132:135], v148, s[74:75] offset:192
	v_lshlrev_b32_e32 v146, 1, v146
	v_mov_b32_e32 v147, v99
	v_lshlrev_b64 v[42:43], 12, v[98:99]
	v_lshl_add_u64 v[42:43], s[64:65], 0, v[42:43]
	v_lshl_add_u64 v[42:43], v[42:43], 0, v[146:147]
	v_or_b32_e32 v54, 16, v98
	v_mov_b32_e32 v55, v99
	v_lshlrev_b64 v[44:45], 12, v[54:55]
	v_lshl_add_u64 v[44:45], s[64:65], 0, v[44:45]
	v_lshl_add_u64 v[44:45], v[44:45], 0, v[146:147]
	v_or_b32_e32 v54, 32, v98
	v_mov_b32_e32 v55, v99
	v_lshlrev_b64 v[46:47], 12, v[54:55]
	v_lshl_add_u64 v[46:47], s[64:65], 0, v[46:47]
	v_lshl_add_u64 v[46:47], v[46:47], 0, v[146:147]
	v_or_b32_e32 v54, 48, v98
	v_mov_b32_e32 v55, v99
	v_lshlrev_b64 v[48:49], 12, v[54:55]
	v_lshl_add_u64 v[48:49], s[64:65], 0, v[48:49]
	v_lshl_add_u64 v[48:49], v[48:49], 0, v[146:147]
	s_waitcnt vmcnt(0)
	v_pk_mul_f32 v[94:95], v[136:137], v[94:95] op_sel_hi:[0,1]
	v_pk_mul_f32 v[96:97], v[136:137], v[96:97] op_sel_hi:[0,1]
	v_pk_mul_f32 v[94:95], v[120:121], v[94:95]
	v_pk_mul_f32 v[96:97], v[96:97], v[122:123]
	v_cvt_pk_bf16_f32 v94, v94, v95
	v_cvt_pk_bf16_f32 v95, v96, v97
	global_store_dwordx2 v[42:43], v[94:95], off
	v_pk_mul_f32 v[90:91], v[136:137], v[90:91] op_sel_hi:[0,1]
	v_pk_mul_f32 v[92:93], v[136:137], v[92:93] op_sel_hi:[0,1]
	v_pk_mul_f32 v[90:91], v[124:125], v[90:91]
	v_pk_mul_f32 v[92:93], v[92:93], v[126:127]
	v_cvt_pk_bf16_f32 v90, v90, v91
	v_cvt_pk_bf16_f32 v91, v92, v93
	global_store_dwordx2 v[42:43], v[90:91], off offset:32
	v_pk_mul_f32 v[86:87], v[136:137], v[86:87] op_sel_hi:[0,1]
	v_pk_mul_f32 v[88:89], v[136:137], v[88:89] op_sel_hi:[0,1]
	v_pk_mul_f32 v[86:87], v[128:129], v[86:87]
	v_pk_mul_f32 v[88:89], v[88:89], v[130:131]
	v_cvt_pk_bf16_f32 v86, v86, v87
	v_cvt_pk_bf16_f32 v87, v88, v89
	global_store_dwordx2 v[42:43], v[86:87], off offset:64
	v_pk_mul_f32 v[82:83], v[136:137], v[82:83] op_sel_hi:[0,1]
	v_pk_mul_f32 v[84:85], v[136:137], v[84:85] op_sel_hi:[0,1]
	v_pk_mul_f32 v[82:83], v[132:133], v[82:83]
	v_pk_mul_f32 v[84:85], v[84:85], v[134:135]
	v_cvt_pk_bf16_f32 v82, v82, v83
	v_cvt_pk_bf16_f32 v83, v84, v85
	global_store_dwordx2 v[42:43], v[82:83], off offset:96
	v_pk_mul_f32 v[74:75], v[138:139], v[74:75] op_sel_hi:[0,1]
	v_pk_mul_f32 v[76:77], v[138:139], v[76:77] op_sel_hi:[0,1]
	v_pk_mul_f32 v[74:75], v[120:121], v[74:75]
	v_pk_mul_f32 v[76:77], v[76:77], v[122:123]
	v_cvt_pk_bf16_f32 v74, v74, v75
	v_cvt_pk_bf16_f32 v75, v76, v77
	global_store_dwordx2 v[44:45], v[74:75], off
	v_pk_mul_f32 v[50:51], v[138:139], v[50:51] op_sel_hi:[0,1]
	v_pk_mul_f32 v[52:53], v[138:139], v[52:53] op_sel_hi:[0,1]
	v_pk_mul_f32 v[50:51], v[124:125], v[50:51]
	v_pk_mul_f32 v[52:53], v[52:53], v[126:127]
	v_cvt_pk_bf16_f32 v50, v50, v51
	v_cvt_pk_bf16_f32 v51, v52, v53
	global_store_dwordx2 v[44:45], v[50:51], off offset:32
	v_pk_mul_f32 v[38:39], v[138:139], v[38:39] op_sel_hi:[0,1]
	v_pk_mul_f32 v[40:41], v[138:139], v[40:41] op_sel_hi:[0,1]
	v_pk_mul_f32 v[38:39], v[128:129], v[38:39]
	v_pk_mul_f32 v[40:41], v[40:41], v[130:131]
	v_cvt_pk_bf16_f32 v38, v38, v39
	v_cvt_pk_bf16_f32 v39, v40, v41
	global_store_dwordx2 v[44:45], v[38:39], off offset:64
	v_pk_mul_f32 v[30:31], v[138:139], v[30:31] op_sel_hi:[0,1]
	v_pk_mul_f32 v[32:33], v[138:139], v[32:33] op_sel_hi:[0,1]
	v_pk_mul_f32 v[30:31], v[132:133], v[30:31]
	v_pk_mul_f32 v[32:33], v[32:33], v[134:135]
	v_cvt_pk_bf16_f32 v30, v30, v31
	v_cvt_pk_bf16_f32 v31, v32, v33
	global_store_dwordx2 v[44:45], v[30:31], off offset:96
	v_pk_mul_f32 v[34:35], v[140:141], v[34:35] op_sel_hi:[0,1]
	v_pk_mul_f32 v[36:37], v[140:141], v[36:37] op_sel_hi:[0,1]
	v_pk_mul_f32 v[34:35], v[120:121], v[34:35]
	v_pk_mul_f32 v[36:37], v[36:37], v[122:123]
	v_cvt_pk_bf16_f32 v34, v34, v35
	v_cvt_pk_bf16_f32 v35, v36, v37
	global_store_dwordx2 v[46:47], v[34:35], off
	v_pk_mul_f32 v[26:27], v[140:141], v[26:27] op_sel_hi:[0,1]
	v_pk_mul_f32 v[28:29], v[140:141], v[28:29] op_sel_hi:[0,1]
	v_pk_mul_f32 v[26:27], v[124:125], v[26:27]
	v_pk_mul_f32 v[28:29], v[28:29], v[126:127]
	v_cvt_pk_bf16_f32 v26, v26, v27
	v_cvt_pk_bf16_f32 v27, v28, v29
	global_store_dwordx2 v[46:47], v[26:27], off offset:32
	v_pk_mul_f32 v[22:23], v[140:141], v[22:23] op_sel_hi:[0,1]
	v_pk_mul_f32 v[24:25], v[140:141], v[24:25] op_sel_hi:[0,1]
	v_pk_mul_f32 v[22:23], v[128:129], v[22:23]
	v_pk_mul_f32 v[24:25], v[24:25], v[130:131]
	v_cvt_pk_bf16_f32 v22, v22, v23
	v_cvt_pk_bf16_f32 v23, v24, v25
	global_store_dwordx2 v[46:47], v[22:23], off offset:64
	v_pk_mul_f32 v[18:19], v[140:141], v[18:19] op_sel_hi:[0,1]
	v_pk_mul_f32 v[20:21], v[140:141], v[20:21] op_sel_hi:[0,1]
	v_pk_mul_f32 v[18:19], v[132:133], v[18:19]
	v_pk_mul_f32 v[20:21], v[20:21], v[134:135]
	v_cvt_pk_bf16_f32 v18, v18, v19
	v_cvt_pk_bf16_f32 v19, v20, v21
	global_store_dwordx2 v[46:47], v[18:19], off offset:96
	v_pk_mul_f32 v[14:15], v[142:143], v[14:15] op_sel_hi:[0,1]
	v_pk_mul_f32 v[16:17], v[142:143], v[16:17] op_sel_hi:[0,1]
	v_pk_mul_f32 v[14:15], v[120:121], v[14:15]
	v_pk_mul_f32 v[16:17], v[16:17], v[122:123]
	v_cvt_pk_bf16_f32 v14, v14, v15
	v_cvt_pk_bf16_f32 v15, v16, v17
	global_store_dwordx2 v[48:49], v[14:15], off
	v_pk_mul_f32 v[10:11], v[142:143], v[10:11] op_sel_hi:[0,1]
	v_pk_mul_f32 v[12:13], v[142:143], v[12:13] op_sel_hi:[0,1]
	v_pk_mul_f32 v[10:11], v[124:125], v[10:11]
	v_pk_mul_f32 v[12:13], v[12:13], v[126:127]
	v_cvt_pk_bf16_f32 v10, v10, v11
	v_cvt_pk_bf16_f32 v11, v12, v13
	global_store_dwordx2 v[48:49], v[10:11], off offset:32
	v_pk_mul_f32 v[6:7], v[142:143], v[6:7] op_sel_hi:[0,1]
	v_pk_mul_f32 v[8:9], v[142:143], v[8:9] op_sel_hi:[0,1]
	v_pk_mul_f32 v[6:7], v[128:129], v[6:7]
	v_pk_mul_f32 v[8:9], v[8:9], v[130:131]
	v_cvt_pk_bf16_f32 v6, v6, v7
	v_cvt_pk_bf16_f32 v7, v8, v9
	global_store_dwordx2 v[48:49], v[6:7], off offset:64
	v_pk_mul_f32 v[2:3], v[142:143], v[2:3] op_sel_hi:[0,1]
	v_pk_mul_f32 v[4:5], v[142:143], v[4:5] op_sel_hi:[0,1]
	v_pk_mul_f32 v[2:3], v[132:133], v[2:3]
	v_pk_mul_f32 v[4:5], v[4:5], v[134:135]
	v_cvt_pk_bf16_f32 v2, v2, v3
	v_cvt_pk_bf16_f32 v3, v4, v5
	global_store_dwordx2 v[48:49], v[2:3], off offset:96
	s_add_i32 s6, s6, s3
	s_cmpk_lt_u32 s6, 0x200
	s_cbranch_scc1 .LBB0_518

.LBB0_664:
	s_cmpk_lt_u32 s3, 0x1c0
	s_cselect_b32 s4, 1, 2
	s_cselect_b32 s13, 7, 6
	s_cmpk_gt_u32 s3, 0xdf
	s_cselect_b32 s4, s4, 0
	s_mul_i32 s14, s4, 0xff20
	s_add_i32 s16, s14, s3
	s_sext_i32_i16 s14, s16
	v_cvt_f32_ubyte0_e32 v3, s13
	v_cvt_f32_i32_e32 v2, s14
	v_rcp_iflag_f32_e32 v4, v3
	s_ashr_i32 s14, s14, 30
	s_or_b32 s17, s14, 1
	s_mul_i32 s4, s4, 7
	v_mul_f32_e32 v4, v2, v4
	v_trunc_f32_e32 v4, v4
	v_fma_f32 v2, -v4, v3, v2
	v_cvt_i32_f32_e32 v4, v4
	v_cmp_ge_f32_e64 s[14:15], |v2|, v3
	s_and_b64 s[14:15], s[14:15], exec
	s_cselect_b32 s14, s17, 0
	v_readfirstlane_b32 s15, v4
	s_add_i32 s14, s15, s14
	s_sext_i32_i16 s15, s14
	s_mul_i32 s14, s14, s13
	s_sub_i32 s13, s16, s14
	s_sext_i32_i16 s13, s13
	s_add_i32 s4, s4, s13
	s_lshl_b32 s13, s15, 10
	s_or_b32 s13, s13, s6
	v_or_b32_e32 v2, s13, v1
	v_ashrrev_i32_e32 v3, 31, v2
	s_lshl_b32 s14, s4, 7
	v_lshlrev_b64 v[2:3], 12, v[2:3]
	v_lshl_add_u64 v[104:105], v[100:101], 0, v[2:3]
	v_or_b32_e32 v2, s14, v1
	v_ashrrev_i32_e32 v3, 31, v2
	v_lshlrev_b64 v[2:3], 11, v[2:3]
	v_add_co_u32_e32 v6, vcc, s7, v104
	v_lshl_add_u64 v[108:109], v[102:103], 0, v[2:3]
	v_and_b32_e32 v181, 7, v106
	v_bfe_u32 v180, v106, 3, 3
	v_xor_b32_e32 v180, v181, v180
	v_sub_u32_e32 v180, v180, v181
	v_lshlrev_b32_e32 v180, 4, v180
	v_ashrrev_i32_e32 v181, 31, v180
	v_lshrrev_b32_e32 v186, 6, v106
	v_mov_b32_e32 v187, 0x110
	v_lshl_add_u32 v186, v186, 10, v187
	v_lshl_add_u64 v[188:189], v[104:105], 0, v[180:181]
	v_lshl_add_u64 v[196:197], v[108:109], 0, v[180:181]
	v_readfirstlane_b32 s17, v186
	v_add_co_u32_e32 v190, vcc, s7, v188
	v_addc_co_u32_e32 v191, vcc, 0, v189, vcc
	v_add_co_u32_e32 v192, vcc, s9, v188
	v_addc_co_u32_e32 v193, vcc, 0, v189, vcc
	v_add_co_u32_e32 v194, vcc, s10, v188
	v_addc_co_u32_e32 v195, vcc, 0, v189, vcc
	v_add_co_u32_e32 v198, vcc, s8, v196
	v_addc_co_u32_e32 v199, vcc, 0, v197, vcc
	v_add_co_u32_e32 v200, vcc, s7, v196
	v_addc_co_u32_e32 v201, vcc, 0, v197, vcc
	v_add_co_u32_e32 v202, vcc, s11, v196
	v_addc_co_u32_e32 v203, vcc, 0, v197, vcc
	v_mov_b32_e32 v34, 0
	v_mov_b32_e32 v35, v99
	v_mov_b32_e32 v36, v99
	v_mov_b32_e32 v37, v99
	v_mov_b32_e32 v38, 0
	v_mov_b32_e32 v39, v99
	v_mov_b32_e32 v40, v99
	v_mov_b32_e32 v41, v99
	v_mov_b32_e32 v42, 0
	v_mov_b32_e32 v43, v99
	v_mov_b32_e32 v44, v99
	v_mov_b32_e32 v45, v99
	v_mov_b32_e32 v54, 0
	v_mov_b32_e32 v55, v99
	v_mov_b32_e32 v56, v99
	v_mov_b32_e32 v57, v99
	v_mov_b32_e32 v82, 0
	v_mov_b32_e32 v83, v99
	v_mov_b32_e32 v84, v99
	v_mov_b32_e32 v85, v99
	v_mov_b32_e32 v86, 0
	v_mov_b32_e32 v87, v99
	v_mov_b32_e32 v88, v99
	v_mov_b32_e32 v89, v99
	v_mov_b32_e32 v90, 0
	v_mov_b32_e32 v91, v99
	v_mov_b32_e32 v92, v99
	v_mov_b32_e32 v93, v99
	v_mov_b32_e32 v94, 0
	v_mov_b32_e32 v95, v99
	v_mov_b32_e32 v96, v99
	v_mov_b32_e32 v97, v99
	v_mov_b32_e32 v78, 0
	v_mov_b32_e32 v79, v99
	v_mov_b32_e32 v80, v99
	v_mov_b32_e32 v81, v99
	v_mov_b32_e32 v74, 0
	v_mov_b32_e32 v75, v99
	v_mov_b32_e32 v76, v99
	v_mov_b32_e32 v77, v99
	v_mov_b32_e32 v70, 0
	v_mov_b32_e32 v71, v99
	v_mov_b32_e32 v72, v99
	v_mov_b32_e32 v73, v99
	v_mov_b32_e32 v66, 0
	v_mov_b32_e32 v67, v99
	v_mov_b32_e32 v68, v99
	v_mov_b32_e32 v69, v99
	v_mov_b32_e32 v62, 0
	v_mov_b32_e32 v63, v99
	v_mov_b32_e32 v64, v99
	v_mov_b32_e32 v65, v99
	v_mov_b32_e32 v58, 0
	v_mov_b32_e32 v59, v99
	v_mov_b32_e32 v60, v99
	v_mov_b32_e32 v61, v99
	v_mov_b32_e32 v50, 0
	v_mov_b32_e32 v51, v99
	v_mov_b32_e32 v52, v99
	v_mov_b32_e32 v53, v99
	v_mov_b32_e32 v46, 0
	v_mov_b32_e32 v47, v99
	v_mov_b32_e32 v48, v99
	v_mov_b32_e32 v49, v99
	s_add_u32 m0, s17, 0x0
	s_nop 0
	global_load_lds_dwordx4 v[188:189], off
	s_add_u32 m0, s17, 0x1000
	s_nop 0
	global_load_lds_dwordx4 v[190:191], off
	s_add_u32 m0, s17, 0x2000
	s_nop 0
	global_load_lds_dwordx4 v[192:193], off
	s_add_u32 m0, s17, 0x3000
	s_nop 0
	global_load_lds_dwordx4 v[194:195], off
	s_add_u32 m0, s17, 0x4000
	s_nop 0
	global_load_lds_dwordx4 v[196:197], off
	s_add_u32 m0, s17, 0x5000
	s_nop 0
	global_load_lds_dwordx4 v[198:199], off
	s_add_u32 m0, s17, 0x6000
	s_nop 0
	global_load_lds_dwordx4 v[200:201], off
	s_add_u32 m0, s17, 0x7000
	s_nop 0
	global_load_lds_dwordx4 v[202:203], off
	s_mov_b32 s4, 0x80
	s_add_u32 m0, s17, 0x8000
	v_lshl_add_u64 v[204:205], v[188:189], 0, s[4:5]
	global_load_lds_dwordx4 v[204:205], off
	s_add_u32 m0, s17, 0x9000
	v_lshl_add_u64 v[206:207], v[190:191], 0, s[4:5]
	global_load_lds_dwordx4 v[206:207], off
	s_add_u32 m0, s17, 0xa000
	v_lshl_add_u64 v[204:205], v[192:193], 0, s[4:5]
	global_load_lds_dwordx4 v[204:205], off
	s_add_u32 m0, s17, 0xb000
	v_lshl_add_u64 v[206:207], v[194:195], 0, s[4:5]
	global_load_lds_dwordx4 v[206:207], off
	s_add_u32 m0, s17, 0xc000
	v_lshl_add_u64 v[204:205], v[196:197], 0, s[4:5]
	global_load_lds_dwordx4 v[204:205], off
	s_add_u32 m0, s17, 0xd000
	v_lshl_add_u64 v[206:207], v[198:199], 0, s[4:5]
	global_load_lds_dwordx4 v[206:207], off
	s_add_u32 m0, s17, 0xe000
	v_lshl_add_u64 v[204:205], v[200:201], 0, s[4:5]
	global_load_lds_dwordx4 v[204:205], off
	s_add_u32 m0, s17, 0xf000
	v_lshl_add_u64 v[206:207], v[202:203], 0, s[4:5]
	global_load_lds_dwordx4 v[206:207], off
	s_mov_b32 s16, 0
	s_mov_b32 s15, -2
	s_waitcnt vmcnt(8)
	s_barrier
.Lglds2_22142:
	ds_read_b128 v[152:155], v112 offset:16384
	ds_read_b128 v[156:159], v112 offset:18432
	ds_read_b128 v[160:163], v110
	ds_read_b128 v[164:167], v110 offset:2048
	ds_read_b128 v[168:171], v112 offset:20480
	ds_read_b128 v[172:175], v113 offset:16384
	ds_read_b128 v[208:211], v110 offset:4096
	ds_read_b128 v[212:215], v111
	ds_read_b128 v[216:219], v116 offset:16384
	ds_read_b128 v[220:223], v116 offset:18432
	ds_read_b128 v[224:227], v114
	ds_read_b128 v[228:231], v114 offset:2048
	ds_read_b128 v[232:235], v116 offset:20480
	ds_read_b128 v[236:239], v117 offset:16384
	ds_read_b128 v[240:243], v114 offset:4096
	ds_read_b128 v[244:247], v115
	s_setprio 1
	s_waitcnt lgkmcnt(8)
	v_mfma_f32_16x16x32_bf16 v[94:97], v[152:155], v[160:163], v[94:97]
	v_mfma_f32_16x16x32_bf16 v[90:93], v[156:159], v[160:163], v[90:93]
	v_mfma_f32_16x16x32_bf16 v[86:89], v[168:171], v[160:163], v[86:89]
	v_mfma_f32_16x16x32_bf16 v[82:85], v[172:175], v[160:163], v[82:85]
	v_mfma_f32_16x16x32_bf16 v[54:57], v[152:155], v[164:167], v[54:57]
	v_mfma_f32_16x16x32_bf16 v[42:45], v[156:159], v[164:167], v[42:45]
	v_mfma_f32_16x16x32_bf16 v[38:41], v[168:171], v[164:167], v[38:41]
	v_mfma_f32_16x16x32_bf16 v[34:37], v[172:175], v[164:167], v[34:37]
	v_mfma_f32_16x16x32_bf16 v[78:81], v[152:155], v[208:211], v[78:81]
	v_mfma_f32_16x16x32_bf16 v[74:77], v[156:159], v[208:211], v[74:77]
	v_mfma_f32_16x16x32_bf16 v[70:73], v[168:171], v[208:211], v[70:73]
	v_mfma_f32_16x16x32_bf16 v[66:69], v[172:175], v[208:211], v[66:69]
	v_mfma_f32_16x16x32_bf16 v[62:65], v[152:155], v[212:215], v[62:65]
	v_mfma_f32_16x16x32_bf16 v[58:61], v[156:159], v[212:215], v[58:61]
	v_mfma_f32_16x16x32_bf16 v[50:53], v[168:171], v[212:215], v[50:53]
	v_mfma_f32_16x16x32_bf16 v[46:49], v[172:175], v[212:215], v[46:49]
	s_setprio 0
	s_waitcnt lgkmcnt(0)
	s_barrier
	s_add_i32 s4, s16, 0x80
	s_min_u32 s4, s4, 0x3c0
	s_lshl_b32 s4, s4, 1
	s_setprio 1
	v_mfma_f32_16x16x32_bf16 v[94:97], v[216:219], v[224:227], v[94:97]
	s_add_u32 m0, s17, 0x0
	v_lshl_add_u64 v[204:205], v[188:189], 0, s[4:5]
	global_load_lds_dwordx4 v[204:205], off
	v_mfma_f32_16x16x32_bf16 v[90:93], v[220:223], v[224:227], v[90:93]
	v_mfma_f32_16x16x32_bf16 v[86:89], v[232:235], v[224:227], v[86:89]
	s_add_u32 m0, s17, 0x1000
	v_lshl_add_u64 v[206:207], v[190:191], 0, s[4:5]
	global_load_lds_dwordx4 v[206:207], off
	v_mfma_f32_16x16x32_bf16 v[82:85], v[236:239], v[224:227], v[82:85]
	v_mfma_f32_16x16x32_bf16 v[54:57], v[216:219], v[228:231], v[54:57]
	s_add_u32 m0, s17, 0x2000
	v_lshl_add_u64 v[204:205], v[192:193], 0, s[4:5]
	global_load_lds_dwordx4 v[204:205], off
	v_mfma_f32_16x16x32_bf16 v[42:45], v[220:223], v[228:231], v[42:45]
	v_mfma_f32_16x16x32_bf16 v[38:41], v[232:235], v[228:231], v[38:41]
	s_add_u32 m0, s17, 0x3000
	v_lshl_add_u64 v[206:207], v[194:195], 0, s[4:5]
	global_load_lds_dwordx4 v[206:207], off
	v_mfma_f32_16x16x32_bf16 v[34:37], v[236:239], v[228:231], v[34:37]
	v_mfma_f32_16x16x32_bf16 v[78:81], v[216:219], v[240:243], v[78:81]
	s_add_u32 m0, s17, 0x4000
	v_lshl_add_u64 v[204:205], v[196:197], 0, s[4:5]
	global_load_lds_dwordx4 v[204:205], off
	v_mfma_f32_16x16x32_bf16 v[74:77], v[220:223], v[240:243], v[74:77]
	v_mfma_f32_16x16x32_bf16 v[70:73], v[232:235], v[240:243], v[70:73]
	s_add_u32 m0, s17, 0x5000
	v_lshl_add_u64 v[206:207], v[198:199], 0, s[4:5]
	global_load_lds_dwordx4 v[206:207], off
	v_mfma_f32_16x16x32_bf16 v[66:69], v[236:239], v[240:243], v[66:69]
	v_mfma_f32_16x16x32_bf16 v[62:65], v[216:219], v[244:247], v[62:65]
	s_add_u32 m0, s17, 0x6000
	v_lshl_add_u64 v[204:205], v[200:201], 0, s[4:5]
	global_load_lds_dwordx4 v[204:205], off
	v_mfma_f32_16x16x32_bf16 v[58:61], v[220:223], v[244:247], v[58:61]
	v_mfma_f32_16x16x32_bf16 v[50:53], v[232:235], v[244:247], v[50:53]
	s_add_u32 m0, s17, 0x7000
	v_lshl_add_u64 v[206:207], v[202:203], 0, s[4:5]
	global_load_lds_dwordx4 v[206:207], off
	v_mfma_f32_16x16x32_bf16 v[46:49], v[236:239], v[244:247], v[46:49]
	s_setprio 0
	s_waitcnt vmcnt(8)
	s_barrier
	ds_read_b128 v[152:155], v112 offset:49152
	ds_read_b128 v[156:159], v112 offset:51200
	ds_read_b128 v[160:163], v110 offset:32768
	ds_read_b128 v[164:167], v110 offset:34816
	ds_read_b128 v[168:171], v112 offset:53248
	ds_read_b128 v[172:175], v113 offset:49152
	ds_read_b128 v[208:211], v110 offset:36864
	ds_read_b128 v[212:215], v111 offset:32768
	ds_read_b128 v[216:219], v116 offset:49152
	ds_read_b128 v[220:223], v116 offset:51200
	ds_read_b128 v[224:227], v114 offset:32768
	ds_read_b128 v[228:231], v114 offset:34816
	ds_read_b128 v[232:235], v116 offset:53248
	ds_read_b128 v[236:239], v117 offset:49152
	ds_read_b128 v[240:243], v114 offset:36864
	ds_read_b128 v[244:247], v115 offset:32768
	s_setprio 1
	s_waitcnt lgkmcnt(8)
	v_mfma_f32_16x16x32_bf16 v[94:97], v[152:155], v[160:163], v[94:97]
	v_mfma_f32_16x16x32_bf16 v[90:93], v[156:159], v[160:163], v[90:93]
	v_mfma_f32_16x16x32_bf16 v[86:89], v[168:171], v[160:163], v[86:89]
	v_mfma_f32_16x16x32_bf16 v[82:85], v[172:175], v[160:163], v[82:85]
	v_mfma_f32_16x16x32_bf16 v[54:57], v[152:155], v[164:167], v[54:57]
	v_mfma_f32_16x16x32_bf16 v[42:45], v[156:159], v[164:167], v[42:45]
	v_mfma_f32_16x16x32_bf16 v[38:41], v[168:171], v[164:167], v[38:41]
	v_mfma_f32_16x16x32_bf16 v[34:37], v[172:175], v[164:167], v[34:37]
	v_mfma_f32_16x16x32_bf16 v[78:81], v[152:155], v[208:211], v[78:81]
	v_mfma_f32_16x16x32_bf16 v[74:77], v[156:159], v[208:211], v[74:77]
	v_mfma_f32_16x16x32_bf16 v[70:73], v[168:171], v[208:211], v[70:73]
	v_mfma_f32_16x16x32_bf16 v[66:69], v[172:175], v[208:211], v[66:69]
	v_mfma_f32_16x16x32_bf16 v[62:65], v[152:155], v[212:215], v[62:65]
	v_mfma_f32_16x16x32_bf16 v[58:61], v[156:159], v[212:215], v[58:61]
	v_mfma_f32_16x16x32_bf16 v[50:53], v[168:171], v[212:215], v[50:53]
	v_mfma_f32_16x16x32_bf16 v[46:49], v[172:175], v[212:215], v[46:49]
	s_setprio 0
	s_waitcnt lgkmcnt(0)
	s_barrier
	s_add_i32 s4, s16, 0xc0
	s_min_u32 s4, s4, 0x3c0
	s_lshl_b32 s4, s4, 1
	s_setprio 1
	v_mfma_f32_16x16x32_bf16 v[94:97], v[216:219], v[224:227], v[94:97]
	s_add_u32 m0, s17, 0x8000
	v_lshl_add_u64 v[204:205], v[188:189], 0, s[4:5]
	global_load_lds_dwordx4 v[204:205], off
	v_mfma_f32_16x16x32_bf16 v[90:93], v[220:223], v[224:227], v[90:93]
	v_mfma_f32_16x16x32_bf16 v[86:89], v[232:235], v[224:227], v[86:89]
	s_add_u32 m0, s17, 0x9000
	v_lshl_add_u64 v[206:207], v[190:191], 0, s[4:5]
	global_load_lds_dwordx4 v[206:207], off
	v_mfma_f32_16x16x32_bf16 v[82:85], v[236:239], v[224:227], v[82:85]
	v_mfma_f32_16x16x32_bf16 v[54:57], v[216:219], v[228:231], v[54:57]
	s_add_u32 m0, s17, 0xa000
	v_lshl_add_u64 v[204:205], v[192:193], 0, s[4:5]
	global_load_lds_dwordx4 v[204:205], off
	v_mfma_f32_16x16x32_bf16 v[42:45], v[220:223], v[228:231], v[42:45]
	v_mfma_f32_16x16x32_bf16 v[38:41], v[232:235], v[228:231], v[38:41]
	s_add_u32 m0, s17, 0xb000
	v_lshl_add_u64 v[206:207], v[194:195], 0, s[4:5]
	global_load_lds_dwordx4 v[206:207], off
	v_mfma_f32_16x16x32_bf16 v[34:37], v[236:239], v[228:231], v[34:37]
	v_mfma_f32_16x16x32_bf16 v[78:81], v[216:219], v[240:243], v[78:81]
	s_add_u32 m0, s17, 0xc000
	v_lshl_add_u64 v[204:205], v[196:197], 0, s[4:5]
	global_load_lds_dwordx4 v[204:205], off
	v_mfma_f32_16x16x32_bf16 v[74:77], v[220:223], v[240:243], v[74:77]
	v_mfma_f32_16x16x32_bf16 v[70:73], v[232:235], v[240:243], v[70:73]
	s_add_u32 m0, s17, 0xd000
	v_lshl_add_u64 v[206:207], v[198:199], 0, s[4:5]
	global_load_lds_dwordx4 v[206:207], off
	v_mfma_f32_16x16x32_bf16 v[66:69], v[236:239], v[240:243], v[66:69]
	v_mfma_f32_16x16x32_bf16 v[62:65], v[216:219], v[244:247], v[62:65]
	s_add_u32 m0, s17, 0xe000
	v_lshl_add_u64 v[204:205], v[200:201], 0, s[4:5]
	global_load_lds_dwordx4 v[204:205], off
	v_mfma_f32_16x16x32_bf16 v[58:61], v[220:223], v[244:247], v[58:61]
	v_mfma_f32_16x16x32_bf16 v[50:53], v[232:235], v[244:247], v[50:53]
	s_add_u32 m0, s17, 0xf000
	v_lshl_add_u64 v[206:207], v[202:203], 0, s[4:5]
	global_load_lds_dwordx4 v[206:207], off
	v_mfma_f32_16x16x32_bf16 v[46:49], v[236:239], v[244:247], v[46:49]
	s_setprio 0
	s_waitcnt vmcnt(8)
	s_barrier
	s_add_i32 s16, s16, 0x80
	s_add_i32 s15, s15, 2
	s_cmp_lt_u32 s15, 14
	s_cbranch_scc1 .Lglds2_22142
	s_waitcnt vmcnt(0)
	s_waitcnt vmcnt(7)
	v_or_b32_e32 v2, s14, v119
	s_waitcnt vmcnt(5)
	v_add_u32_e32 v10, s13, v118
	v_mov_b64_e32 v[4:5], s[64:65]
	v_ashrrev_i32_e32 v3, 31, v2
	v_mad_i64_i32 v[6:7], s[14:15], v10, s12, v[4:5]
	v_lshlrev_b64 v[2:3], 1, v[2:3]
	v_lshl_add_u64 v[6:7], v[6:7], 0, v[2:3]
	v_cvt_pk_bf16_f32 v8, v94, v95
	v_cvt_pk_bf16_f32 v9, v96, v97
	global_store_dwordx2 v[6:7], v[8:9], off
	v_cvt_pk_bf16_f32 v8, v90, v91
	v_cvt_pk_bf16_f32 v9, v92, v93
	global_store_dwordx2 v[6:7], v[8:9], off offset:32
	v_cvt_pk_bf16_f32 v8, v86, v87
	v_cvt_pk_bf16_f32 v9, v88, v89
	global_store_dwordx2 v[6:7], v[8:9], off offset:64
	v_cvt_pk_bf16_f32 v8, v82, v83
	v_cvt_pk_bf16_f32 v9, v84, v85
	global_store_dwordx2 v[6:7], v[8:9], off offset:96
	v_or_b32_e32 v6, 16, v10
	v_mad_i64_i32 v[6:7], s[14:15], v6, s12, v[4:5]
	v_lshl_add_u64 v[6:7], v[6:7], 0, v[2:3]
	v_cvt_pk_bf16_f32 v8, v54, v55
	v_cvt_pk_bf16_f32 v9, v56, v57
	global_store_dwordx2 v[6:7], v[8:9], off
	v_cvt_pk_bf16_f32 v8, v42, v43
	v_cvt_pk_bf16_f32 v9, v44, v45
	global_store_dwordx2 v[6:7], v[8:9], off offset:32
	v_cvt_pk_bf16_f32 v8, v38, v39
	v_cvt_pk_bf16_f32 v9, v40, v41
	global_store_dwordx2 v[6:7], v[8:9], off offset:64
	v_cvt_pk_bf16_f32 v8, v34, v35
	v_cvt_pk_bf16_f32 v9, v36, v37
	global_store_dwordx2 v[6:7], v[8:9], off offset:96
	v_or_b32_e32 v6, 32, v10
	v_mad_i64_i32 v[6:7], s[14:15], v6, s12, v[4:5]
	v_lshl_add_u64 v[6:7], v[6:7], 0, v[2:3]
	v_cvt_pk_bf16_f32 v8, v78, v79
	v_cvt_pk_bf16_f32 v9, v80, v81
	global_store_dwordx2 v[6:7], v[8:9], off
	v_cvt_pk_bf16_f32 v8, v74, v75
	v_cvt_pk_bf16_f32 v9, v76, v77
	global_store_dwordx2 v[6:7], v[8:9], off offset:32
	v_cvt_pk_bf16_f32 v8, v70, v71
	v_cvt_pk_bf16_f32 v9, v72, v73
	global_store_dwordx2 v[6:7], v[8:9], off offset:64
	v_cvt_pk_bf16_f32 v8, v66, v67
	v_cvt_pk_bf16_f32 v9, v68, v69
	global_store_dwordx2 v[6:7], v[8:9], off offset:96
	v_or_b32_e32 v6, 48, v10
	v_mad_i64_i32 v[4:5], s[14:15], v6, s12, v[4:5]
	v_lshl_add_u64 v[2:3], v[4:5], 0, v[2:3]
	v_cvt_pk_bf16_f32 v4, v62, v63
	v_cvt_pk_bf16_f32 v5, v64, v65
	global_store_dwordx2 v[2:3], v[4:5], off
	v_cvt_pk_bf16_f32 v4, v58, v59
	v_cvt_pk_bf16_f32 v5, v60, v61
	global_store_dwordx2 v[2:3], v[4:5], off offset:32
	v_cvt_pk_bf16_f32 v4, v50, v51
	v_cvt_pk_bf16_f32 v5, v52, v53
	s_add_i32 s3, s3, s2
	global_store_dwordx2 v[2:3], v[4:5], off offset:64
	v_cvt_pk_bf16_f32 v4, v46, v47
	v_cvt_pk_bf16_f32 v5, v48, v49
	s_cmpk_lt_u32 s3, 0x280
	global_store_dwordx2 v[2:3], v[4:5], off offset:96
	s_cbranch_scc1 .LBB0_664

.LBB0_798:
	s_and_b32 s4, s7, 0xf8
	s_or_b32 s4, s4, s2
	s_lshl_b32 s11, s4, 7
	s_lshl_b32 s4, s7, 7
	v_or_b32_e32 v0, s11, v107
	s_and_b32 s12, s4, 0x380
	v_lshlrev_b32_e32 v96, 11, v0
	v_lshl_add_u64 v[102:103], v[100:101], 0, v[96:97]
	v_or_b32_e32 v0, s12, v107
	v_lshlrev_b32_e32 v96, 11, v0
	v_lshl_add_u64 v[104:105], v[98:99], 0, v[96:97]
	v_and_b32_e32 v181, 7, v106
	v_bfe_u32 v180, v106, 3, 3
	v_xor_b32_e32 v180, v181, v180
	v_sub_u32_e32 v180, v180, v181
	v_lshlrev_b32_e32 v180, 4, v180
	v_ashrrev_i32_e32 v181, 31, v180
	v_lshrrev_b32_e32 v186, 6, v106
	v_mov_b32_e32 v187, 0x110
	v_lshl_add_u32 v186, v186, 10, v187
	v_lshl_add_u64 v[188:189], v[102:103], 0, v[180:181]
	v_lshl_add_u64 v[196:197], v[104:105], 0, v[180:181]
	v_readfirstlane_b32 s15, v186
	v_add_co_u32_e32 v190, vcc, s8, v188
	v_addc_co_u32_e32 v191, vcc, 0, v189, vcc
	v_add_co_u32_e32 v192, vcc, s9, v188
	v_addc_co_u32_e32 v193, vcc, 0, v189, vcc
	v_add_co_u32_e32 v194, vcc, s10, v188
	v_addc_co_u32_e32 v195, vcc, 0, v189, vcc
	v_add_co_u32_e32 v198, vcc, s8, v196
	v_addc_co_u32_e32 v199, vcc, 0, v197, vcc
	v_add_co_u32_e32 v200, vcc, s9, v196
	v_addc_co_u32_e32 v201, vcc, 0, v197, vcc
	v_add_co_u32_e32 v202, vcc, s10, v196
	v_addc_co_u32_e32 v203, vcc, 0, v197, vcc
	v_mov_b32_e32 v28, 0
	v_mov_b32_e32 v29, v97
	v_mov_b32_e32 v30, v97
	v_mov_b32_e32 v31, v97
	v_mov_b32_e32 v60, 0
	v_mov_b32_e32 v61, v97
	v_mov_b32_e32 v62, v97
	v_mov_b32_e32 v63, v97
	v_mov_b32_e32 v72, 0
	v_mov_b32_e32 v73, v97
	v_mov_b32_e32 v74, v97
	v_mov_b32_e32 v75, v97
	v_mov_b32_e32 v76, 0
	v_mov_b32_e32 v77, v97
	v_mov_b32_e32 v78, v97
	v_mov_b32_e32 v79, v97
	v_mov_b32_e32 v80, 0
	v_mov_b32_e32 v81, v97
	v_mov_b32_e32 v82, v97
	v_mov_b32_e32 v83, v97
	v_mov_b32_e32 v84, 0
	v_mov_b32_e32 v85, v97
	v_mov_b32_e32 v86, v97
	v_mov_b32_e32 v87, v97
	v_mov_b32_e32 v88, 0
	v_mov_b32_e32 v89, v97
	v_mov_b32_e32 v90, v97
	v_mov_b32_e32 v91, v97
	v_mov_b32_e32 v92, 0
	v_mov_b32_e32 v93, v97
	v_mov_b32_e32 v94, v97
	v_mov_b32_e32 v95, v97
	v_mov_b32_e32 v64, 0
	v_mov_b32_e32 v65, v97
	v_mov_b32_e32 v66, v97
	v_mov_b32_e32 v67, v97
	v_mov_b32_e32 v36, 0
	v_mov_b32_e32 v37, v97
	v_mov_b32_e32 v38, v97
	v_mov_b32_e32 v39, v97
	v_mov_b32_e32 v32, 0
	v_mov_b32_e32 v33, v97
	v_mov_b32_e32 v34, v97
	v_mov_b32_e32 v35, v97
	v_mov_b32_e32 v16, 0
	v_mov_b32_e32 v17, v97
	v_mov_b32_e32 v18, v97
	v_mov_b32_e32 v19, v97
	v_mov_b32_e32 v12, 0
	v_mov_b32_e32 v13, v97
	v_mov_b32_e32 v14, v97
	v_mov_b32_e32 v15, v97
	v_mov_b32_e32 v8, 0
	v_mov_b32_e32 v9, v97
	v_mov_b32_e32 v10, v97
	v_mov_b32_e32 v11, v97
	v_mov_b32_e32 v4, 0
	v_mov_b32_e32 v5, v97
	v_mov_b32_e32 v6, v97
	v_mov_b32_e32 v7, v97
	v_mov_b32_e32 v0, 0
	v_mov_b32_e32 v1, v97
	v_mov_b32_e32 v2, v97
	v_mov_b32_e32 v3, v97
	s_add_u32 m0, s15, 0x0
	s_nop 0
	global_load_lds_dwordx4 v[188:189], off
	s_add_u32 m0, s15, 0x1000
	s_nop 0
	global_load_lds_dwordx4 v[190:191], off
	s_add_u32 m0, s15, 0x2000
	s_nop 0
	global_load_lds_dwordx4 v[192:193], off
	s_add_u32 m0, s15, 0x3000
	s_nop 0
	global_load_lds_dwordx4 v[194:195], off
	s_add_u32 m0, s15, 0x4000
	s_nop 0
	global_load_lds_dwordx4 v[196:197], off
	s_add_u32 m0, s15, 0x5000
	s_nop 0
	global_load_lds_dwordx4 v[198:199], off
	s_add_u32 m0, s15, 0x6000
	s_nop 0
	global_load_lds_dwordx4 v[200:201], off
	s_add_u32 m0, s15, 0x7000
	s_nop 0
	global_load_lds_dwordx4 v[202:203], off
	s_mov_b32 s4, 0x80
	s_add_u32 m0, s15, 0x8000
	v_lshl_add_u64 v[204:205], v[188:189], 0, s[4:5]
	global_load_lds_dwordx4 v[204:205], off
	s_add_u32 m0, s15, 0x9000
	v_lshl_add_u64 v[206:207], v[190:191], 0, s[4:5]
	global_load_lds_dwordx4 v[206:207], off
	s_add_u32 m0, s15, 0xa000
	v_lshl_add_u64 v[204:205], v[192:193], 0, s[4:5]
	global_load_lds_dwordx4 v[204:205], off
	s_add_u32 m0, s15, 0xb000
	v_lshl_add_u64 v[206:207], v[194:195], 0, s[4:5]
	global_load_lds_dwordx4 v[206:207], off
	s_add_u32 m0, s15, 0xc000
	v_lshl_add_u64 v[204:205], v[196:197], 0, s[4:5]
	global_load_lds_dwordx4 v[204:205], off
	s_add_u32 m0, s15, 0xd000
	v_lshl_add_u64 v[206:207], v[198:199], 0, s[4:5]
	global_load_lds_dwordx4 v[206:207], off
	s_add_u32 m0, s15, 0xe000
	v_lshl_add_u64 v[204:205], v[200:201], 0, s[4:5]
	global_load_lds_dwordx4 v[204:205], off
	s_add_u32 m0, s15, 0xf000
	v_lshl_add_u64 v[206:207], v[202:203], 0, s[4:5]
	global_load_lds_dwordx4 v[206:207], off
	s_mov_b32 s14, 0
	s_mov_b32 s13, -2
	s_waitcnt vmcnt(8)
	s_barrier
.Lglds2_26323:
	ds_read_b128 v[152:155], v111 offset:16384
	ds_read_b128 v[156:159], v111 offset:18432
	ds_read_b128 v[160:163], v109
	ds_read_b128 v[164:167], v109 offset:2048
	ds_read_b128 v[168:171], v111 offset:20480
	ds_read_b128 v[172:175], v112 offset:16384
	ds_read_b128 v[208:211], v109 offset:4096
	ds_read_b128 v[212:215], v110
	ds_read_b128 v[216:219], v115 offset:16384
	ds_read_b128 v[220:223], v115 offset:18432
	ds_read_b128 v[224:227], v113
	ds_read_b128 v[228:231], v113 offset:2048
	ds_read_b128 v[232:235], v115 offset:20480
	ds_read_b128 v[236:239], v116 offset:16384
	ds_read_b128 v[240:243], v113 offset:4096
	ds_read_b128 v[244:247], v114
	s_setprio 1
	s_waitcnt lgkmcnt(8)
	v_mfma_f32_16x16x32_bf16 v[92:95], v[152:155], v[160:163], v[92:95]
	v_mfma_f32_16x16x32_bf16 v[88:91], v[156:159], v[160:163], v[88:91]
	v_mfma_f32_16x16x32_bf16 v[84:87], v[168:171], v[160:163], v[84:87]
	v_mfma_f32_16x16x32_bf16 v[80:83], v[172:175], v[160:163], v[80:83]
	v_mfma_f32_16x16x32_bf16 v[76:79], v[152:155], v[164:167], v[76:79]
	v_mfma_f32_16x16x32_bf16 v[72:75], v[156:159], v[164:167], v[72:75]
	v_mfma_f32_16x16x32_bf16 v[60:63], v[168:171], v[164:167], v[60:63]
	v_mfma_f32_16x16x32_bf16 v[28:31], v[172:175], v[164:167], v[28:31]
	v_mfma_f32_16x16x32_bf16 v[64:67], v[152:155], v[208:211], v[64:67]
	v_mfma_f32_16x16x32_bf16 v[36:39], v[156:159], v[208:211], v[36:39]
	v_mfma_f32_16x16x32_bf16 v[32:35], v[168:171], v[208:211], v[32:35]
	v_mfma_f32_16x16x32_bf16 v[16:19], v[172:175], v[208:211], v[16:19]
	v_mfma_f32_16x16x32_bf16 v[12:15], v[152:155], v[212:215], v[12:15]
	v_mfma_f32_16x16x32_bf16 v[8:11], v[156:159], v[212:215], v[8:11]
	v_mfma_f32_16x16x32_bf16 v[4:7], v[168:171], v[212:215], v[4:7]
	v_mfma_f32_16x16x32_bf16 v[0:3], v[172:175], v[212:215], v[0:3]
	s_setprio 0
	s_waitcnt lgkmcnt(0)
	s_barrier
	s_add_i32 s4, s14, 0x80
	s_min_u32 s4, s4, 0x3c0
	s_lshl_b32 s4, s4, 1
	s_setprio 1
	v_mfma_f32_16x16x32_bf16 v[92:95], v[216:219], v[224:227], v[92:95]
	s_add_u32 m0, s15, 0x0
	v_lshl_add_u64 v[204:205], v[188:189], 0, s[4:5]
	global_load_lds_dwordx4 v[204:205], off
	v_mfma_f32_16x16x32_bf16 v[88:91], v[220:223], v[224:227], v[88:91]
	v_mfma_f32_16x16x32_bf16 v[84:87], v[232:235], v[224:227], v[84:87]
	s_add_u32 m0, s15, 0x1000
	v_lshl_add_u64 v[206:207], v[190:191], 0, s[4:5]
	global_load_lds_dwordx4 v[206:207], off
	v_mfma_f32_16x16x32_bf16 v[80:83], v[236:239], v[224:227], v[80:83]
	v_mfma_f32_16x16x32_bf16 v[76:79], v[216:219], v[228:231], v[76:79]
	s_add_u32 m0, s15, 0x2000
	v_lshl_add_u64 v[204:205], v[192:193], 0, s[4:5]
	global_load_lds_dwordx4 v[204:205], off
	v_mfma_f32_16x16x32_bf16 v[72:75], v[220:223], v[228:231], v[72:75]
	v_mfma_f32_16x16x32_bf16 v[60:63], v[232:235], v[228:231], v[60:63]
	s_add_u32 m0, s15, 0x3000
	v_lshl_add_u64 v[206:207], v[194:195], 0, s[4:5]
	global_load_lds_dwordx4 v[206:207], off
	v_mfma_f32_16x16x32_bf16 v[28:31], v[236:239], v[228:231], v[28:31]
	v_mfma_f32_16x16x32_bf16 v[64:67], v[216:219], v[240:243], v[64:67]
	s_add_u32 m0, s15, 0x4000
	v_lshl_add_u64 v[204:205], v[196:197], 0, s[4:5]
	global_load_lds_dwordx4 v[204:205], off
	v_mfma_f32_16x16x32_bf16 v[36:39], v[220:223], v[240:243], v[36:39]
	v_mfma_f32_16x16x32_bf16 v[32:35], v[232:235], v[240:243], v[32:35]
	s_add_u32 m0, s15, 0x5000
	v_lshl_add_u64 v[206:207], v[198:199], 0, s[4:5]
	global_load_lds_dwordx4 v[206:207], off
	v_mfma_f32_16x16x32_bf16 v[16:19], v[236:239], v[240:243], v[16:19]
	v_mfma_f32_16x16x32_bf16 v[12:15], v[216:219], v[244:247], v[12:15]
	s_add_u32 m0, s15, 0x6000
	v_lshl_add_u64 v[204:205], v[200:201], 0, s[4:5]
	global_load_lds_dwordx4 v[204:205], off
	v_mfma_f32_16x16x32_bf16 v[8:11], v[220:223], v[244:247], v[8:11]
	v_mfma_f32_16x16x32_bf16 v[4:7], v[232:235], v[244:247], v[4:7]
	s_add_u32 m0, s15, 0x7000
	v_lshl_add_u64 v[206:207], v[202:203], 0, s[4:5]
	global_load_lds_dwordx4 v[206:207], off
	v_mfma_f32_16x16x32_bf16 v[0:3], v[236:239], v[244:247], v[0:3]
	s_setprio 0
	s_waitcnt vmcnt(8)
	s_barrier
	ds_read_b128 v[152:155], v111 offset:49152
	ds_read_b128 v[156:159], v111 offset:51200
	ds_read_b128 v[160:163], v109 offset:32768
	ds_read_b128 v[164:167], v109 offset:34816
	ds_read_b128 v[168:171], v111 offset:53248
	ds_read_b128 v[172:175], v112 offset:49152
	ds_read_b128 v[208:211], v109 offset:36864
	ds_read_b128 v[212:215], v110 offset:32768
	ds_read_b128 v[216:219], v115 offset:49152
	ds_read_b128 v[220:223], v115 offset:51200
	ds_read_b128 v[224:227], v113 offset:32768
	ds_read_b128 v[228:231], v113 offset:34816
	ds_read_b128 v[232:235], v115 offset:53248
	ds_read_b128 v[236:239], v116 offset:49152
	ds_read_b128 v[240:243], v113 offset:36864
	ds_read_b128 v[244:247], v114 offset:32768
	s_setprio 1
	s_waitcnt lgkmcnt(8)
	v_mfma_f32_16x16x32_bf16 v[92:95], v[152:155], v[160:163], v[92:95]
	v_mfma_f32_16x16x32_bf16 v[88:91], v[156:159], v[160:163], v[88:91]
	v_mfma_f32_16x16x32_bf16 v[84:87], v[168:171], v[160:163], v[84:87]
	v_mfma_f32_16x16x32_bf16 v[80:83], v[172:175], v[160:163], v[80:83]
	v_mfma_f32_16x16x32_bf16 v[76:79], v[152:155], v[164:167], v[76:79]
	v_mfma_f32_16x16x32_bf16 v[72:75], v[156:159], v[164:167], v[72:75]
	v_mfma_f32_16x16x32_bf16 v[60:63], v[168:171], v[164:167], v[60:63]
	v_mfma_f32_16x16x32_bf16 v[28:31], v[172:175], v[164:167], v[28:31]
	v_mfma_f32_16x16x32_bf16 v[64:67], v[152:155], v[208:211], v[64:67]
	v_mfma_f32_16x16x32_bf16 v[36:39], v[156:159], v[208:211], v[36:39]
	v_mfma_f32_16x16x32_bf16 v[32:35], v[168:171], v[208:211], v[32:35]
	v_mfma_f32_16x16x32_bf16 v[16:19], v[172:175], v[208:211], v[16:19]
	v_mfma_f32_16x16x32_bf16 v[12:15], v[152:155], v[212:215], v[12:15]
	v_mfma_f32_16x16x32_bf16 v[8:11], v[156:159], v[212:215], v[8:11]
	v_mfma_f32_16x16x32_bf16 v[4:7], v[168:171], v[212:215], v[4:7]
	v_mfma_f32_16x16x32_bf16 v[0:3], v[172:175], v[212:215], v[0:3]
	s_setprio 0
	s_waitcnt lgkmcnt(0)
	s_barrier
	s_add_i32 s4, s14, 0xc0
	s_min_u32 s4, s4, 0x3c0
	s_lshl_b32 s4, s4, 1
	s_setprio 1
	v_mfma_f32_16x16x32_bf16 v[92:95], v[216:219], v[224:227], v[92:95]
	s_add_u32 m0, s15, 0x8000
	v_lshl_add_u64 v[204:205], v[188:189], 0, s[4:5]
	global_load_lds_dwordx4 v[204:205], off
	v_mfma_f32_16x16x32_bf16 v[88:91], v[220:223], v[224:227], v[88:91]
	v_mfma_f32_16x16x32_bf16 v[84:87], v[232:235], v[224:227], v[84:87]
	s_add_u32 m0, s15, 0x9000
	v_lshl_add_u64 v[206:207], v[190:191], 0, s[4:5]
	global_load_lds_dwordx4 v[206:207], off
	v_mfma_f32_16x16x32_bf16 v[80:83], v[236:239], v[224:227], v[80:83]
	v_mfma_f32_16x16x32_bf16 v[76:79], v[216:219], v[228:231], v[76:79]
	s_add_u32 m0, s15, 0xa000
	v_lshl_add_u64 v[204:205], v[192:193], 0, s[4:5]
	global_load_lds_dwordx4 v[204:205], off
	v_mfma_f32_16x16x32_bf16 v[72:75], v[220:223], v[228:231], v[72:75]
	v_mfma_f32_16x16x32_bf16 v[60:63], v[232:235], v[228:231], v[60:63]
	s_add_u32 m0, s15, 0xb000
	v_lshl_add_u64 v[206:207], v[194:195], 0, s[4:5]
	global_load_lds_dwordx4 v[206:207], off
	v_mfma_f32_16x16x32_bf16 v[28:31], v[236:239], v[228:231], v[28:31]
	v_mfma_f32_16x16x32_bf16 v[64:67], v[216:219], v[240:243], v[64:67]
	s_add_u32 m0, s15, 0xc000
	v_lshl_add_u64 v[204:205], v[196:197], 0, s[4:5]
	global_load_lds_dwordx4 v[204:205], off
	v_mfma_f32_16x16x32_bf16 v[36:39], v[220:223], v[240:243], v[36:39]
	v_mfma_f32_16x16x32_bf16 v[32:35], v[232:235], v[240:243], v[32:35]
	s_add_u32 m0, s15, 0xd000
	v_lshl_add_u64 v[206:207], v[198:199], 0, s[4:5]
	global_load_lds_dwordx4 v[206:207], off
	v_mfma_f32_16x16x32_bf16 v[16:19], v[236:239], v[240:243], v[16:19]
	v_mfma_f32_16x16x32_bf16 v[12:15], v[216:219], v[244:247], v[12:15]
	s_add_u32 m0, s15, 0xe000
	v_lshl_add_u64 v[204:205], v[200:201], 0, s[4:5]
	global_load_lds_dwordx4 v[204:205], off
	v_mfma_f32_16x16x32_bf16 v[8:11], v[220:223], v[244:247], v[8:11]
	v_mfma_f32_16x16x32_bf16 v[4:7], v[232:235], v[244:247], v[4:7]
	s_add_u32 m0, s15, 0xf000
	v_lshl_add_u64 v[206:207], v[202:203], 0, s[4:5]
	global_load_lds_dwordx4 v[206:207], off
	v_mfma_f32_16x16x32_bf16 v[0:3], v[236:239], v[244:247], v[0:3]
	s_setprio 0
	s_waitcnt vmcnt(8)
	s_barrier
	s_add_i32 s14, s14, 0x80
	s_add_i32 s13, s13, 2
	s_cmp_lt_u32 s13, 14
	s_cbranch_scc1 .Lglds2_26323
	s_waitcnt vmcnt(0)
	s_waitcnt vmcnt(0)
	v_or_b32_e32 v170, s12, v118
	v_add_lshl_u32 v96, v117, s11, 10
	v_readlane_b32 s12, v254, 24
	v_readlane_b32 s16, v254, 28
	v_readlane_b32 s17, v254, 29
	v_readlane_b32 s13, v254, 25
	v_readlane_b32 s14, v254, 26
	v_readlane_b32 s15, v254, 27
	v_readlane_b32 s18, v254, 30
	v_readlane_b32 s19, v254, 31
	v_readlane_b32 s20, v254, 32
	v_readlane_b32 s21, v254, 33
	v_readlane_b32 s22, v254, 34
	v_readlane_b32 s23, v254, 35
	v_readlane_b32 s24, v254, 36
	v_readlane_b32 s25, v254, 37
	v_readlane_b32 s26, v254, 38
	v_readlane_b32 s27, v254, 39
	v_lshlrev_b32_e32 v168, 2, v170
	v_mov_b32_e32 v169, v97
	v_lshlrev_b64 v[174:175], 2, v[96:97]
	v_lshl_add_u64 v[152:153], s[16:17], 0, v[174:175]
	v_lshl_add_u64 v[160:161], s[82:83], 0, v[174:175]
	v_lshl_add_u64 v[152:153], v[152:153], 0, v[168:169]
	v_lshl_add_u64 v[160:161], v[160:161], 0, v[168:169]
	global_load_dwordx4 v[120:123], v[152:153], off
	global_load_dwordx4 v[124:127], v[152:153], off offset:64
	global_load_dwordx4 v[128:131], v[152:153], off offset:128
	global_load_dwordx4 v[132:135], v[152:153], off offset:192
	v_or_b32_e32 v172, 0x4000, v96
	v_mov_b32_e32 v173, v97
	v_lshlrev_b64 v[174:175], 2, v[172:173]
	v_lshl_add_u64 v[154:155], s[16:17], 0, v[174:175]
	v_lshl_add_u64 v[162:163], s[82:83], 0, v[174:175]
	v_lshl_add_u64 v[154:155], v[154:155], 0, v[168:169]
	v_lshl_add_u64 v[162:163], v[162:163], 0, v[168:169]
	global_load_dwordx4 v[136:139], v[154:155], off
	global_load_dwordx4 v[140:143], v[154:155], off offset:64
	global_load_dwordx4 v[144:147], v[154:155], off offset:128
	global_load_dwordx4 v[148:151], v[154:155], off offset:192
	v_or_b32_e32 v172, 0x8000, v96
	v_mov_b32_e32 v173, v97
	v_lshlrev_b64 v[174:175], 2, v[172:173]
	v_lshl_add_u64 v[156:157], s[16:17], 0, v[174:175]
	v_lshl_add_u64 v[164:165], s[82:83], 0, v[174:175]
	v_lshl_add_u64 v[156:157], v[156:157], 0, v[168:169]
	v_lshl_add_u64 v[164:165], v[164:165], 0, v[168:169]
	global_load_dwordx4 v[20:23], v[156:157], off
	global_load_dwordx4 v[24:27], v[156:157], off offset:64
	global_load_dwordx4 v[40:43], v[156:157], off offset:128
	global_load_dwordx4 v[44:47], v[156:157], off offset:192
	v_or_b32_e32 v172, 0xc000, v96
	v_mov_b32_e32 v173, v97
	v_lshlrev_b64 v[174:175], 2, v[172:173]
	v_lshl_add_u64 v[158:159], s[16:17], 0, v[174:175]
	v_lshl_add_u64 v[166:167], s[82:83], 0, v[174:175]
	v_lshl_add_u64 v[158:159], v[158:159], 0, v[168:169]
	v_lshl_add_u64 v[166:167], v[166:167], 0, v[168:169]
	global_load_dwordx4 v[48:51], v[158:159], off
	global_load_dwordx4 v[52:55], v[158:159], off offset:64
	global_load_dwordx4 v[56:59], v[158:159], off offset:128
	global_load_dwordx4 v[68:71], v[158:159], off offset:192
	s_waitcnt vmcnt(15)
	v_pk_fma_f32 v[120:121], v[120:121], s[6:7], v[92:93] op_sel_hi:[1,0,1]
	v_pk_fma_f32 v[122:123], v[122:123], s[6:7], v[94:95] op_sel_hi:[1,0,1]
	s_waitcnt vmcnt(14)
	v_pk_fma_f32 v[124:125], v[124:125], s[6:7], v[88:89] op_sel_hi:[1,0,1]
	v_pk_fma_f32 v[126:127], v[126:127], s[6:7], v[90:91] op_sel_hi:[1,0,1]
	s_waitcnt vmcnt(13)
	v_pk_fma_f32 v[128:129], v[128:129], s[6:7], v[84:85] op_sel_hi:[1,0,1]
	v_pk_fma_f32 v[130:131], v[130:131], s[6:7], v[86:87] op_sel_hi:[1,0,1]
	s_waitcnt vmcnt(12)
	v_pk_fma_f32 v[132:133], v[132:133], s[6:7], v[80:81] op_sel_hi:[1,0,1]
	v_pk_fma_f32 v[134:135], v[134:135], s[6:7], v[82:83] op_sel_hi:[1,0,1]
	s_waitcnt vmcnt(11)
	v_pk_fma_f32 v[136:137], v[136:137], s[6:7], v[76:77] op_sel_hi:[1,0,1]
	v_pk_fma_f32 v[138:139], v[138:139], s[6:7], v[78:79] op_sel_hi:[1,0,1]
	s_waitcnt vmcnt(10)
	v_pk_fma_f32 v[140:141], v[140:141], s[6:7], v[72:73] op_sel_hi:[1,0,1]
	v_pk_fma_f32 v[142:143], v[142:143], s[6:7], v[74:75] op_sel_hi:[1,0,1]
	s_waitcnt vmcnt(9)
	v_pk_fma_f32 v[144:145], v[144:145], s[6:7], v[60:61] op_sel_hi:[1,0,1]
	v_pk_fma_f32 v[146:147], v[146:147], s[6:7], v[62:63] op_sel_hi:[1,0,1]
	s_waitcnt vmcnt(8)
	v_pk_fma_f32 v[148:149], v[148:149], s[6:7], v[28:29] op_sel_hi:[1,0,1]
	v_pk_fma_f32 v[150:151], v[150:151], s[6:7], v[30:31] op_sel_hi:[1,0,1]
	s_waitcnt vmcnt(7)
	v_pk_fma_f32 v[20:21], v[20:21], s[6:7], v[64:65] op_sel_hi:[1,0,1]
	v_pk_fma_f32 v[22:23], v[22:23], s[6:7], v[66:67] op_sel_hi:[1,0,1]
	s_waitcnt vmcnt(6)
	v_pk_fma_f32 v[24:25], v[24:25], s[6:7], v[36:37] op_sel_hi:[1,0,1]
	v_pk_fma_f32 v[26:27], v[26:27], s[6:7], v[38:39] op_sel_hi:[1,0,1]
	s_waitcnt vmcnt(5)
	v_pk_fma_f32 v[40:41], v[40:41], s[6:7], v[32:33] op_sel_hi:[1,0,1]
	v_pk_fma_f32 v[42:43], v[42:43], s[6:7], v[34:35] op_sel_hi:[1,0,1]
	s_waitcnt vmcnt(4)
	v_pk_fma_f32 v[44:45], v[44:45], s[6:7], v[16:17] op_sel_hi:[1,0,1]
	v_pk_fma_f32 v[46:47], v[46:47], s[6:7], v[18:19] op_sel_hi:[1,0,1]
	s_waitcnt vmcnt(3)
	v_pk_fma_f32 v[48:49], v[48:49], s[6:7], v[12:13] op_sel_hi:[1,0,1]
	v_pk_fma_f32 v[50:51], v[50:51], s[6:7], v[14:15] op_sel_hi:[1,0,1]
	s_waitcnt vmcnt(2)
	v_pk_fma_f32 v[52:53], v[52:53], s[6:7], v[8:9] op_sel_hi:[1,0,1]
	v_pk_fma_f32 v[54:55], v[54:55], s[6:7], v[10:11] op_sel_hi:[1,0,1]
	s_waitcnt vmcnt(1)
	v_pk_fma_f32 v[56:57], v[56:57], s[6:7], v[4:5] op_sel_hi:[1,0,1]
	v_pk_fma_f32 v[58:59], v[58:59], s[6:7], v[6:7] op_sel_hi:[1,0,1]
	s_waitcnt vmcnt(0)
	v_pk_fma_f32 v[68:69], v[68:69], s[6:7], v[0:1] op_sel_hi:[1,0,1]
	v_pk_fma_f32 v[70:71], v[70:71], s[6:7], v[2:3] op_sel_hi:[1,0,1]
	global_store_dwordx4 v[160:161], v[120:123], off
	global_store_dwordx4 v[160:161], v[124:127], off offset:64
	global_store_dwordx4 v[160:161], v[128:131], off offset:128
	global_store_dwordx4 v[160:161], v[132:135], off offset:192
	global_store_dwordx4 v[162:163], v[136:139], off
	global_store_dwordx4 v[162:163], v[140:143], off offset:64
	global_store_dwordx4 v[162:163], v[144:147], off offset:128
	global_store_dwordx4 v[162:163], v[148:151], off offset:192
	global_store_dwordx4 v[164:165], v[20:23], off
	global_store_dwordx4 v[164:165], v[24:27], off offset:64
	global_store_dwordx4 v[164:165], v[40:43], off offset:128
	global_store_dwordx4 v[164:165], v[44:47], off offset:192
	global_store_dwordx4 v[166:167], v[48:51], off
	global_store_dwordx4 v[166:167], v[52:55], off offset:64
	global_store_dwordx4 v[166:167], v[56:59], off offset:128
	global_store_dwordx4 v[166:167], v[68:71], off offset:192
	s_add_i32 s7, s7, s3
	s_cmpk_lt_u32 s7, 0x100
	s_cbranch_scc1 .LBB0_798

.LBB0_889:
	s_lshr_b32 s6, s8, 1
	s_and_b32 s6, s6, 0xf8
	s_or_b32 s6, s6, s2
	s_lshl_b32 s12, s6, 7
	s_lshl_b32 s6, s8, 7
	v_or_b32_e32 v0, s12, v107
	s_and_b32 s13, s6, 0x780
	v_lshlrev_b32_e32 v96, 10, v0
	v_lshl_add_u64 v[102:103], v[98:99], 0, v[96:97]
	v_or_b32_e32 v0, s13, v107
	v_lshlrev_b32_e32 v96, 10, v0
	v_lshl_add_u64 v[104:105], v[100:101], 0, v[96:97]
	v_and_b32_e32 v181, 7, v106
	v_bfe_u32 v180, v106, 3, 3
	v_xor_b32_e32 v180, v181, v180
	v_sub_u32_e32 v180, v180, v181
	v_lshlrev_b32_e32 v180, 4, v180
	v_ashrrev_i32_e32 v181, 31, v180
	v_lshrrev_b32_e32 v186, 6, v106
	v_mov_b32_e32 v187, 0x110
	v_lshl_add_u32 v186, v186, 10, v187
	v_lshl_add_u64 v[188:189], v[102:103], 0, v[180:181]
	v_lshl_add_u64 v[196:197], v[104:105], 0, v[180:181]
	v_readfirstlane_b32 s16, v186
	v_add_co_u32_e32 v190, vcc, s9, v188
	v_addc_co_u32_e32 v191, vcc, 0, v189, vcc
	v_add_co_u32_e32 v192, vcc, s10, v188
	v_addc_co_u32_e32 v193, vcc, 0, v189, vcc
	v_add_co_u32_e32 v194, vcc, s11, v188
	v_addc_co_u32_e32 v195, vcc, 0, v189, vcc
	v_add_co_u32_e32 v198, vcc, s9, v196
	v_addc_co_u32_e32 v199, vcc, 0, v197, vcc
	v_add_co_u32_e32 v200, vcc, s10, v196
	v_addc_co_u32_e32 v201, vcc, 0, v197, vcc
	v_add_co_u32_e32 v202, vcc, s11, v196
	v_addc_co_u32_e32 v203, vcc, 0, v197, vcc
	v_mov_b32_e32 v28, 0
	v_mov_b32_e32 v29, v97
	v_mov_b32_e32 v30, v97
	v_mov_b32_e32 v31, v97
	v_mov_b32_e32 v36, 0
	v_mov_b32_e32 v37, v97
	v_mov_b32_e32 v38, v97
	v_mov_b32_e32 v39, v97
	v_mov_b32_e32 v40, 0
	v_mov_b32_e32 v41, v97
	v_mov_b32_e32 v42, v97
	v_mov_b32_e32 v43, v97
	v_mov_b32_e32 v60, 0
	v_mov_b32_e32 v61, v97
	v_mov_b32_e32 v62, v97
	v_mov_b32_e32 v63, v97
	v_mov_b32_e32 v80, 0
	v_mov_b32_e32 v81, v97
	v_mov_b32_e32 v82, v97
	v_mov_b32_e32 v83, v97
	v_mov_b32_e32 v84, 0
	v_mov_b32_e32 v85, v97
	v_mov_b32_e32 v86, v97
	v_mov_b32_e32 v87, v97
	v_mov_b32_e32 v88, 0
	v_mov_b32_e32 v89, v97
	v_mov_b32_e32 v90, v97
	v_mov_b32_e32 v91, v97
	v_mov_b32_e32 v92, 0
	v_mov_b32_e32 v93, v97
	v_mov_b32_e32 v94, v97
	v_mov_b32_e32 v95, v97
	v_mov_b32_e32 v32, 0
	v_mov_b32_e32 v33, v97
	v_mov_b32_e32 v34, v97
	v_mov_b32_e32 v35, v97
	v_mov_b32_e32 v24, 0
	v_mov_b32_e32 v25, v97
	v_mov_b32_e32 v26, v97
	v_mov_b32_e32 v27, v97
	v_mov_b32_e32 v20, 0
	v_mov_b32_e32 v21, v97
	v_mov_b32_e32 v22, v97
	v_mov_b32_e32 v23, v97
	v_mov_b32_e32 v16, 0
	v_mov_b32_e32 v17, v97
	v_mov_b32_e32 v18, v97
	v_mov_b32_e32 v19, v97
	v_mov_b32_e32 v12, 0
	v_mov_b32_e32 v13, v97
	v_mov_b32_e32 v14, v97
	v_mov_b32_e32 v15, v97
	v_mov_b32_e32 v8, 0
	v_mov_b32_e32 v9, v97
	v_mov_b32_e32 v10, v97
	v_mov_b32_e32 v11, v97
	v_mov_b32_e32 v4, 0
	v_mov_b32_e32 v5, v97
	v_mov_b32_e32 v6, v97
	v_mov_b32_e32 v7, v97
	v_mov_b32_e32 v0, 0
	v_mov_b32_e32 v1, v97
	v_mov_b32_e32 v2, v97
	v_mov_b32_e32 v3, v97
	s_add_u32 m0, s16, 0x0
	s_nop 0
	global_load_lds_dwordx4 v[188:189], off
	s_add_u32 m0, s16, 0x1000
	s_nop 0
	global_load_lds_dwordx4 v[190:191], off
	s_add_u32 m0, s16, 0x2000
	s_nop 0
	global_load_lds_dwordx4 v[192:193], off
	s_add_u32 m0, s16, 0x3000
	s_nop 0
	global_load_lds_dwordx4 v[194:195], off
	s_add_u32 m0, s16, 0x4000
	s_nop 0
	global_load_lds_dwordx4 v[196:197], off
	s_add_u32 m0, s16, 0x5000
	s_nop 0
	global_load_lds_dwordx4 v[198:199], off
	s_add_u32 m0, s16, 0x6000
	s_nop 0
	global_load_lds_dwordx4 v[200:201], off
	s_add_u32 m0, s16, 0x7000
	s_nop 0
	global_load_lds_dwordx4 v[202:203], off
	s_mov_b32 s6, 0x80
	s_add_u32 m0, s16, 0x8000
	v_lshl_add_u64 v[204:205], v[188:189], 0, s[6:7]
	global_load_lds_dwordx4 v[204:205], off
	s_add_u32 m0, s16, 0x9000
	v_lshl_add_u64 v[206:207], v[190:191], 0, s[6:7]
	global_load_lds_dwordx4 v[206:207], off
	s_add_u32 m0, s16, 0xa000
	v_lshl_add_u64 v[204:205], v[192:193], 0, s[6:7]
	global_load_lds_dwordx4 v[204:205], off
	s_add_u32 m0, s16, 0xb000
	v_lshl_add_u64 v[206:207], v[194:195], 0, s[6:7]
	global_load_lds_dwordx4 v[206:207], off
	s_add_u32 m0, s16, 0xc000
	v_lshl_add_u64 v[204:205], v[196:197], 0, s[6:7]
	global_load_lds_dwordx4 v[204:205], off
	s_add_u32 m0, s16, 0xd000
	v_lshl_add_u64 v[206:207], v[198:199], 0, s[6:7]
	global_load_lds_dwordx4 v[206:207], off
	s_add_u32 m0, s16, 0xe000
	v_lshl_add_u64 v[204:205], v[200:201], 0, s[6:7]
	global_load_lds_dwordx4 v[204:205], off
	s_add_u32 m0, s16, 0xf000
	v_lshl_add_u64 v[206:207], v[202:203], 0, s[6:7]
	global_load_lds_dwordx4 v[206:207], off
	s_mov_b32 s15, 0
	s_mov_b32 s14, -2
	s_waitcnt vmcnt(8)
	s_barrier
.Lglds2_28042:
	ds_read_b128 v[152:155], v111 offset:16384
	ds_read_b128 v[156:159], v111 offset:18432
	ds_read_b128 v[160:163], v109
	ds_read_b128 v[164:167], v109 offset:2048
	ds_read_b128 v[168:171], v111 offset:20480
	ds_read_b128 v[172:175], v112 offset:16384
	ds_read_b128 v[208:211], v109 offset:4096
	ds_read_b128 v[212:215], v110
	ds_read_b128 v[216:219], v115 offset:16384
	ds_read_b128 v[220:223], v115 offset:18432
	ds_read_b128 v[224:227], v113
	ds_read_b128 v[228:231], v113 offset:2048
	ds_read_b128 v[232:235], v115 offset:20480
	ds_read_b128 v[236:239], v116 offset:16384
	ds_read_b128 v[240:243], v113 offset:4096
	ds_read_b128 v[244:247], v114
	s_setprio 1
	s_waitcnt lgkmcnt(8)
	v_mfma_i32_16x16x64_i8 v[92:95], v[152:155], v[160:163], v[92:95]
	v_mfma_i32_16x16x64_i8 v[88:91], v[156:159], v[160:163], v[88:91]
	v_mfma_i32_16x16x64_i8 v[84:87], v[168:171], v[160:163], v[84:87]
	v_mfma_i32_16x16x64_i8 v[80:83], v[172:175], v[160:163], v[80:83]
	v_mfma_i32_16x16x64_i8 v[60:63], v[152:155], v[164:167], v[60:63]
	v_mfma_i32_16x16x64_i8 v[40:43], v[156:159], v[164:167], v[40:43]
	v_mfma_i32_16x16x64_i8 v[36:39], v[168:171], v[164:167], v[36:39]
	v_mfma_i32_16x16x64_i8 v[28:31], v[172:175], v[164:167], v[28:31]
	v_mfma_i32_16x16x64_i8 v[32:35], v[152:155], v[208:211], v[32:35]
	v_mfma_i32_16x16x64_i8 v[24:27], v[156:159], v[208:211], v[24:27]
	v_mfma_i32_16x16x64_i8 v[20:23], v[168:171], v[208:211], v[20:23]
	v_mfma_i32_16x16x64_i8 v[16:19], v[172:175], v[208:211], v[16:19]
	v_mfma_i32_16x16x64_i8 v[12:15], v[152:155], v[212:215], v[12:15]
	v_mfma_i32_16x16x64_i8 v[8:11], v[156:159], v[212:215], v[8:11]
	v_mfma_i32_16x16x64_i8 v[4:7], v[168:171], v[212:215], v[4:7]
	v_mfma_i32_16x16x64_i8 v[0:3], v[172:175], v[212:215], v[0:3]
	s_setprio 0
	s_waitcnt lgkmcnt(0)
	s_barrier
	s_add_i32 s6, s15, 0x80
	s_min_u32 s6, s6, 0x1c0
	s_lshl_b32 s6, s6, 1
	s_setprio 1
	v_mfma_i32_16x16x64_i8 v[92:95], v[216:219], v[224:227], v[92:95]
	s_add_u32 m0, s16, 0x0
	v_lshl_add_u64 v[204:205], v[188:189], 0, s[6:7]
	global_load_lds_dwordx4 v[204:205], off
	v_mfma_i32_16x16x64_i8 v[88:91], v[220:223], v[224:227], v[88:91]
	v_mfma_i32_16x16x64_i8 v[84:87], v[232:235], v[224:227], v[84:87]
	s_add_u32 m0, s16, 0x1000
	v_lshl_add_u64 v[206:207], v[190:191], 0, s[6:7]
	global_load_lds_dwordx4 v[206:207], off
	v_mfma_i32_16x16x64_i8 v[80:83], v[236:239], v[224:227], v[80:83]
	v_mfma_i32_16x16x64_i8 v[60:63], v[216:219], v[228:231], v[60:63]
	s_add_u32 m0, s16, 0x2000
	v_lshl_add_u64 v[204:205], v[192:193], 0, s[6:7]
	global_load_lds_dwordx4 v[204:205], off
	v_mfma_i32_16x16x64_i8 v[40:43], v[220:223], v[228:231], v[40:43]
	v_mfma_i32_16x16x64_i8 v[36:39], v[232:235], v[228:231], v[36:39]
	s_add_u32 m0, s16, 0x3000
	v_lshl_add_u64 v[206:207], v[194:195], 0, s[6:7]
	global_load_lds_dwordx4 v[206:207], off
	v_mfma_i32_16x16x64_i8 v[28:31], v[236:239], v[228:231], v[28:31]
	v_mfma_i32_16x16x64_i8 v[32:35], v[216:219], v[240:243], v[32:35]
	s_add_u32 m0, s16, 0x4000
	v_lshl_add_u64 v[204:205], v[196:197], 0, s[6:7]
	global_load_lds_dwordx4 v[204:205], off
	v_mfma_i32_16x16x64_i8 v[24:27], v[220:223], v[240:243], v[24:27]
	v_mfma_i32_16x16x64_i8 v[20:23], v[232:235], v[240:243], v[20:23]
	s_add_u32 m0, s16, 0x5000
	v_lshl_add_u64 v[206:207], v[198:199], 0, s[6:7]
	global_load_lds_dwordx4 v[206:207], off
	v_mfma_i32_16x16x64_i8 v[16:19], v[236:239], v[240:243], v[16:19]
	v_mfma_i32_16x16x64_i8 v[12:15], v[216:219], v[244:247], v[12:15]
	s_add_u32 m0, s16, 0x6000
	v_lshl_add_u64 v[204:205], v[200:201], 0, s[6:7]
	global_load_lds_dwordx4 v[204:205], off
	v_mfma_i32_16x16x64_i8 v[8:11], v[220:223], v[244:247], v[8:11]
	v_mfma_i32_16x16x64_i8 v[4:7], v[232:235], v[244:247], v[4:7]
	s_add_u32 m0, s16, 0x7000
	v_lshl_add_u64 v[206:207], v[202:203], 0, s[6:7]
	global_load_lds_dwordx4 v[206:207], off
	v_mfma_i32_16x16x64_i8 v[0:3], v[236:239], v[244:247], v[0:3]
	s_setprio 0
	s_waitcnt vmcnt(8)
	s_barrier
	ds_read_b128 v[152:155], v111 offset:49152
	ds_read_b128 v[156:159], v111 offset:51200
	ds_read_b128 v[160:163], v109 offset:32768
	ds_read_b128 v[164:167], v109 offset:34816
	ds_read_b128 v[168:171], v111 offset:53248
	ds_read_b128 v[172:175], v112 offset:49152
	ds_read_b128 v[208:211], v109 offset:36864
	ds_read_b128 v[212:215], v110 offset:32768
	ds_read_b128 v[216:219], v115 offset:49152
	ds_read_b128 v[220:223], v115 offset:51200
	ds_read_b128 v[224:227], v113 offset:32768
	ds_read_b128 v[228:231], v113 offset:34816
	ds_read_b128 v[232:235], v115 offset:53248
	ds_read_b128 v[236:239], v116 offset:49152
	ds_read_b128 v[240:243], v113 offset:36864
	ds_read_b128 v[244:247], v114 offset:32768
	s_setprio 1
	s_waitcnt lgkmcnt(8)
	v_mfma_i32_16x16x64_i8 v[92:95], v[152:155], v[160:163], v[92:95]
	v_mfma_i32_16x16x64_i8 v[88:91], v[156:159], v[160:163], v[88:91]
	v_mfma_i32_16x16x64_i8 v[84:87], v[168:171], v[160:163], v[84:87]
	v_mfma_i32_16x16x64_i8 v[80:83], v[172:175], v[160:163], v[80:83]
	v_mfma_i32_16x16x64_i8 v[60:63], v[152:155], v[164:167], v[60:63]
	v_mfma_i32_16x16x64_i8 v[40:43], v[156:159], v[164:167], v[40:43]
	v_mfma_i32_16x16x64_i8 v[36:39], v[168:171], v[164:167], v[36:39]
	v_mfma_i32_16x16x64_i8 v[28:31], v[172:175], v[164:167], v[28:31]
	v_mfma_i32_16x16x64_i8 v[32:35], v[152:155], v[208:211], v[32:35]
	v_mfma_i32_16x16x64_i8 v[24:27], v[156:159], v[208:211], v[24:27]
	v_mfma_i32_16x16x64_i8 v[20:23], v[168:171], v[208:211], v[20:23]
	v_mfma_i32_16x16x64_i8 v[16:19], v[172:175], v[208:211], v[16:19]
	v_mfma_i32_16x16x64_i8 v[12:15], v[152:155], v[212:215], v[12:15]
	v_mfma_i32_16x16x64_i8 v[8:11], v[156:159], v[212:215], v[8:11]
	v_mfma_i32_16x16x64_i8 v[4:7], v[168:171], v[212:215], v[4:7]
	v_mfma_i32_16x16x64_i8 v[0:3], v[172:175], v[212:215], v[0:3]
	s_setprio 0
	s_waitcnt lgkmcnt(0)
	s_barrier
	s_add_i32 s6, s15, 0xc0
	s_min_u32 s6, s6, 0x1c0
	s_lshl_b32 s6, s6, 1
	s_setprio 1
	v_mfma_i32_16x16x64_i8 v[92:95], v[216:219], v[224:227], v[92:95]
	s_add_u32 m0, s16, 0x8000
	v_lshl_add_u64 v[204:205], v[188:189], 0, s[6:7]
	global_load_lds_dwordx4 v[204:205], off
	v_mfma_i32_16x16x64_i8 v[88:91], v[220:223], v[224:227], v[88:91]
	v_mfma_i32_16x16x64_i8 v[84:87], v[232:235], v[224:227], v[84:87]
	s_add_u32 m0, s16, 0x9000
	v_lshl_add_u64 v[206:207], v[190:191], 0, s[6:7]
	global_load_lds_dwordx4 v[206:207], off
	v_mfma_i32_16x16x64_i8 v[80:83], v[236:239], v[224:227], v[80:83]
	v_mfma_i32_16x16x64_i8 v[60:63], v[216:219], v[228:231], v[60:63]
	s_add_u32 m0, s16, 0xa000
	v_lshl_add_u64 v[204:205], v[192:193], 0, s[6:7]
	global_load_lds_dwordx4 v[204:205], off
	v_mfma_i32_16x16x64_i8 v[40:43], v[220:223], v[228:231], v[40:43]
	v_mfma_i32_16x16x64_i8 v[36:39], v[232:235], v[228:231], v[36:39]
	s_add_u32 m0, s16, 0xb000
	v_lshl_add_u64 v[206:207], v[194:195], 0, s[6:7]
	global_load_lds_dwordx4 v[206:207], off
	v_mfma_i32_16x16x64_i8 v[28:31], v[236:239], v[228:231], v[28:31]
	v_mfma_i32_16x16x64_i8 v[32:35], v[216:219], v[240:243], v[32:35]
	s_add_u32 m0, s16, 0xc000
	v_lshl_add_u64 v[204:205], v[196:197], 0, s[6:7]
	global_load_lds_dwordx4 v[204:205], off
	v_mfma_i32_16x16x64_i8 v[24:27], v[220:223], v[240:243], v[24:27]
	v_mfma_i32_16x16x64_i8 v[20:23], v[232:235], v[240:243], v[20:23]
	s_add_u32 m0, s16, 0xd000
	v_lshl_add_u64 v[206:207], v[198:199], 0, s[6:7]
	global_load_lds_dwordx4 v[206:207], off
	v_mfma_i32_16x16x64_i8 v[16:19], v[236:239], v[240:243], v[16:19]
	v_mfma_i32_16x16x64_i8 v[12:15], v[216:219], v[244:247], v[12:15]
	s_add_u32 m0, s16, 0xe000
	v_lshl_add_u64 v[204:205], v[200:201], 0, s[6:7]
	global_load_lds_dwordx4 v[204:205], off
	v_mfma_i32_16x16x64_i8 v[8:11], v[220:223], v[244:247], v[8:11]
	v_mfma_i32_16x16x64_i8 v[4:7], v[232:235], v[244:247], v[4:7]
	s_add_u32 m0, s16, 0xf000
	v_lshl_add_u64 v[206:207], v[202:203], 0, s[6:7]
	global_load_lds_dwordx4 v[206:207], off
	v_mfma_i32_16x16x64_i8 v[0:3], v[236:239], v[244:247], v[0:3]
	s_setprio 0
	s_waitcnt vmcnt(8)
	s_barrier
	s_add_i32 s15, s15, 0x80
	s_add_i32 s14, s14, 2
	s_cmp_lt_u32 s14, 6
	s_cbranch_scc1 .Lglds2_28042
	s_waitcnt vmcnt(0)
	v_cvt_f32_i32_e32 v92, v92
	v_cvt_f32_i32_e32 v93, v93
	v_cvt_f32_i32_e32 v94, v94
	v_cvt_f32_i32_e32 v95, v95
	v_cvt_f32_i32_e32 v88, v88
	v_cvt_f32_i32_e32 v89, v89
	v_cvt_f32_i32_e32 v90, v90
	v_cvt_f32_i32_e32 v91, v91
	v_cvt_f32_i32_e32 v84, v84
	v_cvt_f32_i32_e32 v85, v85
	v_cvt_f32_i32_e32 v86, v86
	v_cvt_f32_i32_e32 v87, v87
	v_cvt_f32_i32_e32 v80, v80
	v_cvt_f32_i32_e32 v81, v81
	v_cvt_f32_i32_e32 v82, v82
	v_cvt_f32_i32_e32 v83, v83
	v_cvt_f32_i32_e32 v60, v60
	v_cvt_f32_i32_e32 v61, v61
	v_cvt_f32_i32_e32 v62, v62
	v_cvt_f32_i32_e32 v63, v63
	v_cvt_f32_i32_e32 v40, v40
	v_cvt_f32_i32_e32 v41, v41
	v_cvt_f32_i32_e32 v42, v42
	v_cvt_f32_i32_e32 v43, v43
	v_cvt_f32_i32_e32 v36, v36
	v_cvt_f32_i32_e32 v37, v37
	v_cvt_f32_i32_e32 v38, v38
	v_cvt_f32_i32_e32 v39, v39
	v_cvt_f32_i32_e32 v28, v28
	v_cvt_f32_i32_e32 v29, v29
	v_cvt_f32_i32_e32 v30, v30
	v_cvt_f32_i32_e32 v31, v31
	v_cvt_f32_i32_e32 v32, v32
	v_cvt_f32_i32_e32 v33, v33
	v_cvt_f32_i32_e32 v34, v34
	v_cvt_f32_i32_e32 v35, v35
	v_cvt_f32_i32_e32 v24, v24
	v_cvt_f32_i32_e32 v25, v25
	v_cvt_f32_i32_e32 v26, v26
	v_cvt_f32_i32_e32 v27, v27
	v_cvt_f32_i32_e32 v20, v20
	v_cvt_f32_i32_e32 v21, v21
	v_cvt_f32_i32_e32 v22, v22
	v_cvt_f32_i32_e32 v23, v23
	v_cvt_f32_i32_e32 v16, v16
	v_cvt_f32_i32_e32 v17, v17
	v_cvt_f32_i32_e32 v18, v18
	v_cvt_f32_i32_e32 v19, v19
	v_cvt_f32_i32_e32 v12, v12
	v_cvt_f32_i32_e32 v13, v13
	v_cvt_f32_i32_e32 v14, v14
	v_cvt_f32_i32_e32 v15, v15
	v_cvt_f32_i32_e32 v8, v8
	v_cvt_f32_i32_e32 v9, v9
	v_cvt_f32_i32_e32 v10, v10
	v_cvt_f32_i32_e32 v11, v11
	v_cvt_f32_i32_e32 v4, v4
	v_cvt_f32_i32_e32 v5, v5
	v_cvt_f32_i32_e32 v6, v6
	v_cvt_f32_i32_e32 v7, v7
	v_cvt_f32_i32_e32 v0, v0
	v_cvt_f32_i32_e32 v1, v1
	v_cvt_f32_i32_e32 v2, v2
	v_cvt_f32_i32_e32 v3, v3
	s_waitcnt vmcnt(0)
	v_add_u32_e32 v96, s12, v117
	v_or_b32_e32 v146, s13, v118
	v_lshl_add_u64 v[144:145], v[96:97], 2, s[68:69]
	v_lshlrev_b32_e32 v148, 2, v146
	global_load_dword v136, v[144:145], off
	global_load_dword v138, v[144:145], off offset:64
	global_load_dword v140, v[144:145], off offset:128
	global_load_dword v142, v[144:145], off offset:192
	global_load_dwordx4 v[120:123], v148, s[0:1]
	global_load_dwordx4 v[124:127], v148, s[0:1] offset:64
	global_load_dwordx4 v[128:131], v148, s[0:1] offset:128
	global_load_dwordx4 v[132:135], v148, s[0:1] offset:192
	v_lshlrev_b32_e32 v146, 1, v146
	v_mov_b32_e32 v147, v97
	v_lshlrev_b64 v[44:45], 12, v[96:97]
	v_lshl_add_u64 v[44:45], s[64:65], 0, v[44:45]
	v_lshl_add_u64 v[44:45], v[44:45], 0, v[146:147]
	v_or_b32_e32 v52, 16, v96
	v_mov_b32_e32 v53, v97
	v_lshlrev_b64 v[46:47], 12, v[52:53]
	v_lshl_add_u64 v[46:47], s[64:65], 0, v[46:47]
	v_lshl_add_u64 v[46:47], v[46:47], 0, v[146:147]
	v_or_b32_e32 v52, 32, v96
	v_mov_b32_e32 v53, v97
	v_lshlrev_b64 v[48:49], 12, v[52:53]
	v_lshl_add_u64 v[48:49], s[64:65], 0, v[48:49]
	v_lshl_add_u64 v[48:49], v[48:49], 0, v[146:147]
	v_or_b32_e32 v52, 48, v96
	v_mov_b32_e32 v53, v97
	v_lshlrev_b64 v[50:51], 12, v[52:53]
	v_lshl_add_u64 v[50:51], s[64:65], 0, v[50:51]
	v_lshl_add_u64 v[50:51], v[50:51], 0, v[146:147]
	s_waitcnt vmcnt(0)
	v_pk_mul_f32 v[92:93], v[136:137], v[92:93] op_sel_hi:[0,1]
	v_pk_mul_f32 v[94:95], v[136:137], v[94:95] op_sel_hi:[0,1]
	v_pk_mul_f32 v[92:93], v[120:121], v[92:93]
	v_pk_mul_f32 v[94:95], v[94:95], v[122:123]
	v_cvt_pk_bf16_f32 v92, v92, v93
	v_cvt_pk_bf16_f32 v93, v94, v95
	global_store_dwordx2 v[44:45], v[92:93], off
	v_pk_mul_f32 v[88:89], v[136:137], v[88:89] op_sel_hi:[0,1]
	v_pk_mul_f32 v[90:91], v[136:137], v[90:91] op_sel_hi:[0,1]
	v_pk_mul_f32 v[88:89], v[124:125], v[88:89]
	v_pk_mul_f32 v[90:91], v[90:91], v[126:127]
	v_cvt_pk_bf16_f32 v88, v88, v89
	v_cvt_pk_bf16_f32 v89, v90, v91
	global_store_dwordx2 v[44:45], v[88:89], off offset:32
	v_pk_mul_f32 v[84:85], v[136:137], v[84:85] op_sel_hi:[0,1]
	v_pk_mul_f32 v[86:87], v[136:137], v[86:87] op_sel_hi:[0,1]
	v_pk_mul_f32 v[84:85], v[128:129], v[84:85]
	v_pk_mul_f32 v[86:87], v[86:87], v[130:131]
	v_cvt_pk_bf16_f32 v84, v84, v85
	v_cvt_pk_bf16_f32 v85, v86, v87
	global_store_dwordx2 v[44:45], v[84:85], off offset:64
	v_pk_mul_f32 v[80:81], v[136:137], v[80:81] op_sel_hi:[0,1]
	v_pk_mul_f32 v[82:83], v[136:137], v[82:83] op_sel_hi:[0,1]
	v_pk_mul_f32 v[80:81], v[132:133], v[80:81]
	v_pk_mul_f32 v[82:83], v[82:83], v[134:135]
	v_cvt_pk_bf16_f32 v80, v80, v81
	v_cvt_pk_bf16_f32 v81, v82, v83
	global_store_dwordx2 v[44:45], v[80:81], off offset:96
	v_pk_mul_f32 v[60:61], v[138:139], v[60:61] op_sel_hi:[0,1]
	v_pk_mul_f32 v[62:63], v[138:139], v[62:63] op_sel_hi:[0,1]
	v_pk_mul_f32 v[60:61], v[120:121], v[60:61]
	v_pk_mul_f32 v[62:63], v[62:63], v[122:123]
	v_cvt_pk_bf16_f32 v60, v60, v61
	v_cvt_pk_bf16_f32 v61, v62, v63
	global_store_dwordx2 v[46:47], v[60:61], off
	v_pk_mul_f32 v[40:41], v[138:139], v[40:41] op_sel_hi:[0,1]
	v_pk_mul_f32 v[42:43], v[138:139], v[42:43] op_sel_hi:[0,1]
	v_pk_mul_f32 v[40:41], v[124:125], v[40:41]
	v_pk_mul_f32 v[42:43], v[42:43], v[126:127]
	v_cvt_pk_bf16_f32 v40, v40, v41
	v_cvt_pk_bf16_f32 v41, v42, v43
	global_store_dwordx2 v[46:47], v[40:41], off offset:32
	v_pk_mul_f32 v[36:37], v[138:139], v[36:37] op_sel_hi:[0,1]
	v_pk_mul_f32 v[38:39], v[138:139], v[38:39] op_sel_hi:[0,1]
	v_pk_mul_f32 v[36:37], v[128:129], v[36:37]
	v_pk_mul_f32 v[38:39], v[38:39], v[130:131]
	v_cvt_pk_bf16_f32 v36, v36, v37
	v_cvt_pk_bf16_f32 v37, v38, v39
	global_store_dwordx2 v[46:47], v[36:37], off offset:64
	v_pk_mul_f32 v[28:29], v[138:139], v[28:29] op_sel_hi:[0,1]
	v_pk_mul_f32 v[30:31], v[138:139], v[30:31] op_sel_hi:[0,1]
	v_pk_mul_f32 v[28:29], v[132:133], v[28:29]
	v_pk_mul_f32 v[30:31], v[30:31], v[134:135]
	v_cvt_pk_bf16_f32 v28, v28, v29
	v_cvt_pk_bf16_f32 v29, v30, v31
	global_store_dwordx2 v[46:47], v[28:29], off offset:96
	v_pk_mul_f32 v[32:33], v[140:141], v[32:33] op_sel_hi:[0,1]
	v_pk_mul_f32 v[34:35], v[140:141], v[34:35] op_sel_hi:[0,1]
	v_pk_mul_f32 v[32:33], v[120:121], v[32:33]
	v_pk_mul_f32 v[34:35], v[34:35], v[122:123]
	v_cvt_pk_bf16_f32 v32, v32, v33
	v_cvt_pk_bf16_f32 v33, v34, v35
	global_store_dwordx2 v[48:49], v[32:33], off
	v_pk_mul_f32 v[24:25], v[140:141], v[24:25] op_sel_hi:[0,1]
	v_pk_mul_f32 v[26:27], v[140:141], v[26:27] op_sel_hi:[0,1]
	v_pk_mul_f32 v[24:25], v[124:125], v[24:25]
	v_pk_mul_f32 v[26:27], v[26:27], v[126:127]
	v_cvt_pk_bf16_f32 v24, v24, v25
	v_cvt_pk_bf16_f32 v25, v26, v27
	global_store_dwordx2 v[48:49], v[24:25], off offset:32
	v_pk_mul_f32 v[20:21], v[140:141], v[20:21] op_sel_hi:[0,1]
	v_pk_mul_f32 v[22:23], v[140:141], v[22:23] op_sel_hi:[0,1]
	v_pk_mul_f32 v[20:21], v[128:129], v[20:21]
	v_pk_mul_f32 v[22:23], v[22:23], v[130:131]
	v_cvt_pk_bf16_f32 v20, v20, v21
	v_cvt_pk_bf16_f32 v21, v22, v23
	global_store_dwordx2 v[48:49], v[20:21], off offset:64
	v_pk_mul_f32 v[16:17], v[140:141], v[16:17] op_sel_hi:[0,1]
	v_pk_mul_f32 v[18:19], v[140:141], v[18:19] op_sel_hi:[0,1]
	v_pk_mul_f32 v[16:17], v[132:133], v[16:17]
	v_pk_mul_f32 v[18:19], v[18:19], v[134:135]
	v_cvt_pk_bf16_f32 v16, v16, v17
	v_cvt_pk_bf16_f32 v17, v18, v19
	global_store_dwordx2 v[48:49], v[16:17], off offset:96
	v_pk_mul_f32 v[12:13], v[142:143], v[12:13] op_sel_hi:[0,1]
	v_pk_mul_f32 v[14:15], v[142:143], v[14:15] op_sel_hi:[0,1]
	v_pk_mul_f32 v[12:13], v[120:121], v[12:13]
	v_pk_mul_f32 v[14:15], v[14:15], v[122:123]
	v_cvt_pk_bf16_f32 v12, v12, v13
	v_cvt_pk_bf16_f32 v13, v14, v15
	global_store_dwordx2 v[50:51], v[12:13], off
	v_pk_mul_f32 v[8:9], v[142:143], v[8:9] op_sel_hi:[0,1]
	v_pk_mul_f32 v[10:11], v[142:143], v[10:11] op_sel_hi:[0,1]
	v_pk_mul_f32 v[8:9], v[124:125], v[8:9]
	v_pk_mul_f32 v[10:11], v[10:11], v[126:127]
	v_cvt_pk_bf16_f32 v8, v8, v9
	v_cvt_pk_bf16_f32 v9, v10, v11
	global_store_dwordx2 v[50:51], v[8:9], off offset:32
	v_pk_mul_f32 v[4:5], v[142:143], v[4:5] op_sel_hi:[0,1]
	v_pk_mul_f32 v[6:7], v[142:143], v[6:7] op_sel_hi:[0,1]
	v_pk_mul_f32 v[4:5], v[128:129], v[4:5]
	v_pk_mul_f32 v[6:7], v[6:7], v[130:131]
	v_cvt_pk_bf16_f32 v4, v4, v5
	v_cvt_pk_bf16_f32 v5, v6, v7
	global_store_dwordx2 v[50:51], v[4:5], off offset:64
	v_pk_mul_f32 v[0:1], v[142:143], v[0:1] op_sel_hi:[0,1]
	v_pk_mul_f32 v[2:3], v[142:143], v[2:3] op_sel_hi:[0,1]
	v_pk_mul_f32 v[0:1], v[132:133], v[0:1]
	v_pk_mul_f32 v[2:3], v[2:3], v[134:135]
	v_cvt_pk_bf16_f32 v0, v0, v1
	v_cvt_pk_bf16_f32 v1, v2, v3
	global_store_dwordx2 v[50:51], v[0:1], off offset:96
	s_add_i32 s8, s8, s3
	s_cmpk_lt_u32 s8, 0x200
	s_cbranch_scc1 .LBB0_889
